# removed the 32 mid-block s_setprio 0/1 flip pairs inside the GEMM MFMA blocks
# speedup vs baseline: 1.0057x; 1.0057x over previous
; #define PG8_STAGE(bufoff, gbase, voff) do { _Pragma("unroll") for (int _i = 0; _i < 2; ++_i) \
;         __builtin_amdgcn_global_load_lds((const unsigned*)((const char*)(gbase) + (voff)[_i]), (PG8_LAS unsigned*)(lds + (bufoff) + ldsw + _i * 8192), 16, 0, 0); } while (0)
; #define PG8_LDA(dst, b, h) do { _Pragma("unroll") for (int m = 0; m < 4; ++m) _Pragma("unroll") for (int k = 0; k < 2; ++k) dst[m][k] = *(const PG8_LAS bf16x8*)(lds + PG8_SA(b, h) + aoff + m * 2048 + k * 1024); } while (0)
; #define PG8_LDB(dst, b, h) do { _Pragma("unroll") for (int n = 0; n < 2; ++n) _Pragma("unroll") for (int k = 0; k < 2; ++k) dst[n][k] = *(const PG8_LAS bf16x8*)(lds + PG8_SB(b, h) + boff + n * 2048 + k * 1024); } while (0)
; #define PG8_MMA(ai, bj, At, Bt) do { __builtin_amdgcn_s_setprio(1); _Pragma("unroll") for (int m = 0; m < 4; ++m) _Pragma("unroll") for (int n = 0; n < 2; ++n) _Pragma("unroll") for (int k = 0; k < 2; ++k) \
;         acc[ai][bj][m][n] = __builtin_amdgcn_mfma_f32_16x16x32_bf16(Bt[n][k], At[m][k], acc[ai][bj][m][n], 0, 0, 0); __builtin_amdgcn_s_setprio(0); } while (0)
; #define PG8_WAIT_V(n) asm volatile("s_waitcnt vmcnt(" #n ")" ::: "memory")
; #define PG8_BAR __builtin_amdgcn_s_barrier()
; template <class Epi, class Sched, bool ALIGN_EPI = false, bool SP2 = false>
; __device__ __forceinline__ void gemm_phase(PG8_LAS unsigned char* lds, const Gemm g, const Sched& S, const Epi& E) {
;     ...
;         for (int t = 0; t < nt; t += 2) {
;             const bool last = (t == nt - 2);
;             const char* a1 = cA + (size_t)(t + 1) * kstep;
;             const char* a2 = last ? nA : cA + (size_t)(t + 2) * kstep; const char* b2 = last ? nB : cB + (size_t)(t + 2) * kstepB;
;             const char* a3 = a2 + kstep; const char* b3 = b2 + kstepB;
;             if (last && has_next) S.a_ready(nxt);
;             if constexpr (SP2) {
;             PG8_LDB(B0, 0, 0); PG8_LDB(B1, 0, 1); PG8_SCHED; PG8_LDA(At, 0, 0); PG8_STAGE(PG8_SA(1, 1), a1 + hstepA, voffA);
;             PG8_WAIT_V(8); PG8_WAIT_L(0); PG8_BAR; PG8_MMA(0, 0, At, B0); PG8_MMA(0, 1, At, B1); PG8_BAR; PG8_SCHED;
;             PG8_LDA(At, 0, 1); PG8_STAGE(PG8_SB(0, 0), b2, voffB); PG8_STAGE(PG8_SB(0, 1), b2 + hstepB, voffB); PG8_STAGE(PG8_SA(0, 0), a2, voffA);
;             PG8_WAIT_V(8); PG8_WAIT_L(0); PG8_BAR; PG8_MMA(1, 0, At, B0); PG8_MMA(1, 1, At, B1); PG8_BAR; PG8_SCHED;
.LBB0_121:
	ds_read_b128 v[150:153], v157
	ds_read_b128 v[160:163], v157 offset:1024
	ds_read_b128 v[164:167], v157 offset:2048
	ds_read_b128 v[168:171], v157 offset:3072
	ds_read_b128 v[172:175], v158
	ds_read_b128 v[176:179], v158 offset:1024
	ds_read_b128 v[180:183], v158 offset:2048
	ds_read_b128 v[184:187], v158 offset:3072
	s_add_u32 s36, s34, 0xfff00080
	s_addc_u32 s37, s35, -1
	s_cmp_eq_u32 s58, 60
	s_cselect_b32 s39, s27, s37
	s_cselect_b32 s38, s54, s36
	s_cselect_b32 s37, s25, s57
	s_cselect_b32 s36, s55, s56
	v_lshl_add_u64 v[192:193], s[34:35], 0, v[142:143]
	s_add_i32 m0, s42, 0xc000
	ds_read_b128 v[188:191], v159
	ds_read_b128 v[196:199], v159 offset:1024
	ds_read_b128 v[200:203], v159 offset:2048
	ds_read_b128 v[204:207], v159 offset:3072
	ds_read_b128 v[208:211], v159 offset:4096
	ds_read_b128 v[212:215], v159 offset:5120
	ds_read_b128 v[216:219], v159 offset:6144
	ds_read_b128 v[220:223], v159 offset:7168
	global_load_lds_dwordx4 v[192:193], off
	v_lshl_add_u64 v[192:193], s[34:35], 0, v[144:145]
	s_add_i32 m0, s42, 0xe000
	s_nop 0
	global_load_lds_dwordx4 v[192:193], off
	s_waitcnt vmcnt(8)
	s_waitcnt lgkmcnt(0)
	s_barrier
	s_setprio 1
	s_waitcnt lgkmcnt(0)
	v_mfma_f32_16x16x32_bf16 v[126:129], v[150:153], v[188:191], v[126:129]
	v_mfma_f32_16x16x32_bf16 v[122:125], v[164:167], v[188:191], v[122:125]
	v_mfma_f32_16x16x32_bf16 v[118:121], v[150:153], v[200:203], v[118:121]
	v_mfma_f32_16x16x32_bf16 v[114:117], v[164:167], v[200:203], v[114:117]
	v_mfma_f32_16x16x32_bf16 v[102:105], v[150:153], v[208:211], v[102:105]
	v_mfma_f32_16x16x32_bf16 v[98:101], v[164:167], v[208:211], v[98:101]
	v_mfma_f32_16x16x32_bf16 v[86:89], v[150:153], v[216:219], v[86:89]
	v_mfma_f32_16x16x32_bf16 v[82:85], v[164:167], v[216:219], v[82:85]
	v_mfma_f32_16x16x32_bf16 v[126:129], v[160:163], v[196:199], v[126:129]
	v_mfma_f32_16x16x32_bf16 v[122:125], v[168:171], v[196:199], v[122:125]
	v_mfma_f32_16x16x32_bf16 v[118:121], v[160:163], v[204:207], v[118:121]
	v_mfma_f32_16x16x32_bf16 v[114:117], v[168:171], v[204:207], v[114:117]
	v_mfma_f32_16x16x32_bf16 v[102:105], v[160:163], v[212:215], v[102:105]
	v_mfma_f32_16x16x32_bf16 v[98:101], v[168:171], v[212:215], v[98:101]
	v_mfma_f32_16x16x32_bf16 v[86:89], v[160:163], v[220:223], v[86:89]
	v_mfma_f32_16x16x32_bf16 v[82:85], v[168:171], v[220:223], v[82:85]
	v_mfma_f32_16x16x32_bf16 v[110:113], v[172:175], v[188:191], v[110:113]
	v_mfma_f32_16x16x32_bf16 v[106:109], v[180:183], v[188:191], v[106:109]
	v_mfma_f32_16x16x32_bf16 v[94:97], v[172:175], v[200:203], v[94:97]
	v_mfma_f32_16x16x32_bf16 v[90:93], v[180:183], v[200:203], v[90:93]
	v_mfma_f32_16x16x32_bf16 v[78:81], v[172:175], v[208:211], v[78:81]
	v_mfma_f32_16x16x32_bf16 v[74:77], v[180:183], v[208:211], v[74:77]
	v_mfma_f32_16x16x32_bf16 v[70:73], v[172:175], v[216:219], v[70:73]
	v_mfma_f32_16x16x32_bf16 v[66:69], v[180:183], v[216:219], v[66:69]
	v_mfma_f32_16x16x32_bf16 v[110:113], v[176:179], v[196:199], v[110:113]
	v_mfma_f32_16x16x32_bf16 v[106:109], v[184:187], v[196:199], v[106:109]
	v_mfma_f32_16x16x32_bf16 v[94:97], v[176:179], v[204:207], v[94:97]
	v_mfma_f32_16x16x32_bf16 v[90:93], v[184:187], v[204:207], v[90:93]
	v_mfma_f32_16x16x32_bf16 v[78:81], v[176:179], v[212:215], v[78:81]
	v_mfma_f32_16x16x32_bf16 v[74:77], v[184:187], v[212:215], v[74:77]
	v_mfma_f32_16x16x32_bf16 v[70:73], v[176:179], v[220:223], v[70:73]
	v_mfma_f32_16x16x32_bf16 v[66:69], v[184:187], v[220:223], v[66:69]
	s_setprio 0
	s_barrier
	s_add_i32 s59, s50, s41
	v_lshl_add_u64 v[192:193], s[36:37], 0, v[132:133]
	s_mov_b32 m0, s59
	ds_read_b128 v[188:191], v159 offset:16384
	ds_read_b128 v[196:199], v159 offset:17408
	ds_read_b128 v[200:203], v159 offset:18432
	ds_read_b128 v[204:207], v159 offset:19456
	ds_read_b128 v[208:211], v159 offset:20480
	ds_read_b128 v[212:215], v159 offset:21504
	ds_read_b128 v[216:219], v159 offset:22528
	ds_read_b128 v[220:223], v159 offset:23552
	global_load_lds_dwordx4 v[192:193], off
	s_add_i32 m0, s59, 0x2000
	s_add_u32 s60, s36, 0x4000
	v_lshl_add_u64 v[192:193], s[36:37], 0, v[136:137]
	s_addc_u32 s61, s37, 0
	s_add_i32 s59, s51, s41
	global_load_lds_dwordx4 v[192:193], off
	v_lshl_add_u64 v[192:193], s[60:61], 0, v[132:133]
	s_mov_b32 m0, s59
	v_lshl_add_u64 v[224:225], s[38:39], 0, v[134:135]
	global_load_lds_dwordx4 v[192:193], off
	v_lshl_add_u64 v[192:193], s[60:61], 0, v[136:137]
	s_add_i32 m0, s59, 0x2000
	s_nop 0
	global_load_lds_dwordx4 v[192:193], off
	v_lshl_add_u64 v[192:193], s[38:39], 0, v[130:131]
	s_mov_b32 m0, s42
	s_nop 0
	global_load_lds_dwordx4 v[192:193], off
	s_mov_b32 m0, s43
	s_nop 0
	global_load_lds_dwordx4 v[224:225], off
	s_waitcnt vmcnt(8)
	s_waitcnt lgkmcnt(0)
	s_barrier
; #define PG8_STAGE(bufoff, gbase, voff) do { _Pragma("unroll") for (int _i = 0; _i < 2; ++_i) \
;         __builtin_amdgcn_global_load_lds((const unsigned*)((const char*)(gbase) + (voff)[_i]), (PG8_LAS unsigned*)(lds + (bufoff) + ldsw + _i * 8192), 16, 0, 0); } while (0)
; #define PG8_LDA(dst, b, h) do { _Pragma("unroll") for (int m = 0; m < 4; ++m) _Pragma("unroll") for (int k = 0; k < 2; ++k) dst[m][k] = *(const PG8_LAS bf16x8*)(lds + PG8_SA(b, h) + aoff + m * 2048 + k * 1024); } while (0)
; #define PG8_LDB(dst, b, h) do { _Pragma("unroll") for (int n = 0; n < 2; ++n) _Pragma("unroll") for (int k = 0; k < 2; ++k) dst[n][k] = *(const PG8_LAS bf16x8*)(lds + PG8_SB(b, h) + boff + n * 2048 + k * 1024); } while (0)
; #define PG8_MMA(ai, bj, At, Bt) do { __builtin_amdgcn_s_setprio(1); _Pragma("unroll") for (int m = 0; m < 4; ++m) _Pragma("unroll") for (int n = 0; n < 2; ++n) _Pragma("unroll") for (int k = 0; k < 2; ++k) \
;         acc[ai][bj][m][n] = __builtin_amdgcn_mfma_f32_16x16x32_bf16(Bt[n][k], At[m][k], acc[ai][bj][m][n], 0, 0, 0); __builtin_amdgcn_s_setprio(0); } while (0)
; #define PG8_WAIT_V(n) asm volatile("s_waitcnt vmcnt(" #n ")" ::: "memory")
; #define PG8_WAIT_L(n) asm volatile("s_waitcnt lgkmcnt(" #n ")" ::: "memory")
; #define PG8_BAR __builtin_amdgcn_s_barrier()
; #define PG8_SCHED __builtin_amdgcn_sched_barrier(0)
; template <class Epi, class Sched, bool ALIGN_EPI = false, bool SP2 = false>
; __device__ __forceinline__ void gemm_phase(PG8_LAS unsigned char* lds, const Gemm g, const Sched& S, const Epi& E) {
;     ...
;             PG8_WAIT_V(8); PG8_WAIT_L(0); PG8_BAR; PG8_MMA(1, 0, At, B0); PG8_MMA(1, 1, At, B1); PG8_BAR; PG8_SCHED;
;             PG8_LDB(B0, 1, 0); PG8_LDB(B1, 1, 1); PG8_SCHED; PG8_LDA(At, 1, 0); PG8_STAGE(PG8_SA(0, 1), a2 + hstepA, voffA);
;             PG8_WAIT_V(8); PG8_WAIT_L(0); PG8_BAR; PG8_MMA(0, 0, At, B0); PG8_MMA(0, 1, At, B1); PG8_BAR; PG8_SCHED;
;             PG8_LDA(At, 1, 1); PG8_STAGE(PG8_SB(1, 0), b3, voffB); PG8_STAGE(PG8_SB(1, 1), b3 + hstepB, voffB); PG8_STAGE(PG8_SA(1, 0), a3, voffA);
	s_setprio 1
	s_waitcnt lgkmcnt(0)
	v_mfma_f32_16x16x32_bf16 v[62:65], v[150:153], v[188:191], v[62:65]
	v_mfma_f32_16x16x32_bf16 v[58:61], v[164:167], v[188:191], v[58:61]
	v_mfma_f32_16x16x32_bf16 v[54:57], v[150:153], v[200:203], v[54:57]
	v_mfma_f32_16x16x32_bf16 v[50:53], v[164:167], v[200:203], v[50:53]
	v_mfma_f32_16x16x32_bf16 v[38:41], v[150:153], v[208:211], v[38:41]
	v_mfma_f32_16x16x32_bf16 v[34:37], v[164:167], v[208:211], v[34:37]
	v_mfma_f32_16x16x32_bf16 v[22:25], v[150:153], v[216:219], v[22:25]
	v_mfma_f32_16x16x32_bf16 v[18:21], v[164:167], v[216:219], v[18:21]
	v_mfma_f32_16x16x32_bf16 v[62:65], v[160:163], v[196:199], v[62:65]
	v_mfma_f32_16x16x32_bf16 v[58:61], v[168:171], v[196:199], v[58:61]
	v_mfma_f32_16x16x32_bf16 v[54:57], v[160:163], v[204:207], v[54:57]
	v_mfma_f32_16x16x32_bf16 v[50:53], v[168:171], v[204:207], v[50:53]
	v_mfma_f32_16x16x32_bf16 v[38:41], v[160:163], v[212:215], v[38:41]
	v_mfma_f32_16x16x32_bf16 v[34:37], v[168:171], v[212:215], v[34:37]
	v_mfma_f32_16x16x32_bf16 v[22:25], v[160:163], v[220:223], v[22:25]
	v_mfma_f32_16x16x32_bf16 v[18:21], v[168:171], v[220:223], v[18:21]
	v_mfma_f32_16x16x32_bf16 v[46:49], v[172:175], v[188:191], v[46:49]
	v_mfma_f32_16x16x32_bf16 v[42:45], v[180:183], v[188:191], v[42:45]
	v_mfma_f32_16x16x32_bf16 v[30:33], v[172:175], v[200:203], v[30:33]
	v_mfma_f32_16x16x32_bf16 v[26:29], v[180:183], v[200:203], v[26:29]
	v_mfma_f32_16x16x32_bf16 v[14:17], v[172:175], v[208:211], v[14:17]
	v_mfma_f32_16x16x32_bf16 v[10:13], v[180:183], v[208:211], v[10:13]
	v_mfma_f32_16x16x32_bf16 v[6:9], v[172:175], v[216:219], v[6:9]
	v_mfma_f32_16x16x32_bf16 v[2:5], v[180:183], v[216:219], v[2:5]
	v_mfma_f32_16x16x32_bf16 v[46:49], v[176:179], v[196:199], v[46:49]
	v_mfma_f32_16x16x32_bf16 v[42:45], v[184:187], v[196:199], v[42:45]
	v_mfma_f32_16x16x32_bf16 v[30:33], v[176:179], v[204:207], v[30:33]
	v_mfma_f32_16x16x32_bf16 v[26:29], v[184:187], v[204:207], v[26:29]
	v_mfma_f32_16x16x32_bf16 v[14:17], v[176:179], v[212:215], v[14:17]
	v_mfma_f32_16x16x32_bf16 v[10:13], v[184:187], v[212:215], v[10:13]
	v_mfma_f32_16x16x32_bf16 v[6:9], v[176:179], v[220:223], v[6:9]
	v_mfma_f32_16x16x32_bf16 v[2:5], v[184:187], v[220:223], v[2:5]
	s_setprio 0
	s_barrier
	s_add_i32 s59, 0, 0x18000
	v_add_u32_e32 v138, s59, v154
	s_add_i32 s60, 0, 0x1c000
	ds_read_b128 v[150:153], v138
	ds_read_b128 v[160:163], v138 offset:1024
	ds_read_b128 v[164:167], v138 offset:2048
	ds_read_b128 v[168:171], v138 offset:3072
	v_add_u32_e32 v138, s60, v154
	ds_read_b128 v[172:175], v138
	ds_read_b128 v[176:179], v138 offset:1024
	ds_read_b128 v[180:183], v138 offset:2048
	ds_read_b128 v[184:187], v138 offset:3072
	s_add_u32 s38, s38, 0x100000
	s_addc_u32 s39, s39, 0
	s_mov_b32 m0, s44
	v_lshl_add_u64 v[226:227], s[38:39], 0, v[130:131]
	ds_read_b128 v[188:191], v159 offset:32768
	ds_read_b128 v[196:199], v159 offset:33792
	ds_read_b128 v[200:203], v159 offset:34816
	ds_read_b128 v[204:207], v159 offset:35840
	ds_read_b128 v[208:211], v159 offset:36864
	ds_read_b128 v[212:215], v159 offset:37888
	ds_read_b128 v[216:219], v159 offset:38912
	ds_read_b128 v[220:223], v159 offset:39936
	global_load_lds_dwordx4 v[226:227], off
	v_lshl_add_u64 v[226:227], s[38:39], 0, v[134:135]
	s_mov_b32 m0, s45
	s_nop 0
	global_load_lds_dwordx4 v[226:227], off
	s_waitcnt vmcnt(8)
	s_waitcnt lgkmcnt(0)
	s_barrier
	s_setprio 1
	s_waitcnt lgkmcnt(0)
	v_mfma_f32_16x16x32_bf16 v[126:129], v[150:153], v[188:191], v[126:129]
	v_mfma_f32_16x16x32_bf16 v[122:125], v[164:167], v[188:191], v[122:125]
	v_mfma_f32_16x16x32_bf16 v[118:121], v[150:153], v[200:203], v[118:121]
	v_mfma_f32_16x16x32_bf16 v[114:117], v[164:167], v[200:203], v[114:117]
	v_mfma_f32_16x16x32_bf16 v[102:105], v[150:153], v[208:211], v[102:105]
	v_mfma_f32_16x16x32_bf16 v[98:101], v[164:167], v[208:211], v[98:101]
	v_mfma_f32_16x16x32_bf16 v[86:89], v[150:153], v[216:219], v[86:89]
	v_mfma_f32_16x16x32_bf16 v[82:85], v[164:167], v[216:219], v[82:85]
	v_mfma_f32_16x16x32_bf16 v[126:129], v[160:163], v[196:199], v[126:129]
	v_mfma_f32_16x16x32_bf16 v[122:125], v[168:171], v[196:199], v[122:125]
	v_mfma_f32_16x16x32_bf16 v[118:121], v[160:163], v[204:207], v[118:121]
	v_mfma_f32_16x16x32_bf16 v[114:117], v[168:171], v[204:207], v[114:117]
	v_mfma_f32_16x16x32_bf16 v[102:105], v[160:163], v[212:215], v[102:105]
	v_mfma_f32_16x16x32_bf16 v[98:101], v[168:171], v[212:215], v[98:101]
	v_mfma_f32_16x16x32_bf16 v[86:89], v[160:163], v[220:223], v[86:89]
	v_mfma_f32_16x16x32_bf16 v[82:85], v[168:171], v[220:223], v[82:85]
	v_mfma_f32_16x16x32_bf16 v[110:113], v[172:175], v[188:191], v[110:113]
	v_mfma_f32_16x16x32_bf16 v[106:109], v[180:183], v[188:191], v[106:109]
	v_mfma_f32_16x16x32_bf16 v[94:97], v[172:175], v[200:203], v[94:97]
	v_mfma_f32_16x16x32_bf16 v[90:93], v[180:183], v[200:203], v[90:93]
	v_mfma_f32_16x16x32_bf16 v[78:81], v[172:175], v[208:211], v[78:81]
	v_mfma_f32_16x16x32_bf16 v[74:77], v[180:183], v[208:211], v[74:77]
	v_mfma_f32_16x16x32_bf16 v[70:73], v[172:175], v[216:219], v[70:73]
	v_mfma_f32_16x16x32_bf16 v[66:69], v[180:183], v[216:219], v[66:69]
	v_mfma_f32_16x16x32_bf16 v[110:113], v[176:179], v[196:199], v[110:113]
	v_mfma_f32_16x16x32_bf16 v[106:109], v[184:187], v[196:199], v[106:109]
	v_mfma_f32_16x16x32_bf16 v[94:97], v[176:179], v[204:207], v[94:97]
	v_mfma_f32_16x16x32_bf16 v[90:93], v[184:187], v[204:207], v[90:93]
	v_mfma_f32_16x16x32_bf16 v[78:81], v[176:179], v[212:215], v[78:81]
	v_mfma_f32_16x16x32_bf16 v[74:77], v[184:187], v[212:215], v[74:77]
	v_mfma_f32_16x16x32_bf16 v[70:73], v[176:179], v[220:223], v[70:73]
	v_mfma_f32_16x16x32_bf16 v[66:69], v[184:187], v[220:223], v[66:69]
	s_setprio 0
	s_barrier
; #define PG8_STAGE(bufoff, gbase, voff) do { _Pragma("unroll") for (int _i = 0; _i < 2; ++_i) \
;         __builtin_amdgcn_global_load_lds((const unsigned*)((const char*)(gbase) + (voff)[_i]), (PG8_LAS unsigned*)(lds + (bufoff) + ldsw + _i * 8192), 16, 0, 0); } while (0)
; #define PG8_LDA(dst, b, h) do { _Pragma("unroll") for (int m = 0; m < 4; ++m) _Pragma("unroll") for (int k = 0; k < 2; ++k) dst[m][k] = *(const PG8_LAS bf16x8*)(lds + PG8_SA(b, h) + aoff + m * 2048 + k * 1024); } while (0)
; #define PG8_MMA(ai, bj, At, Bt) do { __builtin_amdgcn_s_setprio(1); _Pragma("unroll") for (int m = 0; m < 4; ++m) _Pragma("unroll") for (int n = 0; n < 2; ++n) _Pragma("unroll") for (int k = 0; k < 2; ++k) \
;         acc[ai][bj][m][n] = __builtin_amdgcn_mfma_f32_16x16x32_bf16(Bt[n][k], At[m][k], acc[ai][bj][m][n], 0, 0, 0); __builtin_amdgcn_s_setprio(0); } while (0)
; #define PG8_WAIT_V(n) asm volatile("s_waitcnt vmcnt(" #n ")" ::: "memory")
; #define PG8_WAIT_L(n) asm volatile("s_waitcnt lgkmcnt(" #n ")" ::: "memory")
; #define PG8_BAR __builtin_amdgcn_s_barrier()
; #define PG8_SCHED __builtin_amdgcn_sched_barrier(0)
; template <class Epi, class Sched, bool ALIGN_EPI = false, bool SP2 = false>
; __device__ __forceinline__ void gemm_phase(PG8_LAS unsigned char* lds, const Gemm g, const Sched& S, const Epi& E) {
;     ...
;         for (int t = 0; t < nt; t += 2) {
;             const bool last = (t == nt - 2);
;             const char* a1 = cA + (size_t)(t + 1) * kstep;
;             const char* a2 = last ? nA : cA + (size_t)(t + 2) * kstep; const char* b2 = last ? nB : cB + (size_t)(t + 2) * kstepB;
;             const char* a3 = a2 + kstep; const char* b3 = b2 + kstepB;
;             if (last && has_next) S.a_ready(nxt);
;     ...
;             PG8_LDA(At, 1, 1); PG8_STAGE(PG8_SB(1, 0), b3, voffB); PG8_STAGE(PG8_SB(1, 1), b3 + hstepB, voffB); PG8_STAGE(PG8_SA(1, 0), a3, voffA);
;             PG8_WAIT_V(8); PG8_WAIT_L(0); PG8_BAR; PG8_MMA(1, 0, At, B0); PG8_MMA(1, 1, At, B1); PG8_BAR; PG8_SCHED;
	s_add_u32 s38, s36, 0x8000
	s_addc_u32 s39, s37, 0
	s_add_i32 s59, s59, s41
	v_lshl_add_u64 v[226:227], s[38:39], 0, v[132:133]
	s_mov_b32 m0, s59
	ds_read_b128 v[188:191], v159 offset:49152
	ds_read_b128 v[196:199], v159 offset:50176
	ds_read_b128 v[200:203], v159 offset:51200
	ds_read_b128 v[204:207], v159 offset:52224
	ds_read_b128 v[208:211], v159 offset:53248
	ds_read_b128 v[212:215], v159 offset:54272
	ds_read_b128 v[216:219], v159 offset:55296
	ds_read_b128 v[220:223], v159 offset:56320
	global_load_lds_dwordx4 v[226:227], off
	s_add_i32 m0, s59, 0x2000
	s_add_u32 s36, s36, 0xc000
	v_lshl_add_u64 v[226:227], s[38:39], 0, v[136:137]
	s_addc_u32 s37, s37, 0
	s_add_i32 s38, s60, s41
	global_load_lds_dwordx4 v[226:227], off
	v_lshl_add_u64 v[226:227], s[36:37], 0, v[132:133]
	s_mov_b32 m0, s38
	v_lshl_add_u64 v[192:193], v[192:193], 0, s[14:15]
	global_load_lds_dwordx4 v[226:227], off
	v_lshl_add_u64 v[226:227], s[36:37], 0, v[136:137]
	s_add_i32 m0, s38, 0x2000
	s_nop 0
	global_load_lds_dwordx4 v[226:227], off
	s_mov_b32 m0, s47
	s_nop 0
	global_load_lds_dwordx4 v[192:193], off
	v_lshl_add_u64 v[192:193], v[224:225], 0, s[14:15]
	s_mov_b32 m0, s48
	s_nop 0
	global_load_lds_dwordx4 v[192:193], off
	s_waitcnt vmcnt(8)
	s_waitcnt lgkmcnt(0)
	s_barrier
	s_setprio 1
	s_waitcnt lgkmcnt(0)
	v_mfma_f32_16x16x32_bf16 v[62:65], v[150:153], v[188:191], v[62:65]
	v_mfma_f32_16x16x32_bf16 v[58:61], v[164:167], v[188:191], v[58:61]
	v_mfma_f32_16x16x32_bf16 v[54:57], v[150:153], v[200:203], v[54:57]
	v_mfma_f32_16x16x32_bf16 v[50:53], v[164:167], v[200:203], v[50:53]
	v_mfma_f32_16x16x32_bf16 v[38:41], v[150:153], v[208:211], v[38:41]
	v_mfma_f32_16x16x32_bf16 v[34:37], v[164:167], v[208:211], v[34:37]
	v_mfma_f32_16x16x32_bf16 v[22:25], v[150:153], v[216:219], v[22:25]
	v_mfma_f32_16x16x32_bf16 v[18:21], v[164:167], v[216:219], v[18:21]
	v_mfma_f32_16x16x32_bf16 v[62:65], v[160:163], v[196:199], v[62:65]
	v_mfma_f32_16x16x32_bf16 v[58:61], v[168:171], v[196:199], v[58:61]
	v_mfma_f32_16x16x32_bf16 v[54:57], v[160:163], v[204:207], v[54:57]
	v_mfma_f32_16x16x32_bf16 v[50:53], v[168:171], v[204:207], v[50:53]
	v_mfma_f32_16x16x32_bf16 v[38:41], v[160:163], v[212:215], v[38:41]
	v_mfma_f32_16x16x32_bf16 v[34:37], v[168:171], v[212:215], v[34:37]
	v_mfma_f32_16x16x32_bf16 v[22:25], v[160:163], v[220:223], v[22:25]
	v_mfma_f32_16x16x32_bf16 v[18:21], v[168:171], v[220:223], v[18:21]
	v_mfma_f32_16x16x32_bf16 v[46:49], v[172:175], v[188:191], v[46:49]
	v_mfma_f32_16x16x32_bf16 v[42:45], v[180:183], v[188:191], v[42:45]
	v_mfma_f32_16x16x32_bf16 v[30:33], v[172:175], v[200:203], v[30:33]
	v_mfma_f32_16x16x32_bf16 v[26:29], v[180:183], v[200:203], v[26:29]
	v_mfma_f32_16x16x32_bf16 v[14:17], v[172:175], v[208:211], v[14:17]
	v_mfma_f32_16x16x32_bf16 v[10:13], v[180:183], v[208:211], v[10:13]
	v_mfma_f32_16x16x32_bf16 v[6:9], v[172:175], v[216:219], v[6:9]
	v_mfma_f32_16x16x32_bf16 v[2:5], v[180:183], v[216:219], v[2:5]
	v_mfma_f32_16x16x32_bf16 v[46:49], v[176:179], v[196:199], v[46:49]
	v_mfma_f32_16x16x32_bf16 v[42:45], v[184:187], v[196:199], v[42:45]
	v_mfma_f32_16x16x32_bf16 v[30:33], v[176:179], v[204:207], v[30:33]
	v_mfma_f32_16x16x32_bf16 v[26:29], v[184:187], v[204:207], v[26:29]
	v_mfma_f32_16x16x32_bf16 v[14:17], v[176:179], v[212:215], v[14:17]
	v_mfma_f32_16x16x32_bf16 v[10:13], v[184:187], v[212:215], v[10:13]
	v_mfma_f32_16x16x32_bf16 v[6:9], v[176:179], v[220:223], v[6:9]
	v_mfma_f32_16x16x32_bf16 v[2:5], v[184:187], v[220:223], v[2:5]
	s_setprio 0
	s_barrier
	s_add_i32 s58, s58, 2
	s_add_u32 s56, s56, 0x10000
	s_addc_u32 s57, s57, 0
	s_add_u32 s34, s34, 0x100
	s_addc_u32 s35, s35, 0
	s_cmp_gt_u32 s58, 61
	s_cbranch_scc0 .LBB0_121
	s_and_b64 vcc, exec, s[16:17]
	s_cbranch_vccz .LBB0_124
	s_barrier

; #define PG8_STAGE(bufoff, gbase, voff) do { _Pragma("unroll") for (int _i = 0; _i < 2; ++_i) \
;         __builtin_amdgcn_global_load_lds((const unsigned*)((const char*)(gbase) + (voff)[_i]), (PG8_LAS unsigned*)(lds + (bufoff) + ldsw + _i * 8192), 16, 0, 0); } while (0)
; #define PG8_LDA(dst, b, h) do { _Pragma("unroll") for (int m = 0; m < 4; ++m) _Pragma("unroll") for (int k = 0; k < 2; ++k) dst[m][k] = *(const PG8_LAS bf16x8*)(lds + PG8_SA(b, h) + aoff + m * 2048 + k * 1024); } while (0)
; #define PG8_LDB(dst, b, h) do { _Pragma("unroll") for (int n = 0; n < 2; ++n) _Pragma("unroll") for (int k = 0; k < 2; ++k) dst[n][k] = *(const PG8_LAS bf16x8*)(lds + PG8_SB(b, h) + boff + n * 2048 + k * 1024); } while (0)
; #define PG8_MMA(ai, bj, At, Bt) do { __builtin_amdgcn_s_setprio(1); _Pragma("unroll") for (int m = 0; m < 4; ++m) _Pragma("unroll") for (int n = 0; n < 2; ++n) _Pragma("unroll") for (int k = 0; k < 2; ++k) \
;         acc[ai][bj][m][n] = __builtin_amdgcn_mfma_f32_16x16x32_bf16(Bt[n][k], At[m][k], acc[ai][bj][m][n], 0, 0, 0); __builtin_amdgcn_s_setprio(0); } while (0)
; #define PG8_WAIT_V(n) asm volatile("s_waitcnt vmcnt(" #n ")" ::: "memory")
; #define PG8_WAIT_L(n) asm volatile("s_waitcnt lgkmcnt(" #n ")" ::: "memory")
; #define PG8_BAR __builtin_amdgcn_s_barrier()
; #define PG8_SCHED __builtin_amdgcn_sched_barrier(0)
; template <class Epi, class Sched, bool ALIGN_EPI = false, bool SP2 = false>
; __device__ __forceinline__ void gemm_phase(PG8_LAS unsigned char* lds, const Gemm g, const Sched& S, const Epi& E) {
;     ...
;             PG8_LDB(B0, 0, 0); PG8_LDB(B1, 0, 1); PG8_SCHED; PG8_LDA(At, 0, 0); PG8_STAGE(PG8_SA(1, 1), a1 + hstepA, voffA);
;             PG8_WAIT_V(8); PG8_WAIT_L(0); PG8_BAR; PG8_MMA(0, 0, At, B0); PG8_MMA(0, 1, At, B1); PG8_BAR; PG8_SCHED;
;             PG8_LDA(At, 0, 1); PG8_STAGE(PG8_SB(0, 0), b2, voffB); PG8_STAGE(PG8_SB(0, 1), b2 + hstepB, voffB); PG8_STAGE(PG8_SA(0, 0), a2, voffA);
;             PG8_WAIT_V(8); PG8_WAIT_L(0); PG8_BAR; PG8_MMA(1, 0, At, B0); PG8_MMA(1, 1, At, B1); PG8_BAR; PG8_SCHED;
;             PG8_LDB(B0, 1, 0); PG8_LDB(B1, 1, 1); PG8_SCHED; PG8_LDA(At, 1, 0); PG8_STAGE(PG8_SA(0, 1), a2 + hstepA, voffA);
.LBB0_140:
	ds_read_b128 v[82:85], v79
	ds_read_b128 v[86:89], v79 offset:1024
	ds_read_b128 v[90:93], v79 offset:2048
	ds_read_b128 v[94:97], v79 offset:3072
	s_add_u32 s18, s10, s35
	s_addc_u32 s19, s11, s36
	s_add_u32 s44, s10, s33
	s_addc_u32 s45, s11, s34
	s_cmp_eq_u32 s37, 12
	s_cselect_b32 s21, s13, s19
	s_cselect_b32 s20, s12, s18
	s_cselect_b32 s19, s7, s45
	s_cselect_b32 s18, s6, s44
	s_mov_b32 m0, s38
	v_lshl_add_u64 v[130:131], s[10:11], 0, v[74:75]
	ds_read_b128 v[98:101], v80
	ds_read_b128 v[102:105], v80 offset:1024
	ds_read_b128 v[106:109], v80 offset:2048
	ds_read_b128 v[110:113], v80 offset:3072
	ds_read_b128 v[114:117], v80 offset:4096
	ds_read_b128 v[118:121], v80 offset:5120
	ds_read_b128 v[122:125], v80 offset:6144
	ds_read_b128 v[126:129], v80 offset:7168
	global_load_lds_dwordx4 v[130:131], off
	v_lshl_add_u64 v[130:131], s[10:11], 0, v[76:77]
	s_mov_b32 m0, s39
	s_nop 0
	global_load_lds_dwordx4 v[130:131], off
	s_waitcnt vmcnt(8)
	s_waitcnt lgkmcnt(0)
	s_barrier
	s_setprio 1
	s_waitcnt lgkmcnt(0)
	v_mfma_f32_16x16x32_bf16 v[62:65], v[82:85], v[98:101], v[62:65]
	v_mfma_f32_16x16x32_bf16 v[58:61], v[90:93], v[98:101], v[58:61]
	v_mfma_f32_16x16x32_bf16 v[54:57], v[82:85], v[106:109], v[54:57]
	v_mfma_f32_16x16x32_bf16 v[50:53], v[90:93], v[106:109], v[50:53]
	v_mfma_f32_16x16x32_bf16 v[46:49], v[82:85], v[114:117], v[46:49]
	v_mfma_f32_16x16x32_bf16 v[42:45], v[90:93], v[114:117], v[42:45]
	v_mfma_f32_16x16x32_bf16 v[38:41], v[82:85], v[122:125], v[38:41]
	v_mfma_f32_16x16x32_bf16 v[34:37], v[90:93], v[122:125], v[34:37]
	v_mfma_f32_16x16x32_bf16 v[62:65], v[86:89], v[102:105], v[62:65]
	v_mfma_f32_16x16x32_bf16 v[58:61], v[94:97], v[102:105], v[58:61]
	v_mfma_f32_16x16x32_bf16 v[54:57], v[86:89], v[110:113], v[54:57]
	v_mfma_f32_16x16x32_bf16 v[50:53], v[94:97], v[110:113], v[50:53]
	v_mfma_f32_16x16x32_bf16 v[46:49], v[86:89], v[118:121], v[46:49]
	v_mfma_f32_16x16x32_bf16 v[42:45], v[94:97], v[118:121], v[42:45]
	v_mfma_f32_16x16x32_bf16 v[38:41], v[86:89], v[126:129], v[38:41]
	v_mfma_f32_16x16x32_bf16 v[34:37], v[94:97], v[126:129], v[34:37]
	s_setprio 0
	s_barrier
	s_mov_b32 m0, s40
	v_lshl_add_u64 v[130:131], s[18:19], 0, v[70:71]
	s_add_u32 s44, s18, 0x4000
	ds_read_b128 v[98:101], v80 offset:16384
	ds_read_b128 v[102:105], v80 offset:17408
	ds_read_b128 v[106:109], v80 offset:18432
	ds_read_b128 v[110:113], v80 offset:19456
	ds_read_b128 v[114:117], v80 offset:20480
	ds_read_b128 v[118:121], v80 offset:21504
	ds_read_b128 v[122:125], v80 offset:22528
	ds_read_b128 v[126:129], v80 offset:23552
	global_load_lds_dwordx4 v[130:131], off
	v_lshl_add_u64 v[130:131], s[18:19], 0, v[66:67]
	s_mov_b32 m0, s41
	s_addc_u32 s45, s19, 0
	global_load_lds_dwordx4 v[130:131], off
	v_lshl_add_u64 v[130:131], s[44:45], 0, v[70:71]
	s_mov_b32 m0, s22
	v_lshl_add_u64 v[132:133], s[20:21], 0, v[68:69]
	global_load_lds_dwordx4 v[130:131], off
	v_lshl_add_u64 v[130:131], s[44:45], 0, v[66:67]
	s_mov_b32 m0, s23
	s_nop 0
	global_load_lds_dwordx4 v[130:131], off
	v_lshl_add_u64 v[130:131], s[20:21], 0, v[72:73]
	s_mov_b32 m0, s5
	s_nop 0
	global_load_lds_dwordx4 v[130:131], off
	s_mov_b32 m0, s24
	s_nop 0
	global_load_lds_dwordx4 v[132:133], off
	s_waitcnt vmcnt(8)
	s_waitcnt lgkmcnt(0)
	s_barrier
	s_setprio 1
	s_waitcnt lgkmcnt(0)
	v_mfma_f32_16x16x32_bf16 v[30:33], v[82:85], v[98:101], v[30:33]
	v_mfma_f32_16x16x32_bf16 v[26:29], v[90:93], v[98:101], v[26:29]
	v_mfma_f32_16x16x32_bf16 v[22:25], v[82:85], v[106:109], v[22:25]
	v_mfma_f32_16x16x32_bf16 v[18:21], v[90:93], v[106:109], v[18:21]
	v_mfma_f32_16x16x32_bf16 v[14:17], v[82:85], v[114:117], v[14:17]
	v_mfma_f32_16x16x32_bf16 v[10:13], v[90:93], v[114:117], v[10:13]
	v_mfma_f32_16x16x32_bf16 v[6:9], v[82:85], v[122:125], v[6:9]
	v_mfma_f32_16x16x32_bf16 v[2:5], v[90:93], v[122:125], v[2:5]
	v_mfma_f32_16x16x32_bf16 v[30:33], v[86:89], v[102:105], v[30:33]
	v_mfma_f32_16x16x32_bf16 v[26:29], v[94:97], v[102:105], v[26:29]
	v_mfma_f32_16x16x32_bf16 v[22:25], v[86:89], v[110:113], v[22:25]
	v_mfma_f32_16x16x32_bf16 v[18:21], v[94:97], v[110:113], v[18:21]
	v_mfma_f32_16x16x32_bf16 v[14:17], v[86:89], v[118:121], v[14:17]
	v_mfma_f32_16x16x32_bf16 v[10:13], v[94:97], v[118:121], v[10:13]
	v_mfma_f32_16x16x32_bf16 v[6:9], v[86:89], v[126:129], v[6:9]
	v_mfma_f32_16x16x32_bf16 v[2:5], v[94:97], v[126:129], v[2:5]
	s_setprio 0
	s_barrier
; #define PG8_STAGE(bufoff, gbase, voff) do { _Pragma("unroll") for (int _i = 0; _i < 2; ++_i) \
;         __builtin_amdgcn_global_load_lds((const unsigned*)((const char*)(gbase) + (voff)[_i]), (PG8_LAS unsigned*)(lds + (bufoff) + ldsw + _i * 8192), 16, 0, 0); } while (0)
; #define PG8_LDA(dst, b, h) do { _Pragma("unroll") for (int m = 0; m < 4; ++m) _Pragma("unroll") for (int k = 0; k < 2; ++k) dst[m][k] = *(const PG8_LAS bf16x8*)(lds + PG8_SA(b, h) + aoff + m * 2048 + k * 1024); } while (0)
; #define PG8_LDB(dst, b, h) do { _Pragma("unroll") for (int n = 0; n < 2; ++n) _Pragma("unroll") for (int k = 0; k < 2; ++k) dst[n][k] = *(const PG8_LAS bf16x8*)(lds + PG8_SB(b, h) + boff + n * 2048 + k * 1024); } while (0)
; #define PG8_MMA(ai, bj, At, Bt) do { __builtin_amdgcn_s_setprio(1); _Pragma("unroll") for (int m = 0; m < 4; ++m) _Pragma("unroll") for (int n = 0; n < 2; ++n) _Pragma("unroll") for (int k = 0; k < 2; ++k) \
;         acc[ai][bj][m][n] = __builtin_amdgcn_mfma_f32_16x16x32_bf16(Bt[n][k], At[m][k], acc[ai][bj][m][n], 0, 0, 0); __builtin_amdgcn_s_setprio(0); } while (0)
; #define PG8_WAIT_V(n) asm volatile("s_waitcnt vmcnt(" #n ")" ::: "memory")
; #define PG8_WAIT_L(n) asm volatile("s_waitcnt lgkmcnt(" #n ")" ::: "memory")
; #define PG8_BAR __builtin_amdgcn_s_barrier()
; #define PG8_SCHED __builtin_amdgcn_sched_barrier(0)
; template <class Epi, class Sched, bool ALIGN_EPI = false, bool SP2 = false>
; __device__ __forceinline__ void gemm_phase(PG8_LAS unsigned char* lds, const Gemm g, const Sched& S, const Epi& E) {
;     ...
;             PG8_LDB(B0, 1, 0); PG8_LDB(B1, 1, 1); PG8_SCHED; PG8_LDA(At, 1, 0); PG8_STAGE(PG8_SA(0, 1), a2 + hstepA, voffA);
;             PG8_WAIT_V(8); PG8_WAIT_L(0); PG8_BAR; PG8_MMA(0, 0, At, B0); PG8_MMA(0, 1, At, B1); PG8_BAR; PG8_SCHED;
;             PG8_LDA(At, 1, 1); PG8_STAGE(PG8_SB(1, 0), b3, voffB); PG8_STAGE(PG8_SB(1, 1), b3 + hstepB, voffB); PG8_STAGE(PG8_SA(1, 0), a3, voffA);
;             PG8_WAIT_V(8); PG8_WAIT_L(0); PG8_BAR; PG8_MMA(1, 0, At, B0); PG8_MMA(1, 1, At, B1); PG8_BAR; PG8_SCHED;
	ds_read_b128 v[82:85], v81
	ds_read_b128 v[86:89], v81 offset:1024
	ds_read_b128 v[90:93], v81 offset:2048
	ds_read_b128 v[94:97], v81 offset:3072
	s_add_u32 s20, s20, 0x100000
	s_addc_u32 s21, s21, 0
	s_mov_b32 m0, s25
	v_lshl_add_u64 v[134:135], s[20:21], 0, v[72:73]
	ds_read_b128 v[98:101], v80 offset:32768
	ds_read_b128 v[102:105], v80 offset:33792
	ds_read_b128 v[106:109], v80 offset:34816
	ds_read_b128 v[110:113], v80 offset:35840
	ds_read_b128 v[114:117], v80 offset:36864
	ds_read_b128 v[118:121], v80 offset:37888
	ds_read_b128 v[122:125], v80 offset:38912
	ds_read_b128 v[126:129], v80 offset:39936
	global_load_lds_dwordx4 v[134:135], off
	v_lshl_add_u64 v[134:135], s[20:21], 0, v[68:69]
	s_mov_b32 m0, s26
	s_nop 0
	global_load_lds_dwordx4 v[134:135], off
	s_waitcnt vmcnt(8)
	s_waitcnt lgkmcnt(0)
	s_barrier
	s_setprio 1
	s_waitcnt lgkmcnt(0)
	v_mfma_f32_16x16x32_bf16 v[62:65], v[82:85], v[98:101], v[62:65]
	v_mfma_f32_16x16x32_bf16 v[58:61], v[90:93], v[98:101], v[58:61]
	v_mfma_f32_16x16x32_bf16 v[54:57], v[82:85], v[106:109], v[54:57]
	v_mfma_f32_16x16x32_bf16 v[50:53], v[90:93], v[106:109], v[50:53]
	v_mfma_f32_16x16x32_bf16 v[46:49], v[82:85], v[114:117], v[46:49]
	v_mfma_f32_16x16x32_bf16 v[42:45], v[90:93], v[114:117], v[42:45]
	v_mfma_f32_16x16x32_bf16 v[38:41], v[82:85], v[122:125], v[38:41]
	v_mfma_f32_16x16x32_bf16 v[34:37], v[90:93], v[122:125], v[34:37]
	v_mfma_f32_16x16x32_bf16 v[62:65], v[86:89], v[102:105], v[62:65]
	v_mfma_f32_16x16x32_bf16 v[58:61], v[94:97], v[102:105], v[58:61]
	v_mfma_f32_16x16x32_bf16 v[54:57], v[86:89], v[110:113], v[54:57]
	v_mfma_f32_16x16x32_bf16 v[50:53], v[94:97], v[110:113], v[50:53]
	v_mfma_f32_16x16x32_bf16 v[46:49], v[86:89], v[118:121], v[46:49]
	v_mfma_f32_16x16x32_bf16 v[42:45], v[94:97], v[118:121], v[42:45]
	v_mfma_f32_16x16x32_bf16 v[38:41], v[86:89], v[126:129], v[38:41]
	v_mfma_f32_16x16x32_bf16 v[34:37], v[94:97], v[126:129], v[34:37]
	s_setprio 0
	s_barrier
	s_add_u32 s20, s18, 0x8000
	s_addc_u32 s21, s19, 0
	s_mov_b32 m0, s42
	v_lshl_add_u64 v[134:135], s[20:21], 0, v[70:71]
	s_add_u32 s18, s18, 0xc000
	ds_read_b128 v[98:101], v80 offset:49152
	ds_read_b128 v[102:105], v80 offset:50176
	ds_read_b128 v[106:109], v80 offset:51200
	ds_read_b128 v[110:113], v80 offset:52224
	ds_read_b128 v[114:117], v80 offset:53248
	ds_read_b128 v[118:121], v80 offset:54272
	ds_read_b128 v[122:125], v80 offset:55296
	ds_read_b128 v[126:129], v80 offset:56320
	global_load_lds_dwordx4 v[134:135], off
	v_lshl_add_u64 v[134:135], s[20:21], 0, v[66:67]
	s_mov_b32 m0, s43
	s_addc_u32 s19, s19, 0
	global_load_lds_dwordx4 v[134:135], off
	v_lshl_add_u64 v[134:135], s[18:19], 0, v[70:71]
	s_mov_b32 m0, s30
	v_lshl_add_u64 v[130:131], v[130:131], 0, s[14:15]
	global_load_lds_dwordx4 v[134:135], off
	v_lshl_add_u64 v[134:135], s[18:19], 0, v[66:67]
	s_mov_b32 m0, s31
	s_nop 0
	global_load_lds_dwordx4 v[134:135], off
	s_mov_b32 m0, s28
	s_nop 0
	global_load_lds_dwordx4 v[130:131], off
	v_lshl_add_u64 v[130:131], v[132:133], 0, s[14:15]
	s_mov_b32 m0, s29
	s_nop 0
	global_load_lds_dwordx4 v[130:131], off
	s_waitcnt vmcnt(8)
	s_waitcnt lgkmcnt(0)
	s_barrier
	s_setprio 1
	s_waitcnt lgkmcnt(0)
	v_mfma_f32_16x16x32_bf16 v[30:33], v[82:85], v[98:101], v[30:33]
	v_mfma_f32_16x16x32_bf16 v[26:29], v[90:93], v[98:101], v[26:29]
	v_mfma_f32_16x16x32_bf16 v[22:25], v[82:85], v[106:109], v[22:25]
	v_mfma_f32_16x16x32_bf16 v[18:21], v[90:93], v[106:109], v[18:21]
	v_mfma_f32_16x16x32_bf16 v[14:17], v[82:85], v[114:117], v[14:17]
	v_mfma_f32_16x16x32_bf16 v[10:13], v[90:93], v[114:117], v[10:13]
	v_mfma_f32_16x16x32_bf16 v[6:9], v[82:85], v[122:125], v[6:9]
	v_mfma_f32_16x16x32_bf16 v[2:5], v[90:93], v[122:125], v[2:5]
	v_mfma_f32_16x16x32_bf16 v[30:33], v[86:89], v[102:105], v[30:33]
	v_mfma_f32_16x16x32_bf16 v[26:29], v[94:97], v[102:105], v[26:29]
	v_mfma_f32_16x16x32_bf16 v[22:25], v[86:89], v[110:113], v[22:25]
	v_mfma_f32_16x16x32_bf16 v[18:21], v[94:97], v[110:113], v[18:21]
	v_mfma_f32_16x16x32_bf16 v[14:17], v[86:89], v[118:121], v[14:17]
	v_mfma_f32_16x16x32_bf16 v[10:13], v[94:97], v[118:121], v[10:13]
	v_mfma_f32_16x16x32_bf16 v[6:9], v[86:89], v[126:129], v[6:9]
	v_mfma_f32_16x16x32_bf16 v[2:5], v[94:97], v[126:129], v[2:5]
	s_setprio 0
	s_barrier
	s_add_i32 s37, s37, 2
	s_add_u32 s33, s33, 0x10000
	s_addc_u32 s34, s34, 0
	s_add_u32 s35, s35, 0x100
	s_addc_u32 s36, s36, 0
	v_lshl_add_u64 v[74:75], v[74:75], 0, s[16:17]
	s_cmp_gt_u32 s37, 13
	v_lshl_add_u64 v[76:77], v[76:77], 0, s[16:17]
	s_cbranch_scc0 .LBB0_140
	s_cmpk_lt_u32 s3, 0x100
	s_cbranch_scc0 .LBB0_143
	s_barrier

; #define PG8_STAGE(bufoff, gbase, voff) do { _Pragma("unroll") for (int _i = 0; _i < 2; ++_i) \
;         __builtin_amdgcn_global_load_lds((const unsigned*)((const char*)(gbase) + (voff)[_i]), (PG8_LAS unsigned*)(lds + (bufoff) + ldsw + _i * 8192), 16, 0, 0); } while (0)
; #define PG8_LDA(dst, b, h) do { _Pragma("unroll") for (int m = 0; m < 4; ++m) _Pragma("unroll") for (int k = 0; k < 2; ++k) dst[m][k] = *(const PG8_LAS bf16x8*)(lds + PG8_SA(b, h) + aoff + m * 2048 + k * 1024); } while (0)
; #define PG8_LDB(dst, b, h) do { _Pragma("unroll") for (int n = 0; n < 2; ++n) _Pragma("unroll") for (int k = 0; k < 2; ++k) dst[n][k] = *(const PG8_LAS bf16x8*)(lds + PG8_SB(b, h) + boff + n * 2048 + k * 1024); } while (0)
; #define PG8_MMA(ai, bj, At, Bt) do { __builtin_amdgcn_s_setprio(1); _Pragma("unroll") for (int m = 0; m < 4; ++m) _Pragma("unroll") for (int n = 0; n < 2; ++n) _Pragma("unroll") for (int k = 0; k < 2; ++k) \
;         acc[ai][bj][m][n] = __builtin_amdgcn_mfma_f32_16x16x32_bf16(Bt[n][k], At[m][k], acc[ai][bj][m][n], 0, 0, 0); __builtin_amdgcn_s_setprio(0); } while (0)
; #define PG8_WAIT_V(n) asm volatile("s_waitcnt vmcnt(" #n ")" ::: "memory")
; #define PG8_BAR __builtin_amdgcn_s_barrier()
; template <class Epi, class Sched, bool ALIGN_EPI = false, bool SP2 = false>
; __device__ __forceinline__ void gemm_phase(PG8_LAS unsigned char* lds, const Gemm g, const Sched& S, const Epi& E) {
;     ...
;         for (int t = 0; t < nt; t += 2) {
;             const bool last = (t == nt - 2);
;             const char* a1 = cA + (size_t)(t + 1) * kstep;
;             const char* a2 = last ? nA : cA + (size_t)(t + 2) * kstep; const char* b2 = last ? nB : cB + (size_t)(t + 2) * kstepB;
;             const char* a3 = a2 + kstep; const char* b3 = b2 + kstepB;
;             if (last && has_next) S.a_ready(nxt);
;             if constexpr (SP2) {
;             PG8_LDB(B0, 0, 0); PG8_LDB(B1, 0, 1); PG8_SCHED; PG8_LDA(At, 0, 0); PG8_STAGE(PG8_SA(1, 1), a1 + hstepA, voffA);
;             PG8_WAIT_V(8); PG8_WAIT_L(0); PG8_BAR; PG8_MMA(0, 0, At, B0); PG8_MMA(0, 1, At, B1); PG8_BAR; PG8_SCHED;
;             PG8_LDA(At, 0, 1); PG8_STAGE(PG8_SB(0, 0), b2, voffB); PG8_STAGE(PG8_SB(0, 1), b2 + hstepB, voffB); PG8_STAGE(PG8_SA(0, 0), a2, voffA);
;             PG8_WAIT_V(8); PG8_WAIT_L(0); PG8_BAR; PG8_MMA(1, 0, At, B0); PG8_MMA(1, 1, At, B1); PG8_BAR; PG8_SCHED;
.LBB0_643:
	v_add_u32_e32 v142, s59, v1
	v_add_u32_e32 v158, s60, v1
	ds_read_b128 v[130:133], v142
	ds_read_b128 v[134:137], v142 offset:1024
	ds_read_b128 v[138:141], v142 offset:2048
	ds_read_b128 v[142:145], v142 offset:3072
	ds_read_b128 v[146:149], v158
	ds_read_b128 v[150:153], v158 offset:1024
	ds_read_b128 v[154:157], v158 offset:2048
	ds_read_b128 v[158:161], v158 offset:3072
	s_add_u32 s36, s14, 0xffe00080
	s_addc_u32 s37, s15, -1
	s_cmp_eq_u32 s65, 60
	s_cselect_b32 s45, s33, s37
	s_cselect_b32 s44, s39, s36
	s_cselect_b32 s37, s31, s64
	s_cselect_b32 s36, s35, s63
	v_lshl_add_u64 v[218:219], s[14:15], 0, v[186:187]
	s_add_i32 m0, s47, 0xc000
	ds_read_b128 v[162:165], v197
	ds_read_b128 v[166:169], v197 offset:1024
	ds_read_b128 v[170:173], v197 offset:2048
	ds_read_b128 v[198:201], v197 offset:3072
	ds_read_b128 v[202:205], v197 offset:4096
	ds_read_b128 v[206:209], v197 offset:5120
	ds_read_b128 v[210:213], v197 offset:6144
	ds_read_b128 v[214:217], v197 offset:7168
	global_load_lds_dwordx4 v[218:219], off
	v_lshl_add_u64 v[218:219], s[14:15], 0, v[188:189]
	s_add_i32 m0, s47, 0xe000
	s_nop 0
	global_load_lds_dwordx4 v[218:219], off
	s_waitcnt vmcnt(8)
	s_waitcnt lgkmcnt(0)
	s_barrier
	s_setprio 1
	s_waitcnt lgkmcnt(0)
	v_mfma_f32_16x16x32_bf16 v[126:129], v[130:133], v[162:165], v[126:129]
	v_mfma_f32_16x16x32_bf16 v[122:125], v[138:141], v[162:165], v[122:125]
	v_mfma_f32_16x16x32_bf16 v[118:121], v[130:133], v[170:173], v[118:121]
	v_mfma_f32_16x16x32_bf16 v[114:117], v[138:141], v[170:173], v[114:117]
	v_mfma_f32_16x16x32_bf16 v[110:113], v[130:133], v[202:205], v[110:113]
	v_mfma_f32_16x16x32_bf16 v[106:109], v[138:141], v[202:205], v[106:109]
	v_mfma_f32_16x16x32_bf16 v[102:105], v[130:133], v[210:213], v[102:105]
	v_mfma_f32_16x16x32_bf16 v[98:101], v[138:141], v[210:213], v[98:101]
	v_mfma_f32_16x16x32_bf16 v[126:129], v[134:137], v[166:169], v[126:129]
	v_mfma_f32_16x16x32_bf16 v[122:125], v[142:145], v[166:169], v[122:125]
	v_mfma_f32_16x16x32_bf16 v[118:121], v[134:137], v[198:201], v[118:121]
	v_mfma_f32_16x16x32_bf16 v[114:117], v[142:145], v[198:201], v[114:117]
	v_mfma_f32_16x16x32_bf16 v[110:113], v[134:137], v[206:209], v[110:113]
	v_mfma_f32_16x16x32_bf16 v[106:109], v[142:145], v[206:209], v[106:109]
	v_mfma_f32_16x16x32_bf16 v[102:105], v[134:137], v[214:217], v[102:105]
	v_mfma_f32_16x16x32_bf16 v[98:101], v[142:145], v[214:217], v[98:101]
	v_mfma_f32_16x16x32_bf16 v[94:97], v[146:149], v[162:165], v[94:97]
	v_mfma_f32_16x16x32_bf16 v[90:93], v[154:157], v[162:165], v[90:93]
	v_mfma_f32_16x16x32_bf16 v[86:89], v[146:149], v[170:173], v[86:89]
	v_mfma_f32_16x16x32_bf16 v[82:85], v[154:157], v[170:173], v[82:85]
	v_mfma_f32_16x16x32_bf16 v[78:81], v[146:149], v[202:205], v[78:81]
	v_mfma_f32_16x16x32_bf16 v[74:77], v[154:157], v[202:205], v[74:77]
	v_mfma_f32_16x16x32_bf16 v[70:73], v[146:149], v[210:213], v[70:73]
	v_mfma_f32_16x16x32_bf16 v[66:69], v[154:157], v[210:213], v[66:69]
	v_mfma_f32_16x16x32_bf16 v[94:97], v[150:153], v[166:169], v[94:97]
	v_mfma_f32_16x16x32_bf16 v[90:93], v[158:161], v[166:169], v[90:93]
	v_mfma_f32_16x16x32_bf16 v[86:89], v[150:153], v[198:201], v[86:89]
	v_mfma_f32_16x16x32_bf16 v[82:85], v[158:161], v[198:201], v[82:85]
	v_mfma_f32_16x16x32_bf16 v[78:81], v[150:153], v[206:209], v[78:81]
	v_mfma_f32_16x16x32_bf16 v[74:77], v[158:161], v[206:209], v[74:77]
	v_mfma_f32_16x16x32_bf16 v[70:73], v[150:153], v[214:217], v[70:73]
	v_mfma_f32_16x16x32_bf16 v[66:69], v[158:161], v[214:217], v[66:69]
	s_setprio 0
	s_barrier
	s_add_i32 s68, s59, s49
	v_lshl_add_u64 v[218:219], s[36:37], 0, v[180:181]
	s_mov_b32 m0, s68
	ds_read_b128 v[162:165], v197 offset:16384
	ds_read_b128 v[166:169], v197 offset:17408
	ds_read_b128 v[170:173], v197 offset:18432
	ds_read_b128 v[198:201], v197 offset:19456
	ds_read_b128 v[202:205], v197 offset:20480
	ds_read_b128 v[206:209], v197 offset:21504
	ds_read_b128 v[210:213], v197 offset:22528
	ds_read_b128 v[214:217], v197 offset:23552
	global_load_lds_dwordx4 v[218:219], off
	s_add_i32 m0, s68, 0x2000
	s_add_u32 s68, s36, 0x4000
	v_lshl_add_u64 v[218:219], s[36:37], 0, v[176:177]
	s_addc_u32 s69, s37, 0
	s_add_i32 s70, s60, s49
	global_load_lds_dwordx4 v[218:219], off
	v_lshl_add_u64 v[218:219], s[68:69], 0, v[180:181]
	s_mov_b32 m0, s70
	v_lshl_add_u64 v[220:221], s[44:45], 0, v[178:179]
	global_load_lds_dwordx4 v[218:219], off
	v_lshl_add_u64 v[218:219], s[68:69], 0, v[176:177]
	s_add_i32 m0, s70, 0x2000
	s_nop 0
	global_load_lds_dwordx4 v[218:219], off
	v_lshl_add_u64 v[218:219], s[44:45], 0, v[182:183]
	s_mov_b32 m0, s47
	s_nop 0
	global_load_lds_dwordx4 v[218:219], off
	s_mov_b32 m0, s52
	s_nop 0
	global_load_lds_dwordx4 v[220:221], off
	s_waitcnt vmcnt(8)
	s_waitcnt lgkmcnt(0)
	s_barrier
; #define PG8_STAGE(bufoff, gbase, voff) do { _Pragma("unroll") for (int _i = 0; _i < 2; ++_i) \
;         __builtin_amdgcn_global_load_lds((const unsigned*)((const char*)(gbase) + (voff)[_i]), (PG8_LAS unsigned*)(lds + (bufoff) + ldsw + _i * 8192), 16, 0, 0); } while (0)
; #define PG8_LDA(dst, b, h) do { _Pragma("unroll") for (int m = 0; m < 4; ++m) _Pragma("unroll") for (int k = 0; k < 2; ++k) dst[m][k] = *(const PG8_LAS bf16x8*)(lds + PG8_SA(b, h) + aoff + m * 2048 + k * 1024); } while (0)
; #define PG8_LDB(dst, b, h) do { _Pragma("unroll") for (int n = 0; n < 2; ++n) _Pragma("unroll") for (int k = 0; k < 2; ++k) dst[n][k] = *(const PG8_LAS bf16x8*)(lds + PG8_SB(b, h) + boff + n * 2048 + k * 1024); } while (0)
; #define PG8_MMA(ai, bj, At, Bt) do { __builtin_amdgcn_s_setprio(1); _Pragma("unroll") for (int m = 0; m < 4; ++m) _Pragma("unroll") for (int n = 0; n < 2; ++n) _Pragma("unroll") for (int k = 0; k < 2; ++k) \
;         acc[ai][bj][m][n] = __builtin_amdgcn_mfma_f32_16x16x32_bf16(Bt[n][k], At[m][k], acc[ai][bj][m][n], 0, 0, 0); __builtin_amdgcn_s_setprio(0); } while (0)
; #define PG8_WAIT_V(n) asm volatile("s_waitcnt vmcnt(" #n ")" ::: "memory")
; #define PG8_WAIT_L(n) asm volatile("s_waitcnt lgkmcnt(" #n ")" ::: "memory")
; #define PG8_BAR __builtin_amdgcn_s_barrier()
; #define PG8_SCHED __builtin_amdgcn_sched_barrier(0)
; template <class Epi, class Sched, bool ALIGN_EPI = false, bool SP2 = false>
; __device__ __forceinline__ void gemm_phase(PG8_LAS unsigned char* lds, const Gemm g, const Sched& S, const Epi& E) {
;     ...
;             PG8_WAIT_V(8); PG8_WAIT_L(0); PG8_BAR; PG8_MMA(1, 0, At, B0); PG8_MMA(1, 1, At, B1); PG8_BAR; PG8_SCHED;
;             PG8_LDB(B0, 1, 0); PG8_LDB(B1, 1, 1); PG8_SCHED; PG8_LDA(At, 1, 0); PG8_STAGE(PG8_SA(0, 1), a2 + hstepA, voffA);
;             PG8_WAIT_V(8); PG8_WAIT_L(0); PG8_BAR; PG8_MMA(0, 0, At, B0); PG8_MMA(0, 1, At, B1); PG8_BAR; PG8_SCHED;
;             PG8_LDA(At, 1, 1); PG8_STAGE(PG8_SB(1, 0), b3, voffB); PG8_STAGE(PG8_SB(1, 1), b3 + hstepB, voffB); PG8_STAGE(PG8_SA(1, 0), a3, voffA);
	s_setprio 1
	s_waitcnt lgkmcnt(0)
	v_mfma_f32_16x16x32_bf16 v[62:65], v[130:133], v[162:165], v[62:65]
	v_mfma_f32_16x16x32_bf16 v[58:61], v[138:141], v[162:165], v[58:61]
	v_mfma_f32_16x16x32_bf16 v[54:57], v[130:133], v[170:173], v[54:57]
	v_mfma_f32_16x16x32_bf16 v[50:53], v[138:141], v[170:173], v[50:53]
	v_mfma_f32_16x16x32_bf16 v[46:49], v[130:133], v[202:205], v[46:49]
	v_mfma_f32_16x16x32_bf16 v[42:45], v[138:141], v[202:205], v[42:45]
	v_mfma_f32_16x16x32_bf16 v[38:41], v[130:133], v[210:213], v[38:41]
	v_mfma_f32_16x16x32_bf16 v[34:37], v[138:141], v[210:213], v[34:37]
	v_mfma_f32_16x16x32_bf16 v[62:65], v[134:137], v[166:169], v[62:65]
	v_mfma_f32_16x16x32_bf16 v[58:61], v[142:145], v[166:169], v[58:61]
	v_mfma_f32_16x16x32_bf16 v[54:57], v[134:137], v[198:201], v[54:57]
	v_mfma_f32_16x16x32_bf16 v[50:53], v[142:145], v[198:201], v[50:53]
	v_mfma_f32_16x16x32_bf16 v[46:49], v[134:137], v[206:209], v[46:49]
	v_mfma_f32_16x16x32_bf16 v[42:45], v[142:145], v[206:209], v[42:45]
	v_mfma_f32_16x16x32_bf16 v[38:41], v[134:137], v[214:217], v[38:41]
	v_mfma_f32_16x16x32_bf16 v[34:37], v[142:145], v[214:217], v[34:37]
	v_mfma_f32_16x16x32_bf16 v[30:33], v[146:149], v[162:165], v[30:33]
	v_mfma_f32_16x16x32_bf16 v[26:29], v[154:157], v[162:165], v[26:29]
	v_mfma_f32_16x16x32_bf16 v[22:25], v[146:149], v[170:173], v[22:25]
	v_mfma_f32_16x16x32_bf16 v[18:21], v[154:157], v[170:173], v[18:21]
	v_mfma_f32_16x16x32_bf16 v[14:17], v[146:149], v[202:205], v[14:17]
	v_mfma_f32_16x16x32_bf16 v[10:13], v[154:157], v[202:205], v[10:13]
	v_mfma_f32_16x16x32_bf16 v[6:9], v[146:149], v[210:213], v[6:9]
	v_mfma_f32_16x16x32_bf16 v[2:5], v[154:157], v[210:213], v[2:5]
	v_mfma_f32_16x16x32_bf16 v[30:33], v[150:153], v[166:169], v[30:33]
	v_mfma_f32_16x16x32_bf16 v[26:29], v[158:161], v[166:169], v[26:29]
	v_mfma_f32_16x16x32_bf16 v[22:25], v[150:153], v[198:201], v[22:25]
	v_mfma_f32_16x16x32_bf16 v[18:21], v[158:161], v[198:201], v[18:21]
	v_mfma_f32_16x16x32_bf16 v[14:17], v[150:153], v[206:209], v[14:17]
	v_mfma_f32_16x16x32_bf16 v[10:13], v[158:161], v[206:209], v[10:13]
	v_mfma_f32_16x16x32_bf16 v[6:9], v[150:153], v[214:217], v[6:9]
	v_mfma_f32_16x16x32_bf16 v[2:5], v[158:161], v[214:217], v[2:5]
	s_setprio 0
	s_barrier
	s_add_i32 s68, 0, 0x18000
	s_add_i32 s69, 0, 0x1c000
	v_add_u32_e32 v142, s68, v1
	v_add_u32_e32 v158, s69, v1
	ds_read_b128 v[130:133], v142
	ds_read_b128 v[134:137], v142 offset:1024
	ds_read_b128 v[138:141], v142 offset:2048
	ds_read_b128 v[142:145], v142 offset:3072
	ds_read_b128 v[146:149], v158
	ds_read_b128 v[150:153], v158 offset:1024
	ds_read_b128 v[154:157], v158 offset:2048
	ds_read_b128 v[158:161], v158 offset:3072
	s_add_u32 s44, s44, 0x200000
	s_addc_u32 s45, s45, 0
	s_mov_b32 m0, s53
	v_lshl_add_u64 v[222:223], s[44:45], 0, v[182:183]
	ds_read_b128 v[162:165], v197 offset:32768
	ds_read_b128 v[166:169], v197 offset:33792
	ds_read_b128 v[170:173], v197 offset:34816
	ds_read_b128 v[198:201], v197 offset:35840
	ds_read_b128 v[202:205], v197 offset:36864
	ds_read_b128 v[206:209], v197 offset:37888
	ds_read_b128 v[210:213], v197 offset:38912
	ds_read_b128 v[214:217], v197 offset:39936
	global_load_lds_dwordx4 v[222:223], off
	v_lshl_add_u64 v[222:223], s[44:45], 0, v[178:179]
	s_mov_b32 m0, s54
	s_nop 0
	global_load_lds_dwordx4 v[222:223], off
	s_waitcnt vmcnt(8)
	s_waitcnt lgkmcnt(0)
	s_barrier
	s_setprio 1
	s_waitcnt lgkmcnt(0)
	v_mfma_f32_16x16x32_bf16 v[126:129], v[130:133], v[162:165], v[126:129]
	v_mfma_f32_16x16x32_bf16 v[122:125], v[138:141], v[162:165], v[122:125]
	v_mfma_f32_16x16x32_bf16 v[118:121], v[130:133], v[170:173], v[118:121]
	v_mfma_f32_16x16x32_bf16 v[114:117], v[138:141], v[170:173], v[114:117]
	v_mfma_f32_16x16x32_bf16 v[110:113], v[130:133], v[202:205], v[110:113]
	v_mfma_f32_16x16x32_bf16 v[106:109], v[138:141], v[202:205], v[106:109]
	v_mfma_f32_16x16x32_bf16 v[102:105], v[130:133], v[210:213], v[102:105]
	v_mfma_f32_16x16x32_bf16 v[98:101], v[138:141], v[210:213], v[98:101]
	v_mfma_f32_16x16x32_bf16 v[126:129], v[134:137], v[166:169], v[126:129]
	v_mfma_f32_16x16x32_bf16 v[122:125], v[142:145], v[166:169], v[122:125]
	v_mfma_f32_16x16x32_bf16 v[118:121], v[134:137], v[198:201], v[118:121]
	v_mfma_f32_16x16x32_bf16 v[114:117], v[142:145], v[198:201], v[114:117]
	v_mfma_f32_16x16x32_bf16 v[110:113], v[134:137], v[206:209], v[110:113]
	v_mfma_f32_16x16x32_bf16 v[106:109], v[142:145], v[206:209], v[106:109]
	v_mfma_f32_16x16x32_bf16 v[102:105], v[134:137], v[214:217], v[102:105]
	v_mfma_f32_16x16x32_bf16 v[98:101], v[142:145], v[214:217], v[98:101]
	v_mfma_f32_16x16x32_bf16 v[94:97], v[146:149], v[162:165], v[94:97]
	v_mfma_f32_16x16x32_bf16 v[90:93], v[154:157], v[162:165], v[90:93]
	v_mfma_f32_16x16x32_bf16 v[86:89], v[146:149], v[170:173], v[86:89]
	v_mfma_f32_16x16x32_bf16 v[82:85], v[154:157], v[170:173], v[82:85]
	v_mfma_f32_16x16x32_bf16 v[78:81], v[146:149], v[202:205], v[78:81]
	v_mfma_f32_16x16x32_bf16 v[74:77], v[154:157], v[202:205], v[74:77]
	v_mfma_f32_16x16x32_bf16 v[70:73], v[146:149], v[210:213], v[70:73]
	v_mfma_f32_16x16x32_bf16 v[66:69], v[154:157], v[210:213], v[66:69]
	v_mfma_f32_16x16x32_bf16 v[94:97], v[150:153], v[166:169], v[94:97]
	v_mfma_f32_16x16x32_bf16 v[90:93], v[158:161], v[166:169], v[90:93]
	v_mfma_f32_16x16x32_bf16 v[86:89], v[150:153], v[198:201], v[86:89]
	v_mfma_f32_16x16x32_bf16 v[82:85], v[158:161], v[198:201], v[82:85]
	v_mfma_f32_16x16x32_bf16 v[78:81], v[150:153], v[206:209], v[78:81]
	v_mfma_f32_16x16x32_bf16 v[74:77], v[158:161], v[206:209], v[74:77]
	v_mfma_f32_16x16x32_bf16 v[70:73], v[150:153], v[214:217], v[70:73]
	v_mfma_f32_16x16x32_bf16 v[66:69], v[158:161], v[214:217], v[66:69]
	s_setprio 0
	s_barrier
; #define PG8_STAGE(bufoff, gbase, voff) do { _Pragma("unroll") for (int _i = 0; _i < 2; ++_i) \
;         __builtin_amdgcn_global_load_lds((const unsigned*)((const char*)(gbase) + (voff)[_i]), (PG8_LAS unsigned*)(lds + (bufoff) + ldsw + _i * 8192), 16, 0, 0); } while (0)
; #define PG8_LDA(dst, b, h) do { _Pragma("unroll") for (int m = 0; m < 4; ++m) _Pragma("unroll") for (int k = 0; k < 2; ++k) dst[m][k] = *(const PG8_LAS bf16x8*)(lds + PG8_SA(b, h) + aoff + m * 2048 + k * 1024); } while (0)
; #define PG8_MMA(ai, bj, At, Bt) do { __builtin_amdgcn_s_setprio(1); _Pragma("unroll") for (int m = 0; m < 4; ++m) _Pragma("unroll") for (int n = 0; n < 2; ++n) _Pragma("unroll") for (int k = 0; k < 2; ++k) \
;         acc[ai][bj][m][n] = __builtin_amdgcn_mfma_f32_16x16x32_bf16(Bt[n][k], At[m][k], acc[ai][bj][m][n], 0, 0, 0); __builtin_amdgcn_s_setprio(0); } while (0)
; #define PG8_WAIT_V(n) asm volatile("s_waitcnt vmcnt(" #n ")" ::: "memory")
; #define PG8_WAIT_L(n) asm volatile("s_waitcnt lgkmcnt(" #n ")" ::: "memory")
; #define PG8_BAR __builtin_amdgcn_s_barrier()
; #define PG8_SCHED __builtin_amdgcn_sched_barrier(0)
; template <class Epi, class Sched, bool ALIGN_EPI = false, bool SP2 = false>
; __device__ __forceinline__ void gemm_phase(PG8_LAS unsigned char* lds, const Gemm g, const Sched& S, const Epi& E) {
;     ...
;         for (int t = 0; t < nt; t += 2) {
;             const bool last = (t == nt - 2);
;             const char* a1 = cA + (size_t)(t + 1) * kstep;
;             const char* a2 = last ? nA : cA + (size_t)(t + 2) * kstep; const char* b2 = last ? nB : cB + (size_t)(t + 2) * kstepB;
;             const char* a3 = a2 + kstep; const char* b3 = b2 + kstepB;
;             if (last && has_next) S.a_ready(nxt);
;     ...
;             PG8_LDA(At, 1, 1); PG8_STAGE(PG8_SB(1, 0), b3, voffB); PG8_STAGE(PG8_SB(1, 1), b3 + hstepB, voffB); PG8_STAGE(PG8_SA(1, 0), a3, voffA);
;             PG8_WAIT_V(8); PG8_WAIT_L(0); PG8_BAR; PG8_MMA(1, 0, At, B0); PG8_MMA(1, 1, At, B1); PG8_BAR; PG8_SCHED;
	s_add_u32 s44, s36, 0x8000
	s_addc_u32 s45, s37, 0
	s_add_i32 s68, s68, s49
	v_lshl_add_u64 v[222:223], s[44:45], 0, v[180:181]
	s_mov_b32 m0, s68
	ds_read_b128 v[162:165], v197 offset:49152
	ds_read_b128 v[166:169], v197 offset:50176
	ds_read_b128 v[170:173], v197 offset:51200
	ds_read_b128 v[198:201], v197 offset:52224
	ds_read_b128 v[202:205], v197 offset:53248
	ds_read_b128 v[206:209], v197 offset:54272
	ds_read_b128 v[210:213], v197 offset:55296
	ds_read_b128 v[214:217], v197 offset:56320
	global_load_lds_dwordx4 v[222:223], off
	s_add_i32 m0, s68, 0x2000
	s_add_u32 s36, s36, 0xc000
	v_lshl_add_u64 v[222:223], s[44:45], 0, v[176:177]
	s_addc_u32 s37, s37, 0
	s_add_i32 s44, s69, s49
	global_load_lds_dwordx4 v[222:223], off
	v_lshl_add_u64 v[222:223], s[36:37], 0, v[180:181]
	s_mov_b32 m0, s44
	v_lshl_add_u64 v[218:219], v[218:219], 0, s[26:27]
	global_load_lds_dwordx4 v[222:223], off
	v_lshl_add_u64 v[222:223], s[36:37], 0, v[176:177]
	s_add_i32 m0, s44, 0x2000
	s_nop 0
	global_load_lds_dwordx4 v[222:223], off
	s_mov_b32 m0, s56
	s_nop 0
	global_load_lds_dwordx4 v[218:219], off
	v_lshl_add_u64 v[218:219], v[220:221], 0, s[26:27]
	s_mov_b32 m0, s57
	s_nop 0
	global_load_lds_dwordx4 v[218:219], off
	s_waitcnt vmcnt(8)
	s_waitcnt lgkmcnt(0)
	s_barrier
	s_setprio 1
	s_waitcnt lgkmcnt(0)
	v_mfma_f32_16x16x32_bf16 v[62:65], v[130:133], v[162:165], v[62:65]
	v_mfma_f32_16x16x32_bf16 v[58:61], v[138:141], v[162:165], v[58:61]
	v_mfma_f32_16x16x32_bf16 v[54:57], v[130:133], v[170:173], v[54:57]
	v_mfma_f32_16x16x32_bf16 v[50:53], v[138:141], v[170:173], v[50:53]
	v_mfma_f32_16x16x32_bf16 v[46:49], v[130:133], v[202:205], v[46:49]
	v_mfma_f32_16x16x32_bf16 v[42:45], v[138:141], v[202:205], v[42:45]
	v_mfma_f32_16x16x32_bf16 v[38:41], v[130:133], v[210:213], v[38:41]
	v_mfma_f32_16x16x32_bf16 v[34:37], v[138:141], v[210:213], v[34:37]
	v_mfma_f32_16x16x32_bf16 v[62:65], v[134:137], v[166:169], v[62:65]
	v_mfma_f32_16x16x32_bf16 v[58:61], v[142:145], v[166:169], v[58:61]
	v_mfma_f32_16x16x32_bf16 v[54:57], v[134:137], v[198:201], v[54:57]
	v_mfma_f32_16x16x32_bf16 v[50:53], v[142:145], v[198:201], v[50:53]
	v_mfma_f32_16x16x32_bf16 v[46:49], v[134:137], v[206:209], v[46:49]
	v_mfma_f32_16x16x32_bf16 v[42:45], v[142:145], v[206:209], v[42:45]
	v_mfma_f32_16x16x32_bf16 v[38:41], v[134:137], v[214:217], v[38:41]
	v_mfma_f32_16x16x32_bf16 v[34:37], v[142:145], v[214:217], v[34:37]
	v_mfma_f32_16x16x32_bf16 v[30:33], v[146:149], v[162:165], v[30:33]
	v_mfma_f32_16x16x32_bf16 v[26:29], v[154:157], v[162:165], v[26:29]
	v_mfma_f32_16x16x32_bf16 v[22:25], v[146:149], v[170:173], v[22:25]
	v_mfma_f32_16x16x32_bf16 v[18:21], v[154:157], v[170:173], v[18:21]
	v_mfma_f32_16x16x32_bf16 v[14:17], v[146:149], v[202:205], v[14:17]
	v_mfma_f32_16x16x32_bf16 v[10:13], v[154:157], v[202:205], v[10:13]
	v_mfma_f32_16x16x32_bf16 v[6:9], v[146:149], v[210:213], v[6:9]
	v_mfma_f32_16x16x32_bf16 v[2:5], v[154:157], v[210:213], v[2:5]
	v_mfma_f32_16x16x32_bf16 v[30:33], v[150:153], v[166:169], v[30:33]
	v_mfma_f32_16x16x32_bf16 v[26:29], v[158:161], v[166:169], v[26:29]
	v_mfma_f32_16x16x32_bf16 v[22:25], v[150:153], v[198:201], v[22:25]
	v_mfma_f32_16x16x32_bf16 v[18:21], v[158:161], v[198:201], v[18:21]
	v_mfma_f32_16x16x32_bf16 v[14:17], v[150:153], v[206:209], v[14:17]
	v_mfma_f32_16x16x32_bf16 v[10:13], v[158:161], v[206:209], v[10:13]
	v_mfma_f32_16x16x32_bf16 v[6:9], v[150:153], v[214:217], v[6:9]
	v_mfma_f32_16x16x32_bf16 v[2:5], v[158:161], v[214:217], v[2:5]
	s_setprio 0
	s_barrier
	s_add_i32 s65, s65, 2
	s_add_u32 s63, s63, 0x10000
	s_addc_u32 s64, s64, 0
	s_add_u32 s14, s14, 0x100
	s_addc_u32 s15, s15, 0
	s_cmp_gt_u32 s65, 61
	s_cbranch_scc0 .LBB0_643
	s_and_b64 vcc, exec, s[28:29]
	s_cbranch_vccz .LBB0_646
	s_barrier

; #define PG8_STAGE(bufoff, gbase, voff) do { _Pragma("unroll") for (int _i = 0; _i < 2; ++_i) \
;         __builtin_amdgcn_global_load_lds((const unsigned*)((const char*)(gbase) + (voff)[_i]), (PG8_LAS unsigned*)(lds + (bufoff) + ldsw + _i * 8192), 16, 0, 0); } while (0)
; #define PG8_LDA(dst, b, h) do { _Pragma("unroll") for (int m = 0; m < 4; ++m) _Pragma("unroll") for (int k = 0; k < 2; ++k) dst[m][k] = *(const PG8_LAS bf16x8*)(lds + PG8_SA(b, h) + aoff + m * 2048 + k * 1024); } while (0)
; #define PG8_LDB(dst, b, h) do { _Pragma("unroll") for (int n = 0; n < 2; ++n) _Pragma("unroll") for (int k = 0; k < 2; ++k) dst[n][k] = *(const PG8_LAS bf16x8*)(lds + PG8_SB(b, h) + boff + n * 2048 + k * 1024); } while (0)
; #define PG8_MMA(ai, bj, At, Bt) do { __builtin_amdgcn_s_setprio(1); _Pragma("unroll") for (int m = 0; m < 4; ++m) _Pragma("unroll") for (int n = 0; n < 2; ++n) _Pragma("unroll") for (int k = 0; k < 2; ++k) \
;         acc[ai][bj][m][n] = __builtin_amdgcn_mfma_f32_16x16x32_bf16(Bt[n][k], At[m][k], acc[ai][bj][m][n], 0, 0, 0); __builtin_amdgcn_s_setprio(0); } while (0)
; #define PG8_WAIT_V(n) asm volatile("s_waitcnt vmcnt(" #n ")" ::: "memory")
; #define PG8_BAR __builtin_amdgcn_s_barrier()
; template <class Epi, class Sched, bool ALIGN_EPI = false, bool SP2 = false>
; __device__ __forceinline__ void gemm_phase(PG8_LAS unsigned char* lds, const Gemm g, const Sched& S, const Epi& E) {
;     ...
;         for (int t = 0; t < nt; t += 2) {
;             const bool last = (t == nt - 2);
;             const char* a1 = cA + (size_t)(t + 1) * kstep;
;             const char* a2 = last ? nA : cA + (size_t)(t + 2) * kstep; const char* b2 = last ? nB : cB + (size_t)(t + 2) * kstepB;
;             const char* a3 = a2 + kstep; const char* b3 = b2 + kstepB;
;             if (last && has_next) S.a_ready(nxt);
;             if constexpr (SP2) {
;             PG8_LDB(B0, 0, 0); PG8_LDB(B1, 0, 1); PG8_SCHED; PG8_LDA(At, 0, 0); PG8_STAGE(PG8_SA(1, 1), a1 + hstepA, voffA);
;             PG8_WAIT_V(8); PG8_WAIT_L(0); PG8_BAR; PG8_MMA(0, 0, At, B0); PG8_MMA(0, 1, At, B1); PG8_BAR; PG8_SCHED;
;             PG8_LDA(At, 0, 1); PG8_STAGE(PG8_SB(0, 0), b2, voffB); PG8_STAGE(PG8_SB(0, 1), b2 + hstepB, voffB); PG8_STAGE(PG8_SA(0, 0), a2, voffA);
;             PG8_WAIT_V(8); PG8_WAIT_L(0); PG8_BAR; PG8_MMA(1, 0, At, B0); PG8_MMA(1, 1, At, B1); PG8_BAR; PG8_SCHED;
.LBB0_694:
	ds_read_b128 v[114:117], v168
	ds_read_b128 v[126:129], v168 offset:1024
	ds_read_b128 v[134:137], v168 offset:2048
	ds_read_b128 v[142:145], v168 offset:3072
	ds_read_b128 v[172:175], v169
	ds_read_b128 v[176:179], v169 offset:1024
	ds_read_b128 v[180:183], v169 offset:2048
	ds_read_b128 v[184:187], v169 offset:3072
	s_add_u32 s46, s36, 0xfff00080
	s_addc_u32 s47, s37, -1
	s_cmp_eq_u32 s70, 60
	s_cselect_b32 s49, s39, s47
	s_cselect_b32 s48, s45, s46
	s_cselect_b32 s47, s31, s69
	s_cselect_b32 s46, s65, s68
	v_lshl_add_u64 v[164:165], s[36:37], 0, v[156:157]
	s_add_i32 m0, s54, 0xc000
	ds_read_b128 v[188:191], v170
	ds_read_b128 v[196:199], v170 offset:1024
	ds_read_b128 v[200:203], v170 offset:2048
	ds_read_b128 v[204:207], v170 offset:3072
	ds_read_b128 v[208:211], v170 offset:4096
	ds_read_b128 v[212:215], v170 offset:5120
	ds_read_b128 v[216:219], v170 offset:6144
	ds_read_b128 v[220:223], v170 offset:7168
	global_load_lds_dwordx4 v[164:165], off
	v_lshl_add_u64 v[164:165], s[36:37], 0, v[158:159]
	s_add_i32 m0, s54, 0xe000
	s_nop 0
	global_load_lds_dwordx4 v[164:165], off
	s_waitcnt vmcnt(8)
	s_waitcnt lgkmcnt(0)
	s_barrier
	s_setprio 1
	s_waitcnt lgkmcnt(0)
	v_mfma_f32_16x16x32_bf16 v[138:141], v[114:117], v[188:191], v[138:141]
	v_mfma_f32_16x16x32_bf16 v[130:133], v[134:137], v[188:191], v[130:133]
	v_mfma_f32_16x16x32_bf16 v[110:113], v[114:117], v[200:203], v[110:113]
	v_mfma_f32_16x16x32_bf16 v[106:109], v[134:137], v[200:203], v[106:109]
	v_mfma_f32_16x16x32_bf16 v[94:97], v[114:117], v[208:211], v[94:97]
	v_mfma_f32_16x16x32_bf16 v[90:93], v[134:137], v[208:211], v[90:93]
	v_mfma_f32_16x16x32_bf16 v[78:81], v[114:117], v[216:219], v[78:81]
	v_mfma_f32_16x16x32_bf16 v[74:77], v[134:137], v[216:219], v[74:77]
	v_mfma_f32_16x16x32_bf16 v[138:141], v[126:129], v[196:199], v[138:141]
	v_mfma_f32_16x16x32_bf16 v[130:133], v[142:145], v[196:199], v[130:133]
	v_mfma_f32_16x16x32_bf16 v[110:113], v[126:129], v[204:207], v[110:113]
	v_mfma_f32_16x16x32_bf16 v[106:109], v[142:145], v[204:207], v[106:109]
	v_mfma_f32_16x16x32_bf16 v[94:97], v[126:129], v[212:215], v[94:97]
	v_mfma_f32_16x16x32_bf16 v[90:93], v[142:145], v[212:215], v[90:93]
	v_mfma_f32_16x16x32_bf16 v[78:81], v[126:129], v[220:223], v[78:81]
	v_mfma_f32_16x16x32_bf16 v[74:77], v[142:145], v[220:223], v[74:77]
	v_mfma_f32_16x16x32_bf16 v[122:125], v[172:175], v[188:191], v[122:125]
	v_mfma_f32_16x16x32_bf16 v[118:121], v[180:183], v[188:191], v[118:121]
	v_mfma_f32_16x16x32_bf16 v[102:105], v[172:175], v[200:203], v[102:105]
	v_mfma_f32_16x16x32_bf16 v[98:101], v[180:183], v[200:203], v[98:101]
	v_mfma_f32_16x16x32_bf16 v[86:89], v[172:175], v[208:211], v[86:89]
	v_mfma_f32_16x16x32_bf16 v[82:85], v[180:183], v[208:211], v[82:85]
	v_mfma_f32_16x16x32_bf16 v[70:73], v[172:175], v[216:219], v[70:73]
	v_mfma_f32_16x16x32_bf16 v[66:69], v[180:183], v[216:219], v[66:69]
	v_mfma_f32_16x16x32_bf16 v[122:125], v[176:179], v[196:199], v[122:125]
	v_mfma_f32_16x16x32_bf16 v[118:121], v[184:187], v[196:199], v[118:121]
	v_mfma_f32_16x16x32_bf16 v[102:105], v[176:179], v[204:207], v[102:105]
	v_mfma_f32_16x16x32_bf16 v[98:101], v[184:187], v[204:207], v[98:101]
	v_mfma_f32_16x16x32_bf16 v[86:89], v[176:179], v[212:215], v[86:89]
	v_mfma_f32_16x16x32_bf16 v[82:85], v[184:187], v[212:215], v[82:85]
	v_mfma_f32_16x16x32_bf16 v[70:73], v[176:179], v[220:223], v[70:73]
	v_mfma_f32_16x16x32_bf16 v[66:69], v[184:187], v[220:223], v[66:69]
	s_setprio 0
	s_barrier
	s_add_i32 s71, s62, s53
	v_lshl_add_u64 v[164:165], s[46:47], 0, v[148:149]
	s_mov_b32 m0, s71
	ds_read_b128 v[188:191], v170 offset:16384
	ds_read_b128 v[196:199], v170 offset:17408
	ds_read_b128 v[200:203], v170 offset:18432
	ds_read_b128 v[204:207], v170 offset:19456
	ds_read_b128 v[208:211], v170 offset:20480
	ds_read_b128 v[212:215], v170 offset:21504
	ds_read_b128 v[216:219], v170 offset:22528
	ds_read_b128 v[220:223], v170 offset:23552
	global_load_lds_dwordx4 v[164:165], off
	s_add_i32 m0, s71, 0x2000
	s_add_u32 s72, s46, 0x4000
	v_lshl_add_u64 v[164:165], s[46:47], 0, v[152:153]
	s_addc_u32 s73, s47, 0
	s_add_i32 s71, s63, s53
	global_load_lds_dwordx4 v[164:165], off
	v_lshl_add_u64 v[164:165], s[72:73], 0, v[148:149]
	s_mov_b32 m0, s71
	v_lshl_add_u64 v[192:193], s[48:49], 0, v[150:151]
	global_load_lds_dwordx4 v[164:165], off
	v_lshl_add_u64 v[164:165], s[72:73], 0, v[152:153]
	s_add_i32 m0, s71, 0x2000
	s_nop 0
	global_load_lds_dwordx4 v[164:165], off
	v_lshl_add_u64 v[164:165], s[48:49], 0, v[146:147]
	s_mov_b32 m0, s54
	s_nop 0
	global_load_lds_dwordx4 v[164:165], off
	s_mov_b32 m0, s55
	s_nop 0
	global_load_lds_dwordx4 v[192:193], off
	s_waitcnt vmcnt(8)
	s_waitcnt lgkmcnt(0)
	s_barrier
; #define PG8_STAGE(bufoff, gbase, voff) do { _Pragma("unroll") for (int _i = 0; _i < 2; ++_i) \
;         __builtin_amdgcn_global_load_lds((const unsigned*)((const char*)(gbase) + (voff)[_i]), (PG8_LAS unsigned*)(lds + (bufoff) + ldsw + _i * 8192), 16, 0, 0); } while (0)
; #define PG8_LDA(dst, b, h) do { _Pragma("unroll") for (int m = 0; m < 4; ++m) _Pragma("unroll") for (int k = 0; k < 2; ++k) dst[m][k] = *(const PG8_LAS bf16x8*)(lds + PG8_SA(b, h) + aoff + m * 2048 + k * 1024); } while (0)
; #define PG8_LDB(dst, b, h) do { _Pragma("unroll") for (int n = 0; n < 2; ++n) _Pragma("unroll") for (int k = 0; k < 2; ++k) dst[n][k] = *(const PG8_LAS bf16x8*)(lds + PG8_SB(b, h) + boff + n * 2048 + k * 1024); } while (0)
; #define PG8_MMA(ai, bj, At, Bt) do { __builtin_amdgcn_s_setprio(1); _Pragma("unroll") for (int m = 0; m < 4; ++m) _Pragma("unroll") for (int n = 0; n < 2; ++n) _Pragma("unroll") for (int k = 0; k < 2; ++k) \
;         acc[ai][bj][m][n] = __builtin_amdgcn_mfma_f32_16x16x32_bf16(Bt[n][k], At[m][k], acc[ai][bj][m][n], 0, 0, 0); __builtin_amdgcn_s_setprio(0); } while (0)
; #define PG8_WAIT_V(n) asm volatile("s_waitcnt vmcnt(" #n ")" ::: "memory")
; #define PG8_WAIT_L(n) asm volatile("s_waitcnt lgkmcnt(" #n ")" ::: "memory")
; #define PG8_BAR __builtin_amdgcn_s_barrier()
; #define PG8_SCHED __builtin_amdgcn_sched_barrier(0)
; template <class Epi, class Sched, bool ALIGN_EPI = false, bool SP2 = false>
; __device__ __forceinline__ void gemm_phase(PG8_LAS unsigned char* lds, const Gemm g, const Sched& S, const Epi& E) {
;     ...
;             PG8_WAIT_V(8); PG8_WAIT_L(0); PG8_BAR; PG8_MMA(1, 0, At, B0); PG8_MMA(1, 1, At, B1); PG8_BAR; PG8_SCHED;
;             PG8_LDB(B0, 1, 0); PG8_LDB(B1, 1, 1); PG8_SCHED; PG8_LDA(At, 1, 0); PG8_STAGE(PG8_SA(0, 1), a2 + hstepA, voffA);
;             PG8_WAIT_V(8); PG8_WAIT_L(0); PG8_BAR; PG8_MMA(0, 0, At, B0); PG8_MMA(0, 1, At, B1); PG8_BAR; PG8_SCHED;
;             PG8_LDA(At, 1, 1); PG8_STAGE(PG8_SB(1, 0), b3, voffB); PG8_STAGE(PG8_SB(1, 1), b3 + hstepB, voffB); PG8_STAGE(PG8_SA(1, 0), a3, voffA);
	s_setprio 1
	s_waitcnt lgkmcnt(0)
	v_mfma_f32_16x16x32_bf16 v[62:65], v[114:117], v[188:191], v[62:65]
	v_mfma_f32_16x16x32_bf16 v[58:61], v[134:137], v[188:191], v[58:61]
	v_mfma_f32_16x16x32_bf16 v[46:49], v[114:117], v[200:203], v[46:49]
	v_mfma_f32_16x16x32_bf16 v[42:45], v[134:137], v[200:203], v[42:45]
	v_mfma_f32_16x16x32_bf16 v[30:33], v[114:117], v[208:211], v[30:33]
	v_mfma_f32_16x16x32_bf16 v[26:29], v[134:137], v[208:211], v[26:29]
	v_mfma_f32_16x16x32_bf16 v[14:17], v[114:117], v[216:219], v[14:17]
	v_mfma_f32_16x16x32_bf16 v[10:13], v[134:137], v[216:219], v[10:13]
	v_mfma_f32_16x16x32_bf16 v[62:65], v[126:129], v[196:199], v[62:65]
	v_mfma_f32_16x16x32_bf16 v[58:61], v[142:145], v[196:199], v[58:61]
	v_mfma_f32_16x16x32_bf16 v[46:49], v[126:129], v[204:207], v[46:49]
	v_mfma_f32_16x16x32_bf16 v[42:45], v[142:145], v[204:207], v[42:45]
	v_mfma_f32_16x16x32_bf16 v[30:33], v[126:129], v[212:215], v[30:33]
	v_mfma_f32_16x16x32_bf16 v[26:29], v[142:145], v[212:215], v[26:29]
	v_mfma_f32_16x16x32_bf16 v[14:17], v[126:129], v[220:223], v[14:17]
	v_mfma_f32_16x16x32_bf16 v[10:13], v[142:145], v[220:223], v[10:13]
	v_mfma_f32_16x16x32_bf16 v[54:57], v[172:175], v[188:191], v[54:57]
	v_mfma_f32_16x16x32_bf16 v[50:53], v[180:183], v[188:191], v[50:53]
	v_mfma_f32_16x16x32_bf16 v[38:41], v[172:175], v[200:203], v[38:41]
	v_mfma_f32_16x16x32_bf16 v[34:37], v[180:183], v[200:203], v[34:37]
	v_mfma_f32_16x16x32_bf16 v[22:25], v[172:175], v[208:211], v[22:25]
	v_mfma_f32_16x16x32_bf16 v[18:21], v[180:183], v[208:211], v[18:21]
	v_mfma_f32_16x16x32_bf16 v[6:9], v[172:175], v[216:219], v[6:9]
	v_mfma_f32_16x16x32_bf16 v[2:5], v[180:183], v[216:219], v[2:5]
	v_mfma_f32_16x16x32_bf16 v[54:57], v[176:179], v[196:199], v[54:57]
	v_mfma_f32_16x16x32_bf16 v[50:53], v[184:187], v[196:199], v[50:53]
	v_mfma_f32_16x16x32_bf16 v[38:41], v[176:179], v[204:207], v[38:41]
	v_mfma_f32_16x16x32_bf16 v[34:37], v[184:187], v[204:207], v[34:37]
	v_mfma_f32_16x16x32_bf16 v[22:25], v[176:179], v[212:215], v[22:25]
	v_mfma_f32_16x16x32_bf16 v[18:21], v[184:187], v[212:215], v[18:21]
	v_mfma_f32_16x16x32_bf16 v[6:9], v[176:179], v[220:223], v[6:9]
	v_mfma_f32_16x16x32_bf16 v[2:5], v[184:187], v[220:223], v[2:5]
	s_setprio 0
	s_barrier
	s_add_i32 s71, 0, 0x18000
	s_add_i32 s72, 0, 0x1c000
	v_add_u32_e32 v142, s71, v166
	v_add_u32_e32 v184, s72, v166
	ds_read_b128 v[114:117], v142
	ds_read_b128 v[126:129], v142 offset:1024
	ds_read_b128 v[134:137], v142 offset:2048
	ds_read_b128 v[142:145], v142 offset:3072
	ds_read_b128 v[172:175], v184
	ds_read_b128 v[176:179], v184 offset:1024
	ds_read_b128 v[180:183], v184 offset:2048
	ds_read_b128 v[184:187], v184 offset:3072
	s_add_u32 s48, s48, 0x100000
	s_addc_u32 s49, s49, 0
	s_mov_b32 m0, s56
	v_lshl_add_u64 v[224:225], s[48:49], 0, v[146:147]
	ds_read_b128 v[188:191], v170 offset:32768
	ds_read_b128 v[196:199], v170 offset:33792
	ds_read_b128 v[200:203], v170 offset:34816
	ds_read_b128 v[204:207], v170 offset:35840
	ds_read_b128 v[208:211], v170 offset:36864
	ds_read_b128 v[212:215], v170 offset:37888
	ds_read_b128 v[216:219], v170 offset:38912
	ds_read_b128 v[220:223], v170 offset:39936
	global_load_lds_dwordx4 v[224:225], off
	v_lshl_add_u64 v[224:225], s[48:49], 0, v[150:151]
	s_mov_b32 m0, s57
	s_nop 0
	global_load_lds_dwordx4 v[224:225], off
	s_waitcnt vmcnt(8)
	s_waitcnt lgkmcnt(0)
	s_barrier
	s_setprio 1
	s_waitcnt lgkmcnt(0)
	v_mfma_f32_16x16x32_bf16 v[138:141], v[114:117], v[188:191], v[138:141]
	v_mfma_f32_16x16x32_bf16 v[130:133], v[134:137], v[188:191], v[130:133]
	v_mfma_f32_16x16x32_bf16 v[110:113], v[114:117], v[200:203], v[110:113]
	v_mfma_f32_16x16x32_bf16 v[106:109], v[134:137], v[200:203], v[106:109]
	v_mfma_f32_16x16x32_bf16 v[94:97], v[114:117], v[208:211], v[94:97]
	v_mfma_f32_16x16x32_bf16 v[90:93], v[134:137], v[208:211], v[90:93]
	v_mfma_f32_16x16x32_bf16 v[78:81], v[114:117], v[216:219], v[78:81]
	v_mfma_f32_16x16x32_bf16 v[74:77], v[134:137], v[216:219], v[74:77]
	v_mfma_f32_16x16x32_bf16 v[138:141], v[126:129], v[196:199], v[138:141]
	v_mfma_f32_16x16x32_bf16 v[130:133], v[142:145], v[196:199], v[130:133]
	v_mfma_f32_16x16x32_bf16 v[110:113], v[126:129], v[204:207], v[110:113]
	v_mfma_f32_16x16x32_bf16 v[106:109], v[142:145], v[204:207], v[106:109]
	v_mfma_f32_16x16x32_bf16 v[94:97], v[126:129], v[212:215], v[94:97]
	v_mfma_f32_16x16x32_bf16 v[90:93], v[142:145], v[212:215], v[90:93]
	v_mfma_f32_16x16x32_bf16 v[78:81], v[126:129], v[220:223], v[78:81]
	v_mfma_f32_16x16x32_bf16 v[74:77], v[142:145], v[220:223], v[74:77]
	v_mfma_f32_16x16x32_bf16 v[122:125], v[172:175], v[188:191], v[122:125]
	v_mfma_f32_16x16x32_bf16 v[118:121], v[180:183], v[188:191], v[118:121]
	v_mfma_f32_16x16x32_bf16 v[102:105], v[172:175], v[200:203], v[102:105]
	v_mfma_f32_16x16x32_bf16 v[98:101], v[180:183], v[200:203], v[98:101]
	v_mfma_f32_16x16x32_bf16 v[86:89], v[172:175], v[208:211], v[86:89]
	v_mfma_f32_16x16x32_bf16 v[82:85], v[180:183], v[208:211], v[82:85]
	v_mfma_f32_16x16x32_bf16 v[70:73], v[172:175], v[216:219], v[70:73]
	v_mfma_f32_16x16x32_bf16 v[66:69], v[180:183], v[216:219], v[66:69]
	v_mfma_f32_16x16x32_bf16 v[122:125], v[176:179], v[196:199], v[122:125]
	v_mfma_f32_16x16x32_bf16 v[118:121], v[184:187], v[196:199], v[118:121]
	v_mfma_f32_16x16x32_bf16 v[102:105], v[176:179], v[204:207], v[102:105]
	v_mfma_f32_16x16x32_bf16 v[98:101], v[184:187], v[204:207], v[98:101]
	v_mfma_f32_16x16x32_bf16 v[86:89], v[176:179], v[212:215], v[86:89]
	v_mfma_f32_16x16x32_bf16 v[82:85], v[184:187], v[212:215], v[82:85]
	v_mfma_f32_16x16x32_bf16 v[70:73], v[176:179], v[220:223], v[70:73]
	v_mfma_f32_16x16x32_bf16 v[66:69], v[184:187], v[220:223], v[66:69]
	s_setprio 0
	s_barrier
; #define PG8_STAGE(bufoff, gbase, voff) do { _Pragma("unroll") for (int _i = 0; _i < 2; ++_i) \
;         __builtin_amdgcn_global_load_lds((const unsigned*)((const char*)(gbase) + (voff)[_i]), (PG8_LAS unsigned*)(lds + (bufoff) + ldsw + _i * 8192), 16, 0, 0); } while (0)
; #define PG8_LDA(dst, b, h) do { _Pragma("unroll") for (int m = 0; m < 4; ++m) _Pragma("unroll") for (int k = 0; k < 2; ++k) dst[m][k] = *(const PG8_LAS bf16x8*)(lds + PG8_SA(b, h) + aoff + m * 2048 + k * 1024); } while (0)
; #define PG8_MMA(ai, bj, At, Bt) do { __builtin_amdgcn_s_setprio(1); _Pragma("unroll") for (int m = 0; m < 4; ++m) _Pragma("unroll") for (int n = 0; n < 2; ++n) _Pragma("unroll") for (int k = 0; k < 2; ++k) \
;         acc[ai][bj][m][n] = __builtin_amdgcn_mfma_f32_16x16x32_bf16(Bt[n][k], At[m][k], acc[ai][bj][m][n], 0, 0, 0); __builtin_amdgcn_s_setprio(0); } while (0)
; #define PG8_WAIT_V(n) asm volatile("s_waitcnt vmcnt(" #n ")" ::: "memory")
; #define PG8_WAIT_L(n) asm volatile("s_waitcnt lgkmcnt(" #n ")" ::: "memory")
; #define PG8_BAR __builtin_amdgcn_s_barrier()
; #define PG8_SCHED __builtin_amdgcn_sched_barrier(0)
; template <class Epi, class Sched, bool ALIGN_EPI = false, bool SP2 = false>
; __device__ __forceinline__ void gemm_phase(PG8_LAS unsigned char* lds, const Gemm g, const Sched& S, const Epi& E) {
;     ...
;         for (int t = 0; t < nt; t += 2) {
;             const bool last = (t == nt - 2);
;             const char* a1 = cA + (size_t)(t + 1) * kstep;
;             const char* a2 = last ? nA : cA + (size_t)(t + 2) * kstep; const char* b2 = last ? nB : cB + (size_t)(t + 2) * kstepB;
;             const char* a3 = a2 + kstep; const char* b3 = b2 + kstepB;
;             if (last && has_next) S.a_ready(nxt);
;     ...
;             PG8_LDA(At, 1, 1); PG8_STAGE(PG8_SB(1, 0), b3, voffB); PG8_STAGE(PG8_SB(1, 1), b3 + hstepB, voffB); PG8_STAGE(PG8_SA(1, 0), a3, voffA);
;             PG8_WAIT_V(8); PG8_WAIT_L(0); PG8_BAR; PG8_MMA(1, 0, At, B0); PG8_MMA(1, 1, At, B1); PG8_BAR; PG8_SCHED;
	s_add_u32 s48, s46, 0x8000
	s_addc_u32 s49, s47, 0
	s_add_i32 s71, s71, s53
	v_lshl_add_u64 v[224:225], s[48:49], 0, v[148:149]
	s_mov_b32 m0, s71
	ds_read_b128 v[188:191], v170 offset:49152
	ds_read_b128 v[196:199], v170 offset:50176
	ds_read_b128 v[200:203], v170 offset:51200
	ds_read_b128 v[204:207], v170 offset:52224
	ds_read_b128 v[208:211], v170 offset:53248
	ds_read_b128 v[212:215], v170 offset:54272
	ds_read_b128 v[216:219], v170 offset:55296
	ds_read_b128 v[220:223], v170 offset:56320
	global_load_lds_dwordx4 v[224:225], off
	s_add_i32 m0, s71, 0x2000
	s_add_u32 s46, s46, 0xc000
	v_lshl_add_u64 v[224:225], s[48:49], 0, v[152:153]
	s_addc_u32 s47, s47, 0
	s_add_i32 s48, s72, s53
	global_load_lds_dwordx4 v[224:225], off
	v_lshl_add_u64 v[224:225], s[46:47], 0, v[148:149]
	s_mov_b32 m0, s48
	v_lshl_add_u64 v[164:165], v[164:165], 0, s[26:27]
	global_load_lds_dwordx4 v[224:225], off
	v_lshl_add_u64 v[224:225], s[46:47], 0, v[152:153]
	s_add_i32 m0, s48, 0x2000
	s_nop 0
	global_load_lds_dwordx4 v[224:225], off
	s_mov_b32 m0, s60
	s_nop 0
	global_load_lds_dwordx4 v[164:165], off
	v_lshl_add_u64 v[164:165], v[192:193], 0, s[26:27]
	s_mov_b32 m0, s61
	s_nop 0
	global_load_lds_dwordx4 v[164:165], off
	s_waitcnt vmcnt(8)
	s_waitcnt lgkmcnt(0)
	s_barrier
	s_setprio 1
	s_waitcnt lgkmcnt(0)
	v_mfma_f32_16x16x32_bf16 v[62:65], v[114:117], v[188:191], v[62:65]
	v_mfma_f32_16x16x32_bf16 v[58:61], v[134:137], v[188:191], v[58:61]
	v_mfma_f32_16x16x32_bf16 v[46:49], v[114:117], v[200:203], v[46:49]
	v_mfma_f32_16x16x32_bf16 v[42:45], v[134:137], v[200:203], v[42:45]
	v_mfma_f32_16x16x32_bf16 v[30:33], v[114:117], v[208:211], v[30:33]
	v_mfma_f32_16x16x32_bf16 v[26:29], v[134:137], v[208:211], v[26:29]
	v_mfma_f32_16x16x32_bf16 v[14:17], v[114:117], v[216:219], v[14:17]
	v_mfma_f32_16x16x32_bf16 v[10:13], v[134:137], v[216:219], v[10:13]
	v_mfma_f32_16x16x32_bf16 v[62:65], v[126:129], v[196:199], v[62:65]
	v_mfma_f32_16x16x32_bf16 v[58:61], v[142:145], v[196:199], v[58:61]
	v_mfma_f32_16x16x32_bf16 v[46:49], v[126:129], v[204:207], v[46:49]
	v_mfma_f32_16x16x32_bf16 v[42:45], v[142:145], v[204:207], v[42:45]
	v_mfma_f32_16x16x32_bf16 v[30:33], v[126:129], v[212:215], v[30:33]
	v_mfma_f32_16x16x32_bf16 v[26:29], v[142:145], v[212:215], v[26:29]
	v_mfma_f32_16x16x32_bf16 v[14:17], v[126:129], v[220:223], v[14:17]
	v_mfma_f32_16x16x32_bf16 v[10:13], v[142:145], v[220:223], v[10:13]
	v_mfma_f32_16x16x32_bf16 v[54:57], v[172:175], v[188:191], v[54:57]
	v_mfma_f32_16x16x32_bf16 v[50:53], v[180:183], v[188:191], v[50:53]
	v_mfma_f32_16x16x32_bf16 v[38:41], v[172:175], v[200:203], v[38:41]
	v_mfma_f32_16x16x32_bf16 v[34:37], v[180:183], v[200:203], v[34:37]
	v_mfma_f32_16x16x32_bf16 v[22:25], v[172:175], v[208:211], v[22:25]
	v_mfma_f32_16x16x32_bf16 v[18:21], v[180:183], v[208:211], v[18:21]
	v_mfma_f32_16x16x32_bf16 v[6:9], v[172:175], v[216:219], v[6:9]
	v_mfma_f32_16x16x32_bf16 v[2:5], v[180:183], v[216:219], v[2:5]
	v_mfma_f32_16x16x32_bf16 v[54:57], v[176:179], v[196:199], v[54:57]
	v_mfma_f32_16x16x32_bf16 v[50:53], v[184:187], v[196:199], v[50:53]
	v_mfma_f32_16x16x32_bf16 v[38:41], v[176:179], v[204:207], v[38:41]
	v_mfma_f32_16x16x32_bf16 v[34:37], v[184:187], v[204:207], v[34:37]
	v_mfma_f32_16x16x32_bf16 v[22:25], v[176:179], v[212:215], v[22:25]
	v_mfma_f32_16x16x32_bf16 v[18:21], v[184:187], v[212:215], v[18:21]
	v_mfma_f32_16x16x32_bf16 v[6:9], v[176:179], v[220:223], v[6:9]
	v_mfma_f32_16x16x32_bf16 v[2:5], v[184:187], v[220:223], v[2:5]
	s_setprio 0
	s_barrier
	s_add_i32 s70, s70, 2
	s_add_u32 s68, s68, 0x10000
	s_addc_u32 s69, s69, 0
	s_add_u32 s36, s36, 0x100
	s_addc_u32 s37, s37, 0
	s_cmp_gt_u32 s70, 61
	s_cbranch_scc0 .LBB0_694
	s_mov_b64 s[48:49], s[80:81]
	s_and_b64 vcc, exec, s[28:29]
	s_cbranch_vccz .LBB0_697
	s_barrier

; #define PG8_STAGE(bufoff, gbase, voff) do { _Pragma("unroll") for (int _i = 0; _i < 2; ++_i) \
;         __builtin_amdgcn_global_load_lds((const unsigned*)((const char*)(gbase) + (voff)[_i]), (PG8_LAS unsigned*)(lds + (bufoff) + ldsw + _i * 8192), 16, 0, 0); } while (0)
; #define PG8_LDA(dst, b, h) do { _Pragma("unroll") for (int m = 0; m < 4; ++m) _Pragma("unroll") for (int k = 0; k < 2; ++k) dst[m][k] = *(const PG8_LAS bf16x8*)(lds + PG8_SA(b, h) + aoff + m * 2048 + k * 1024); } while (0)
; #define PG8_LDB(dst, b, h) do { _Pragma("unroll") for (int n = 0; n < 2; ++n) _Pragma("unroll") for (int k = 0; k < 2; ++k) dst[n][k] = *(const PG8_LAS bf16x8*)(lds + PG8_SB(b, h) + boff + n * 2048 + k * 1024); } while (0)
; #define PG8_MMA(ai, bj, At, Bt) do { __builtin_amdgcn_s_setprio(1); _Pragma("unroll") for (int m = 0; m < 4; ++m) _Pragma("unroll") for (int n = 0; n < 2; ++n) _Pragma("unroll") for (int k = 0; k < 2; ++k) \
;         acc[ai][bj][m][n] = __builtin_amdgcn_mfma_f32_16x16x32_bf16(Bt[n][k], At[m][k], acc[ai][bj][m][n], 0, 0, 0); __builtin_amdgcn_s_setprio(0); } while (0)
; #define PG8_WAIT_V(n) asm volatile("s_waitcnt vmcnt(" #n ")" ::: "memory")
; #define PG8_BAR __builtin_amdgcn_s_barrier()
; template <class Epi, class Sched, bool ALIGN_EPI = false, bool SP2 = false>
; __device__ __forceinline__ void gemm_phase(PG8_LAS unsigned char* lds, const Gemm g, const Sched& S, const Epi& E) {
;     ...
;         for (int t = 0; t < nt; t += 2) {
;             const bool last = (t == nt - 2);
;             const char* a1 = cA + (size_t)(t + 1) * kstep;
;             const char* a2 = last ? nA : cA + (size_t)(t + 2) * kstep; const char* b2 = last ? nB : cB + (size_t)(t + 2) * kstepB;
;             const char* a3 = a2 + kstep; const char* b3 = b2 + kstepB;
;             if (last && has_next) S.a_ready(nxt);
;             if constexpr (SP2) {
;             PG8_LDB(B0, 0, 0); PG8_LDB(B1, 0, 1); PG8_SCHED; PG8_LDA(At, 0, 0); PG8_STAGE(PG8_SA(1, 1), a1 + hstepA, voffA);
;             PG8_WAIT_V(8); PG8_WAIT_L(0); PG8_BAR; PG8_MMA(0, 0, At, B0); PG8_MMA(0, 1, At, B1); PG8_BAR; PG8_SCHED;
;             PG8_LDA(At, 0, 1); PG8_STAGE(PG8_SB(0, 0), b2, voffB); PG8_STAGE(PG8_SB(0, 1), b2 + hstepB, voffB); PG8_STAGE(PG8_SA(0, 0), a2, voffA);
;             PG8_WAIT_V(8); PG8_WAIT_L(0); PG8_BAR; PG8_MMA(1, 0, At, B0); PG8_MMA(1, 1, At, B1); PG8_BAR; PG8_SCHED;
.LBB0_773:
	ds_read_b128 v[152:155], v148
	ds_read_b128 v[156:159], v148 offset:1024
	ds_read_b128 v[160:163], v148 offset:2048
	ds_read_b128 v[164:167], v148 offset:3072
	ds_read_b128 v[168:171], v149
	ds_read_b128 v[172:175], v149 offset:1024
	ds_read_b128 v[176:179], v149 offset:2048
	ds_read_b128 v[180:183], v149 offset:3072
	s_add_u32 s46, s36, 0xfff00080
	s_addc_u32 s47, s37, -1
	s_cmp_eq_u32 s77, 60
	s_cselect_b32 s49, s41, s47
	s_cselect_b32 s48, s73, s46
	s_cselect_b32 s47, s39, s76
	s_cselect_b32 s46, s74, s75
	v_lshl_add_u64 v[236:237], s[36:37], 0, v[140:141]
	s_add_i32 m0, s54, 0xc000
	ds_read_b128 v[184:187], v150
	ds_read_b128 v[208:211], v150 offset:1024
	ds_read_b128 v[212:215], v150 offset:2048
	ds_read_b128 v[216:219], v150 offset:3072
	ds_read_b128 v[220:223], v150 offset:4096
	ds_read_b128 v[224:227], v150 offset:5120
	ds_read_b128 v[228:231], v150 offset:6144
	ds_read_b128 v[232:235], v150 offset:7168
	global_load_lds_dwordx4 v[236:237], off
	v_lshl_add_u64 v[236:237], s[36:37], 0, v[142:143]
	s_add_i32 m0, s54, 0xe000
	s_nop 0
	global_load_lds_dwordx4 v[236:237], off
	s_waitcnt vmcnt(8)
	s_waitcnt lgkmcnt(0)
	s_barrier
	s_setprio 1
	s_waitcnt lgkmcnt(0)
	v_mfma_f32_16x16x32_bf16 v[126:129], v[152:155], v[184:187], v[126:129]
	v_mfma_f32_16x16x32_bf16 v[122:125], v[160:163], v[184:187], v[122:125]
	v_mfma_f32_16x16x32_bf16 v[118:121], v[152:155], v[212:215], v[118:121]
	v_mfma_f32_16x16x32_bf16 v[114:117], v[160:163], v[212:215], v[114:117]
	v_mfma_f32_16x16x32_bf16 v[102:105], v[152:155], v[220:223], v[102:105]
	v_mfma_f32_16x16x32_bf16 v[98:101], v[160:163], v[220:223], v[98:101]
	v_mfma_f32_16x16x32_bf16 v[86:89], v[152:155], v[228:231], v[86:89]
	v_mfma_f32_16x16x32_bf16 v[82:85], v[160:163], v[228:231], v[82:85]
	v_mfma_f32_16x16x32_bf16 v[126:129], v[156:159], v[208:211], v[126:129]
	v_mfma_f32_16x16x32_bf16 v[122:125], v[164:167], v[208:211], v[122:125]
	v_mfma_f32_16x16x32_bf16 v[118:121], v[156:159], v[216:219], v[118:121]
	v_mfma_f32_16x16x32_bf16 v[114:117], v[164:167], v[216:219], v[114:117]
	v_mfma_f32_16x16x32_bf16 v[102:105], v[156:159], v[224:227], v[102:105]
	v_mfma_f32_16x16x32_bf16 v[98:101], v[164:167], v[224:227], v[98:101]
	v_mfma_f32_16x16x32_bf16 v[86:89], v[156:159], v[232:235], v[86:89]
	v_mfma_f32_16x16x32_bf16 v[82:85], v[164:167], v[232:235], v[82:85]
	v_mfma_f32_16x16x32_bf16 v[110:113], v[168:171], v[184:187], v[110:113]
	v_mfma_f32_16x16x32_bf16 v[106:109], v[176:179], v[184:187], v[106:109]
	v_mfma_f32_16x16x32_bf16 v[94:97], v[168:171], v[212:215], v[94:97]
	v_mfma_f32_16x16x32_bf16 v[90:93], v[176:179], v[212:215], v[90:93]
	v_mfma_f32_16x16x32_bf16 v[78:81], v[168:171], v[220:223], v[78:81]
	v_mfma_f32_16x16x32_bf16 v[74:77], v[176:179], v[220:223], v[74:77]
	v_mfma_f32_16x16x32_bf16 v[70:73], v[168:171], v[228:231], v[70:73]
	v_mfma_f32_16x16x32_bf16 v[66:69], v[176:179], v[228:231], v[66:69]
	v_mfma_f32_16x16x32_bf16 v[110:113], v[172:175], v[208:211], v[110:113]
	v_mfma_f32_16x16x32_bf16 v[106:109], v[180:183], v[208:211], v[106:109]
	v_mfma_f32_16x16x32_bf16 v[94:97], v[172:175], v[216:219], v[94:97]
	v_mfma_f32_16x16x32_bf16 v[90:93], v[180:183], v[216:219], v[90:93]
	v_mfma_f32_16x16x32_bf16 v[78:81], v[172:175], v[224:227], v[78:81]
	v_mfma_f32_16x16x32_bf16 v[74:77], v[180:183], v[224:227], v[74:77]
	v_mfma_f32_16x16x32_bf16 v[70:73], v[172:175], v[232:235], v[70:73]
	v_mfma_f32_16x16x32_bf16 v[66:69], v[180:183], v[232:235], v[66:69]
	s_setprio 0
	s_barrier
	s_add_i32 s78, s62, s33
	v_lshl_add_u64 v[236:237], s[46:47], 0, v[134:135]
	s_mov_b32 m0, s78
	ds_read_b128 v[184:187], v150 offset:16384
	ds_read_b128 v[208:211], v150 offset:17408
	ds_read_b128 v[212:215], v150 offset:18432
	ds_read_b128 v[216:219], v150 offset:19456
	ds_read_b128 v[220:223], v150 offset:20480
	ds_read_b128 v[224:227], v150 offset:21504
	ds_read_b128 v[228:231], v150 offset:22528
	ds_read_b128 v[232:235], v150 offset:23552
	global_load_lds_dwordx4 v[236:237], off
	s_add_i32 m0, s78, 0x2000
	s_add_u32 s78, s46, 0x4000
	v_lshl_add_u64 v[236:237], s[46:47], 0, v[130:131]
	s_addc_u32 s79, s47, 0
	s_add_i32 s80, s63, s33
	global_load_lds_dwordx4 v[236:237], off
	v_lshl_add_u64 v[236:237], s[78:79], 0, v[134:135]
	s_mov_b32 m0, s80
	v_lshl_add_u64 v[238:239], s[48:49], 0, v[132:133]
	global_load_lds_dwordx4 v[236:237], off
	v_lshl_add_u64 v[236:237], s[78:79], 0, v[130:131]
	s_add_i32 m0, s80, 0x2000
	s_nop 0
	global_load_lds_dwordx4 v[236:237], off
	v_lshl_add_u64 v[236:237], s[48:49], 0, v[136:137]
	s_mov_b32 m0, s54
	s_nop 0
	global_load_lds_dwordx4 v[236:237], off
	s_mov_b32 m0, s56
	s_nop 0
	global_load_lds_dwordx4 v[238:239], off
	s_waitcnt vmcnt(8)
	s_waitcnt lgkmcnt(0)
	s_barrier
; #define PG8_STAGE(bufoff, gbase, voff) do { _Pragma("unroll") for (int _i = 0; _i < 2; ++_i) \
;         __builtin_amdgcn_global_load_lds((const unsigned*)((const char*)(gbase) + (voff)[_i]), (PG8_LAS unsigned*)(lds + (bufoff) + ldsw + _i * 8192), 16, 0, 0); } while (0)
; #define PG8_LDA(dst, b, h) do { _Pragma("unroll") for (int m = 0; m < 4; ++m) _Pragma("unroll") for (int k = 0; k < 2; ++k) dst[m][k] = *(const PG8_LAS bf16x8*)(lds + PG8_SA(b, h) + aoff + m * 2048 + k * 1024); } while (0)
; #define PG8_LDB(dst, b, h) do { _Pragma("unroll") for (int n = 0; n < 2; ++n) _Pragma("unroll") for (int k = 0; k < 2; ++k) dst[n][k] = *(const PG8_LAS bf16x8*)(lds + PG8_SB(b, h) + boff + n * 2048 + k * 1024); } while (0)
; #define PG8_MMA(ai, bj, At, Bt) do { __builtin_amdgcn_s_setprio(1); _Pragma("unroll") for (int m = 0; m < 4; ++m) _Pragma("unroll") for (int n = 0; n < 2; ++n) _Pragma("unroll") for (int k = 0; k < 2; ++k) \
;         acc[ai][bj][m][n] = __builtin_amdgcn_mfma_f32_16x16x32_bf16(Bt[n][k], At[m][k], acc[ai][bj][m][n], 0, 0, 0); __builtin_amdgcn_s_setprio(0); } while (0)
; #define PG8_WAIT_V(n) asm volatile("s_waitcnt vmcnt(" #n ")" ::: "memory")
; #define PG8_WAIT_L(n) asm volatile("s_waitcnt lgkmcnt(" #n ")" ::: "memory")
; #define PG8_BAR __builtin_amdgcn_s_barrier()
; #define PG8_SCHED __builtin_amdgcn_sched_barrier(0)
; template <class Epi, class Sched, bool ALIGN_EPI = false, bool SP2 = false>
; __device__ __forceinline__ void gemm_phase(PG8_LAS unsigned char* lds, const Gemm g, const Sched& S, const Epi& E) {
;     ...
;             PG8_WAIT_V(8); PG8_WAIT_L(0); PG8_BAR; PG8_MMA(1, 0, At, B0); PG8_MMA(1, 1, At, B1); PG8_BAR; PG8_SCHED;
;             PG8_LDB(B0, 1, 0); PG8_LDB(B1, 1, 1); PG8_SCHED; PG8_LDA(At, 1, 0); PG8_STAGE(PG8_SA(0, 1), a2 + hstepA, voffA);
;             PG8_WAIT_V(8); PG8_WAIT_L(0); PG8_BAR; PG8_MMA(0, 0, At, B0); PG8_MMA(0, 1, At, B1); PG8_BAR; PG8_SCHED;
;             PG8_LDA(At, 1, 1); PG8_STAGE(PG8_SB(1, 0), b3, voffB); PG8_STAGE(PG8_SB(1, 1), b3 + hstepB, voffB); PG8_STAGE(PG8_SA(1, 0), a3, voffA);
	s_setprio 1
	s_waitcnt lgkmcnt(0)
	v_mfma_f32_16x16x32_bf16 v[62:65], v[152:155], v[184:187], v[62:65]
	v_mfma_f32_16x16x32_bf16 v[58:61], v[160:163], v[184:187], v[58:61]
	v_mfma_f32_16x16x32_bf16 v[54:57], v[152:155], v[212:215], v[54:57]
	v_mfma_f32_16x16x32_bf16 v[50:53], v[160:163], v[212:215], v[50:53]
	v_mfma_f32_16x16x32_bf16 v[38:41], v[152:155], v[220:223], v[38:41]
	v_mfma_f32_16x16x32_bf16 v[34:37], v[160:163], v[220:223], v[34:37]
	v_mfma_f32_16x16x32_bf16 v[22:25], v[152:155], v[228:231], v[22:25]
	v_mfma_f32_16x16x32_bf16 v[18:21], v[160:163], v[228:231], v[18:21]
	v_mfma_f32_16x16x32_bf16 v[62:65], v[156:159], v[208:211], v[62:65]
	v_mfma_f32_16x16x32_bf16 v[58:61], v[164:167], v[208:211], v[58:61]
	v_mfma_f32_16x16x32_bf16 v[54:57], v[156:159], v[216:219], v[54:57]
	v_mfma_f32_16x16x32_bf16 v[50:53], v[164:167], v[216:219], v[50:53]
	v_mfma_f32_16x16x32_bf16 v[38:41], v[156:159], v[224:227], v[38:41]
	v_mfma_f32_16x16x32_bf16 v[34:37], v[164:167], v[224:227], v[34:37]
	v_mfma_f32_16x16x32_bf16 v[22:25], v[156:159], v[232:235], v[22:25]
	v_mfma_f32_16x16x32_bf16 v[18:21], v[164:167], v[232:235], v[18:21]
	v_mfma_f32_16x16x32_bf16 v[46:49], v[168:171], v[184:187], v[46:49]
	v_mfma_f32_16x16x32_bf16 v[42:45], v[176:179], v[184:187], v[42:45]
	v_mfma_f32_16x16x32_bf16 v[30:33], v[168:171], v[212:215], v[30:33]
	v_mfma_f32_16x16x32_bf16 v[26:29], v[176:179], v[212:215], v[26:29]
	v_mfma_f32_16x16x32_bf16 v[14:17], v[168:171], v[220:223], v[14:17]
	v_mfma_f32_16x16x32_bf16 v[10:13], v[176:179], v[220:223], v[10:13]
	v_mfma_f32_16x16x32_bf16 v[6:9], v[168:171], v[228:231], v[6:9]
	v_mfma_f32_16x16x32_bf16 v[2:5], v[176:179], v[228:231], v[2:5]
	v_mfma_f32_16x16x32_bf16 v[46:49], v[172:175], v[208:211], v[46:49]
	v_mfma_f32_16x16x32_bf16 v[42:45], v[180:183], v[208:211], v[42:45]
	v_mfma_f32_16x16x32_bf16 v[30:33], v[172:175], v[216:219], v[30:33]
	v_mfma_f32_16x16x32_bf16 v[26:29], v[180:183], v[216:219], v[26:29]
	v_mfma_f32_16x16x32_bf16 v[14:17], v[172:175], v[224:227], v[14:17]
	v_mfma_f32_16x16x32_bf16 v[10:13], v[180:183], v[224:227], v[10:13]
	v_mfma_f32_16x16x32_bf16 v[6:9], v[172:175], v[232:235], v[6:9]
	v_mfma_f32_16x16x32_bf16 v[2:5], v[180:183], v[232:235], v[2:5]
	s_setprio 0
	s_barrier
	s_add_i32 s78, 0, 0x18000
	v_add_u32_e32 v151, s78, v1
	s_add_i32 s79, 0, 0x1c000
	ds_read_b128 v[152:155], v151
	ds_read_b128 v[156:159], v151 offset:1024
	ds_read_b128 v[160:163], v151 offset:2048
	ds_read_b128 v[164:167], v151 offset:3072
	v_add_u32_e32 v151, s79, v1
	ds_read_b128 v[168:171], v151
	ds_read_b128 v[172:175], v151 offset:1024
	ds_read_b128 v[176:179], v151 offset:2048
	ds_read_b128 v[180:183], v151 offset:3072
	s_add_u32 s48, s48, 0x100000
	s_addc_u32 s49, s49, 0
	s_mov_b32 m0, s57
	v_lshl_add_u64 v[240:241], s[48:49], 0, v[136:137]
	ds_read_b128 v[184:187], v150 offset:32768
	ds_read_b128 v[208:211], v150 offset:33792
	ds_read_b128 v[212:215], v150 offset:34816
	ds_read_b128 v[216:219], v150 offset:35840
	ds_read_b128 v[220:223], v150 offset:36864
	ds_read_b128 v[224:227], v150 offset:37888
	ds_read_b128 v[228:231], v150 offset:38912
	ds_read_b128 v[232:235], v150 offset:39936
	global_load_lds_dwordx4 v[240:241], off
	v_lshl_add_u64 v[240:241], s[48:49], 0, v[132:133]
	s_mov_b32 m0, s58
	s_nop 0
	global_load_lds_dwordx4 v[240:241], off
	s_waitcnt vmcnt(8)
	s_waitcnt lgkmcnt(0)
	s_barrier
	s_setprio 1
	s_waitcnt lgkmcnt(0)
	v_mfma_f32_16x16x32_bf16 v[126:129], v[152:155], v[184:187], v[126:129]
	v_mfma_f32_16x16x32_bf16 v[122:125], v[160:163], v[184:187], v[122:125]
	v_mfma_f32_16x16x32_bf16 v[118:121], v[152:155], v[212:215], v[118:121]
	v_mfma_f32_16x16x32_bf16 v[114:117], v[160:163], v[212:215], v[114:117]
	v_mfma_f32_16x16x32_bf16 v[102:105], v[152:155], v[220:223], v[102:105]
	v_mfma_f32_16x16x32_bf16 v[98:101], v[160:163], v[220:223], v[98:101]
	v_mfma_f32_16x16x32_bf16 v[86:89], v[152:155], v[228:231], v[86:89]
	v_mfma_f32_16x16x32_bf16 v[82:85], v[160:163], v[228:231], v[82:85]
	v_mfma_f32_16x16x32_bf16 v[126:129], v[156:159], v[208:211], v[126:129]
	v_mfma_f32_16x16x32_bf16 v[122:125], v[164:167], v[208:211], v[122:125]
	v_mfma_f32_16x16x32_bf16 v[118:121], v[156:159], v[216:219], v[118:121]
	v_mfma_f32_16x16x32_bf16 v[114:117], v[164:167], v[216:219], v[114:117]
	v_mfma_f32_16x16x32_bf16 v[102:105], v[156:159], v[224:227], v[102:105]
	v_mfma_f32_16x16x32_bf16 v[98:101], v[164:167], v[224:227], v[98:101]
	v_mfma_f32_16x16x32_bf16 v[86:89], v[156:159], v[232:235], v[86:89]
	v_mfma_f32_16x16x32_bf16 v[82:85], v[164:167], v[232:235], v[82:85]
	v_mfma_f32_16x16x32_bf16 v[110:113], v[168:171], v[184:187], v[110:113]
	v_mfma_f32_16x16x32_bf16 v[106:109], v[176:179], v[184:187], v[106:109]
	v_mfma_f32_16x16x32_bf16 v[94:97], v[168:171], v[212:215], v[94:97]
	v_mfma_f32_16x16x32_bf16 v[90:93], v[176:179], v[212:215], v[90:93]
	v_mfma_f32_16x16x32_bf16 v[78:81], v[168:171], v[220:223], v[78:81]
	v_mfma_f32_16x16x32_bf16 v[74:77], v[176:179], v[220:223], v[74:77]
	v_mfma_f32_16x16x32_bf16 v[70:73], v[168:171], v[228:231], v[70:73]
	v_mfma_f32_16x16x32_bf16 v[66:69], v[176:179], v[228:231], v[66:69]
	v_mfma_f32_16x16x32_bf16 v[110:113], v[172:175], v[208:211], v[110:113]
	v_mfma_f32_16x16x32_bf16 v[106:109], v[180:183], v[208:211], v[106:109]
	v_mfma_f32_16x16x32_bf16 v[94:97], v[172:175], v[216:219], v[94:97]
	v_mfma_f32_16x16x32_bf16 v[90:93], v[180:183], v[216:219], v[90:93]
	v_mfma_f32_16x16x32_bf16 v[78:81], v[172:175], v[224:227], v[78:81]
	v_mfma_f32_16x16x32_bf16 v[74:77], v[180:183], v[224:227], v[74:77]
	v_mfma_f32_16x16x32_bf16 v[70:73], v[172:175], v[232:235], v[70:73]
	v_mfma_f32_16x16x32_bf16 v[66:69], v[180:183], v[232:235], v[66:69]
	s_setprio 0
	s_barrier
; #define PG8_STAGE(bufoff, gbase, voff) do { _Pragma("unroll") for (int _i = 0; _i < 2; ++_i) \
;         __builtin_amdgcn_global_load_lds((const unsigned*)((const char*)(gbase) + (voff)[_i]), (PG8_LAS unsigned*)(lds + (bufoff) + ldsw + _i * 8192), 16, 0, 0); } while (0)
; #define PG8_LDA(dst, b, h) do { _Pragma("unroll") for (int m = 0; m < 4; ++m) _Pragma("unroll") for (int k = 0; k < 2; ++k) dst[m][k] = *(const PG8_LAS bf16x8*)(lds + PG8_SA(b, h) + aoff + m * 2048 + k * 1024); } while (0)
; #define PG8_MMA(ai, bj, At, Bt) do { __builtin_amdgcn_s_setprio(1); _Pragma("unroll") for (int m = 0; m < 4; ++m) _Pragma("unroll") for (int n = 0; n < 2; ++n) _Pragma("unroll") for (int k = 0; k < 2; ++k) \
;         acc[ai][bj][m][n] = __builtin_amdgcn_mfma_f32_16x16x32_bf16(Bt[n][k], At[m][k], acc[ai][bj][m][n], 0, 0, 0); __builtin_amdgcn_s_setprio(0); } while (0)
; #define PG8_WAIT_V(n) asm volatile("s_waitcnt vmcnt(" #n ")" ::: "memory")
; #define PG8_WAIT_L(n) asm volatile("s_waitcnt lgkmcnt(" #n ")" ::: "memory")
; #define PG8_BAR __builtin_amdgcn_s_barrier()
; #define PG8_SCHED __builtin_amdgcn_sched_barrier(0)
; template <class Epi, class Sched, bool ALIGN_EPI = false, bool SP2 = false>
; __device__ __forceinline__ void gemm_phase(PG8_LAS unsigned char* lds, const Gemm g, const Sched& S, const Epi& E) {
;     ...
;         for (int t = 0; t < nt; t += 2) {
;             const bool last = (t == nt - 2);
;             const char* a1 = cA + (size_t)(t + 1) * kstep;
;             const char* a2 = last ? nA : cA + (size_t)(t + 2) * kstep; const char* b2 = last ? nB : cB + (size_t)(t + 2) * kstepB;
;             const char* a3 = a2 + kstep; const char* b3 = b2 + kstepB;
;             if (last && has_next) S.a_ready(nxt);
;     ...
;             PG8_LDA(At, 1, 1); PG8_STAGE(PG8_SB(1, 0), b3, voffB); PG8_STAGE(PG8_SB(1, 1), b3 + hstepB, voffB); PG8_STAGE(PG8_SA(1, 0), a3, voffA);
;             PG8_WAIT_V(8); PG8_WAIT_L(0); PG8_BAR; PG8_MMA(1, 0, At, B0); PG8_MMA(1, 1, At, B1); PG8_BAR; PG8_SCHED;
	s_add_u32 s48, s46, 0x8000
	s_addc_u32 s49, s47, 0
	s_add_i32 s78, s78, s33
	v_lshl_add_u64 v[240:241], s[48:49], 0, v[134:135]
	s_mov_b32 m0, s78
	ds_read_b128 v[184:187], v150 offset:49152
	ds_read_b128 v[208:211], v150 offset:50176
	ds_read_b128 v[212:215], v150 offset:51200
	ds_read_b128 v[216:219], v150 offset:52224
	ds_read_b128 v[220:223], v150 offset:53248
	ds_read_b128 v[224:227], v150 offset:54272
	ds_read_b128 v[228:231], v150 offset:55296
	ds_read_b128 v[232:235], v150 offset:56320
	global_load_lds_dwordx4 v[240:241], off
	s_add_i32 m0, s78, 0x2000
	s_add_u32 s46, s46, 0xc000
	v_lshl_add_u64 v[240:241], s[48:49], 0, v[130:131]
	s_addc_u32 s47, s47, 0
	s_add_i32 s48, s79, s33
	global_load_lds_dwordx4 v[240:241], off
	v_lshl_add_u64 v[240:241], s[46:47], 0, v[134:135]
	s_mov_b32 m0, s48
	v_lshl_add_u64 v[236:237], v[236:237], 0, s[30:31]
	global_load_lds_dwordx4 v[240:241], off
	v_lshl_add_u64 v[240:241], s[46:47], 0, v[130:131]
	s_add_i32 m0, s48, 0x2000
	s_nop 0
	global_load_lds_dwordx4 v[240:241], off
	s_mov_b32 m0, s60
	s_nop 0
	global_load_lds_dwordx4 v[236:237], off
	v_lshl_add_u64 v[236:237], v[238:239], 0, s[30:31]
	s_mov_b32 m0, s61
	s_nop 0
	global_load_lds_dwordx4 v[236:237], off
	s_waitcnt vmcnt(8)
	s_waitcnt lgkmcnt(0)
	s_barrier
	s_setprio 1
	s_waitcnt lgkmcnt(0)
	v_mfma_f32_16x16x32_bf16 v[62:65], v[152:155], v[184:187], v[62:65]
	v_mfma_f32_16x16x32_bf16 v[58:61], v[160:163], v[184:187], v[58:61]
	v_mfma_f32_16x16x32_bf16 v[54:57], v[152:155], v[212:215], v[54:57]
	v_mfma_f32_16x16x32_bf16 v[50:53], v[160:163], v[212:215], v[50:53]
	v_mfma_f32_16x16x32_bf16 v[38:41], v[152:155], v[220:223], v[38:41]
	v_mfma_f32_16x16x32_bf16 v[34:37], v[160:163], v[220:223], v[34:37]
	v_mfma_f32_16x16x32_bf16 v[22:25], v[152:155], v[228:231], v[22:25]
	v_mfma_f32_16x16x32_bf16 v[18:21], v[160:163], v[228:231], v[18:21]
	v_mfma_f32_16x16x32_bf16 v[62:65], v[156:159], v[208:211], v[62:65]
	v_mfma_f32_16x16x32_bf16 v[58:61], v[164:167], v[208:211], v[58:61]
	v_mfma_f32_16x16x32_bf16 v[54:57], v[156:159], v[216:219], v[54:57]
	v_mfma_f32_16x16x32_bf16 v[50:53], v[164:167], v[216:219], v[50:53]
	v_mfma_f32_16x16x32_bf16 v[38:41], v[156:159], v[224:227], v[38:41]
	v_mfma_f32_16x16x32_bf16 v[34:37], v[164:167], v[224:227], v[34:37]
	v_mfma_f32_16x16x32_bf16 v[22:25], v[156:159], v[232:235], v[22:25]
	v_mfma_f32_16x16x32_bf16 v[18:21], v[164:167], v[232:235], v[18:21]
	v_mfma_f32_16x16x32_bf16 v[46:49], v[168:171], v[184:187], v[46:49]
	v_mfma_f32_16x16x32_bf16 v[42:45], v[176:179], v[184:187], v[42:45]
	v_mfma_f32_16x16x32_bf16 v[30:33], v[168:171], v[212:215], v[30:33]
	v_mfma_f32_16x16x32_bf16 v[26:29], v[176:179], v[212:215], v[26:29]
	v_mfma_f32_16x16x32_bf16 v[14:17], v[168:171], v[220:223], v[14:17]
	v_mfma_f32_16x16x32_bf16 v[10:13], v[176:179], v[220:223], v[10:13]
	v_mfma_f32_16x16x32_bf16 v[6:9], v[168:171], v[228:231], v[6:9]
	v_mfma_f32_16x16x32_bf16 v[2:5], v[176:179], v[228:231], v[2:5]
	v_mfma_f32_16x16x32_bf16 v[46:49], v[172:175], v[208:211], v[46:49]
	v_mfma_f32_16x16x32_bf16 v[42:45], v[180:183], v[208:211], v[42:45]
	v_mfma_f32_16x16x32_bf16 v[30:33], v[172:175], v[216:219], v[30:33]
	v_mfma_f32_16x16x32_bf16 v[26:29], v[180:183], v[216:219], v[26:29]
	v_mfma_f32_16x16x32_bf16 v[14:17], v[172:175], v[224:227], v[14:17]
	v_mfma_f32_16x16x32_bf16 v[10:13], v[180:183], v[224:227], v[10:13]
	v_mfma_f32_16x16x32_bf16 v[6:9], v[172:175], v[232:235], v[6:9]
	v_mfma_f32_16x16x32_bf16 v[2:5], v[180:183], v[232:235], v[2:5]
	s_setprio 0
	s_barrier
	s_add_i32 s77, s77, 2
	s_add_u32 s75, s75, 0x10000
	s_addc_u32 s76, s76, 0
	s_add_u32 s36, s36, 0x100
	s_addc_u32 s37, s37, 0
	s_cmp_gt_u32 s77, 61
	s_cbranch_scc0 .LBB0_773
	s_and_b64 vcc, exec, s[34:35]
	s_cbranch_vccz .LBB0_776
	s_barrier

; #define PG8_STAGE(bufoff, gbase, voff) do { _Pragma("unroll") for (int _i = 0; _i < 2; ++_i) \
;         __builtin_amdgcn_global_load_lds((const unsigned*)((const char*)(gbase) + (voff)[_i]), (PG8_LAS unsigned*)(lds + (bufoff) + ldsw + _i * 8192), 16, 0, 0); } while (0)
; #define PG8_LDA(dst, b, h) do { _Pragma("unroll") for (int m = 0; m < 4; ++m) _Pragma("unroll") for (int k = 0; k < 2; ++k) dst[m][k] = *(const PG8_LAS bf16x8*)(lds + PG8_SA(b, h) + aoff + m * 2048 + k * 1024); } while (0)
; #define PG8_LDB(dst, b, h) do { _Pragma("unroll") for (int n = 0; n < 2; ++n) _Pragma("unroll") for (int k = 0; k < 2; ++k) dst[n][k] = *(const PG8_LAS bf16x8*)(lds + PG8_SB(b, h) + boff + n * 2048 + k * 1024); } while (0)
; #define PG8_MMA(ai, bj, At, Bt) do { __builtin_amdgcn_s_setprio(1); _Pragma("unroll") for (int m = 0; m < 4; ++m) _Pragma("unroll") for (int n = 0; n < 2; ++n) _Pragma("unroll") for (int k = 0; k < 2; ++k) \
;         acc[ai][bj][m][n] = __builtin_amdgcn_mfma_f32_16x16x32_bf16(Bt[n][k], At[m][k], acc[ai][bj][m][n], 0, 0, 0); __builtin_amdgcn_s_setprio(0); } while (0)
; #define PG8_WAIT_V(n) asm volatile("s_waitcnt vmcnt(" #n ")" ::: "memory")
; #define PG8_BAR __builtin_amdgcn_s_barrier()
; template <class Epi, class Sched, bool ALIGN_EPI = false, bool SP2 = false>
; __device__ __forceinline__ void gemm_phase(PG8_LAS unsigned char* lds, const Gemm g, const Sched& S, const Epi& E) {
;     ...
;         for (int t = 0; t < nt; t += 2) {
;             const bool last = (t == nt - 2);
;             const char* a1 = cA + (size_t)(t + 1) * kstep;
;             const char* a2 = last ? nA : cA + (size_t)(t + 2) * kstep; const char* b2 = last ? nB : cB + (size_t)(t + 2) * kstepB;
;             const char* a3 = a2 + kstep; const char* b3 = b2 + kstepB;
;             if (last && has_next) S.a_ready(nxt);
;             if constexpr (SP2) {
;             PG8_LDB(B0, 0, 0); PG8_LDB(B1, 0, 1); PG8_SCHED; PG8_LDA(At, 0, 0); PG8_STAGE(PG8_SA(1, 1), a1 + hstepA, voffA);
;             PG8_WAIT_V(8); PG8_WAIT_L(0); PG8_BAR; PG8_MMA(0, 0, At, B0); PG8_MMA(0, 1, At, B1); PG8_BAR; PG8_SCHED;
;             PG8_LDA(At, 0, 1); PG8_STAGE(PG8_SB(0, 0), b2, voffB); PG8_STAGE(PG8_SB(0, 1), b2 + hstepB, voffB); PG8_STAGE(PG8_SA(0, 0), a2, voffA);
;             PG8_WAIT_V(8); PG8_WAIT_L(0); PG8_BAR; PG8_MMA(1, 0, At, B0); PG8_MMA(1, 1, At, B1); PG8_BAR; PG8_SCHED;
.LBB0_870:
	ds_read_b128 v[114:117], v168
	ds_read_b128 v[118:121], v168 offset:1024
	ds_read_b128 v[130:133], v168 offset:2048
	ds_read_b128 v[134:137], v168 offset:3072
	ds_read_b128 v[172:175], v169
	ds_read_b128 v[176:179], v169 offset:1024
	ds_read_b128 v[180:183], v169 offset:2048
	ds_read_b128 v[184:187], v169 offset:3072
	s_add_u32 s44, s42, 0x100
	s_addc_u32 s45, s43, 0
	s_cmpk_eq_i32 s78, 0xa8
	s_cselect_b32 s49, s7, s45
	s_cselect_b32 s48, s6, s44
	s_cselect_b32 s47, s41, s77
	s_cselect_b32 s46, s40, s76
	v_lshl_add_u64 v[164:165], s[42:43], 0, v[156:157]
	s_add_i32 m0, s52, 0xc000
	ds_read_b128 v[208:211], v170
	ds_read_b128 v[212:215], v170 offset:1024
	ds_read_b128 v[216:219], v170 offset:2048
	ds_read_b128 v[220:223], v170 offset:3072
	ds_read_b128 v[224:227], v170 offset:4096
	ds_read_b128 v[228:231], v170 offset:5120
	ds_read_b128 v[232:235], v170 offset:6144
	ds_read_b128 v[236:239], v170 offset:7168
	global_load_lds_dwordx4 v[164:165], off
	v_lshl_add_u64 v[164:165], s[42:43], 0, v[158:159]
	s_add_i32 m0, s52, 0xe000
	s_nop 0
	global_load_lds_dwordx4 v[164:165], off
	s_waitcnt vmcnt(8)
	s_waitcnt lgkmcnt(0)
	s_barrier
	s_setprio 1
	s_waitcnt lgkmcnt(0)
	v_mfma_f32_16x16x32_bf16 v[142:145], v[114:117], v[208:211], v[142:145]
	v_mfma_f32_16x16x32_bf16 v[138:141], v[130:133], v[208:211], v[138:141]
	v_mfma_f32_16x16x32_bf16 v[110:113], v[114:117], v[216:219], v[110:113]
	v_mfma_f32_16x16x32_bf16 v[106:109], v[130:133], v[216:219], v[106:109]
	v_mfma_f32_16x16x32_bf16 v[94:97], v[114:117], v[224:227], v[94:97]
	v_mfma_f32_16x16x32_bf16 v[90:93], v[130:133], v[224:227], v[90:93]
	v_mfma_f32_16x16x32_bf16 v[78:81], v[114:117], v[232:235], v[78:81]
	v_mfma_f32_16x16x32_bf16 v[74:77], v[130:133], v[232:235], v[74:77]
	v_mfma_f32_16x16x32_bf16 v[142:145], v[118:121], v[212:215], v[142:145]
	v_mfma_f32_16x16x32_bf16 v[138:141], v[134:137], v[212:215], v[138:141]
	v_mfma_f32_16x16x32_bf16 v[110:113], v[118:121], v[220:223], v[110:113]
	v_mfma_f32_16x16x32_bf16 v[106:109], v[134:137], v[220:223], v[106:109]
	v_mfma_f32_16x16x32_bf16 v[94:97], v[118:121], v[228:231], v[94:97]
	v_mfma_f32_16x16x32_bf16 v[90:93], v[134:137], v[228:231], v[90:93]
	v_mfma_f32_16x16x32_bf16 v[78:81], v[118:121], v[236:239], v[78:81]
	v_mfma_f32_16x16x32_bf16 v[74:77], v[134:137], v[236:239], v[74:77]
	v_mfma_f32_16x16x32_bf16 v[126:129], v[172:175], v[208:211], v[126:129]
	v_mfma_f32_16x16x32_bf16 v[122:125], v[180:183], v[208:211], v[122:125]
	v_mfma_f32_16x16x32_bf16 v[102:105], v[172:175], v[216:219], v[102:105]
	v_mfma_f32_16x16x32_bf16 v[98:101], v[180:183], v[216:219], v[98:101]
	v_mfma_f32_16x16x32_bf16 v[86:89], v[172:175], v[224:227], v[86:89]
	v_mfma_f32_16x16x32_bf16 v[82:85], v[180:183], v[224:227], v[82:85]
	v_mfma_f32_16x16x32_bf16 v[70:73], v[172:175], v[232:235], v[70:73]
	v_mfma_f32_16x16x32_bf16 v[66:69], v[180:183], v[232:235], v[66:69]
	v_mfma_f32_16x16x32_bf16 v[126:129], v[176:179], v[212:215], v[126:129]
	v_mfma_f32_16x16x32_bf16 v[122:125], v[184:187], v[212:215], v[122:125]
	v_mfma_f32_16x16x32_bf16 v[102:105], v[176:179], v[220:223], v[102:105]
	v_mfma_f32_16x16x32_bf16 v[98:101], v[184:187], v[220:223], v[98:101]
	v_mfma_f32_16x16x32_bf16 v[86:89], v[176:179], v[228:231], v[86:89]
	v_mfma_f32_16x16x32_bf16 v[82:85], v[184:187], v[228:231], v[82:85]
	v_mfma_f32_16x16x32_bf16 v[70:73], v[176:179], v[236:239], v[70:73]
	v_mfma_f32_16x16x32_bf16 v[66:69], v[184:187], v[236:239], v[66:69]
	s_setprio 0
	s_barrier
	s_add_i32 s42, s62, s33
	v_lshl_add_u64 v[164:165], s[46:47], 0, v[148:149]
	s_mov_b32 m0, s42
	ds_read_b128 v[208:211], v170 offset:16384
	ds_read_b128 v[212:215], v170 offset:17408
	ds_read_b128 v[216:219], v170 offset:18432
	ds_read_b128 v[220:223], v170 offset:19456
	ds_read_b128 v[224:227], v170 offset:20480
	ds_read_b128 v[228:231], v170 offset:21504
	ds_read_b128 v[232:235], v170 offset:22528
	ds_read_b128 v[236:239], v170 offset:23552
	global_load_lds_dwordx4 v[164:165], off
	s_add_i32 m0, s42, 0x2000
	s_add_u32 s42, s46, 0x4000
	v_lshl_add_u64 v[164:165], s[46:47], 0, v[152:153]
	s_addc_u32 s43, s47, 0
	s_add_i32 s79, s63, s33
	global_load_lds_dwordx4 v[164:165], off
	v_lshl_add_u64 v[164:165], s[42:43], 0, v[148:149]
	s_mov_b32 m0, s79
	v_lshl_add_u64 v[240:241], s[48:49], 0, v[150:151]
	global_load_lds_dwordx4 v[164:165], off
	v_lshl_add_u64 v[164:165], s[42:43], 0, v[152:153]
	s_add_i32 m0, s79, 0x2000
	s_nop 0
	global_load_lds_dwordx4 v[164:165], off
	v_lshl_add_u64 v[164:165], s[48:49], 0, v[146:147]
	s_mov_b32 m0, s52
	s_nop 0
	global_load_lds_dwordx4 v[164:165], off
	s_mov_b32 m0, s55
	s_nop 0
	global_load_lds_dwordx4 v[240:241], off
	s_waitcnt vmcnt(8)
	s_waitcnt lgkmcnt(0)
	s_barrier
; #define PG8_STAGE(bufoff, gbase, voff) do { _Pragma("unroll") for (int _i = 0; _i < 2; ++_i) \
;         __builtin_amdgcn_global_load_lds((const unsigned*)((const char*)(gbase) + (voff)[_i]), (PG8_LAS unsigned*)(lds + (bufoff) + ldsw + _i * 8192), 16, 0, 0); } while (0)
; #define PG8_LDA(dst, b, h) do { _Pragma("unroll") for (int m = 0; m < 4; ++m) _Pragma("unroll") for (int k = 0; k < 2; ++k) dst[m][k] = *(const PG8_LAS bf16x8*)(lds + PG8_SA(b, h) + aoff + m * 2048 + k * 1024); } while (0)
; #define PG8_LDB(dst, b, h) do { _Pragma("unroll") for (int n = 0; n < 2; ++n) _Pragma("unroll") for (int k = 0; k < 2; ++k) dst[n][k] = *(const PG8_LAS bf16x8*)(lds + PG8_SB(b, h) + boff + n * 2048 + k * 1024); } while (0)
; #define PG8_MMA(ai, bj, At, Bt) do { __builtin_amdgcn_s_setprio(1); _Pragma("unroll") for (int m = 0; m < 4; ++m) _Pragma("unroll") for (int n = 0; n < 2; ++n) _Pragma("unroll") for (int k = 0; k < 2; ++k) \
;         acc[ai][bj][m][n] = __builtin_amdgcn_mfma_f32_16x16x32_bf16(Bt[n][k], At[m][k], acc[ai][bj][m][n], 0, 0, 0); __builtin_amdgcn_s_setprio(0); } while (0)
; #define PG8_WAIT_V(n) asm volatile("s_waitcnt vmcnt(" #n ")" ::: "memory")
; #define PG8_WAIT_L(n) asm volatile("s_waitcnt lgkmcnt(" #n ")" ::: "memory")
; #define PG8_BAR __builtin_amdgcn_s_barrier()
; #define PG8_SCHED __builtin_amdgcn_sched_barrier(0)
; template <class Epi, class Sched, bool ALIGN_EPI = false, bool SP2 = false>
; __device__ __forceinline__ void gemm_phase(PG8_LAS unsigned char* lds, const Gemm g, const Sched& S, const Epi& E) {
;     ...
;             PG8_WAIT_V(8); PG8_WAIT_L(0); PG8_BAR; PG8_MMA(1, 0, At, B0); PG8_MMA(1, 1, At, B1); PG8_BAR; PG8_SCHED;
;             PG8_LDB(B0, 1, 0); PG8_LDB(B1, 1, 1); PG8_SCHED; PG8_LDA(At, 1, 0); PG8_STAGE(PG8_SA(0, 1), a2 + hstepA, voffA);
;             PG8_WAIT_V(8); PG8_WAIT_L(0); PG8_BAR; PG8_MMA(0, 0, At, B0); PG8_MMA(0, 1, At, B1); PG8_BAR; PG8_SCHED;
;             PG8_LDA(At, 1, 1); PG8_STAGE(PG8_SB(1, 0), b3, voffB); PG8_STAGE(PG8_SB(1, 1), b3 + hstepB, voffB); PG8_STAGE(PG8_SA(1, 0), a3, voffA);
	s_setprio 1
	s_waitcnt lgkmcnt(0)
	v_mfma_f32_16x16x32_bf16 v[62:65], v[114:117], v[208:211], v[62:65]
	v_mfma_f32_16x16x32_bf16 v[58:61], v[130:133], v[208:211], v[58:61]
	v_mfma_f32_16x16x32_bf16 v[46:49], v[114:117], v[216:219], v[46:49]
	v_mfma_f32_16x16x32_bf16 v[42:45], v[130:133], v[216:219], v[42:45]
	v_mfma_f32_16x16x32_bf16 v[30:33], v[114:117], v[224:227], v[30:33]
	v_mfma_f32_16x16x32_bf16 v[26:29], v[130:133], v[224:227], v[26:29]
	v_mfma_f32_16x16x32_bf16 v[14:17], v[114:117], v[232:235], v[14:17]
	v_mfma_f32_16x16x32_bf16 v[10:13], v[130:133], v[232:235], v[10:13]
	v_mfma_f32_16x16x32_bf16 v[62:65], v[118:121], v[212:215], v[62:65]
	v_mfma_f32_16x16x32_bf16 v[58:61], v[134:137], v[212:215], v[58:61]
	v_mfma_f32_16x16x32_bf16 v[46:49], v[118:121], v[220:223], v[46:49]
	v_mfma_f32_16x16x32_bf16 v[42:45], v[134:137], v[220:223], v[42:45]
	v_mfma_f32_16x16x32_bf16 v[30:33], v[118:121], v[228:231], v[30:33]
	v_mfma_f32_16x16x32_bf16 v[26:29], v[134:137], v[228:231], v[26:29]
	v_mfma_f32_16x16x32_bf16 v[14:17], v[118:121], v[236:239], v[14:17]
	v_mfma_f32_16x16x32_bf16 v[10:13], v[134:137], v[236:239], v[10:13]
	v_mfma_f32_16x16x32_bf16 v[54:57], v[172:175], v[208:211], v[54:57]
	v_mfma_f32_16x16x32_bf16 v[50:53], v[180:183], v[208:211], v[50:53]
	v_mfma_f32_16x16x32_bf16 v[38:41], v[172:175], v[216:219], v[38:41]
	v_mfma_f32_16x16x32_bf16 v[34:37], v[180:183], v[216:219], v[34:37]
	v_mfma_f32_16x16x32_bf16 v[22:25], v[172:175], v[224:227], v[22:25]
	v_mfma_f32_16x16x32_bf16 v[18:21], v[180:183], v[224:227], v[18:21]
	v_mfma_f32_16x16x32_bf16 v[6:9], v[172:175], v[232:235], v[6:9]
	v_mfma_f32_16x16x32_bf16 v[2:5], v[180:183], v[232:235], v[2:5]
	v_mfma_f32_16x16x32_bf16 v[54:57], v[176:179], v[212:215], v[54:57]
	v_mfma_f32_16x16x32_bf16 v[50:53], v[184:187], v[212:215], v[50:53]
	v_mfma_f32_16x16x32_bf16 v[38:41], v[176:179], v[220:223], v[38:41]
	v_mfma_f32_16x16x32_bf16 v[34:37], v[184:187], v[220:223], v[34:37]
	v_mfma_f32_16x16x32_bf16 v[22:25], v[176:179], v[228:231], v[22:25]
	v_mfma_f32_16x16x32_bf16 v[18:21], v[184:187], v[228:231], v[18:21]
	v_mfma_f32_16x16x32_bf16 v[6:9], v[176:179], v[236:239], v[6:9]
	v_mfma_f32_16x16x32_bf16 v[2:5], v[184:187], v[236:239], v[2:5]
	s_setprio 0
	s_barrier
	s_add_i32 s79, 0, 0x18000
	s_add_i32 s80, 0, 0x1c000
	v_add_u32_e32 v134, s79, v166
	v_add_u32_e32 v171, s80, v166
	ds_read_b128 v[114:117], v134
	ds_read_b128 v[118:121], v134 offset:1024
	ds_read_b128 v[130:133], v134 offset:2048
	ds_read_b128 v[134:137], v134 offset:3072
	ds_read_b128 v[172:175], v171
	ds_read_b128 v[176:179], v171 offset:1024
	ds_read_b128 v[180:183], v171 offset:2048
	ds_read_b128 v[184:187], v171 offset:3072
	s_add_u32 s42, s48, 0x2b0000
	s_addc_u32 s43, s49, 0
	s_mov_b32 m0, s56
	v_lshl_add_u64 v[242:243], s[42:43], 0, v[146:147]
	ds_read_b128 v[208:211], v170 offset:32768
	ds_read_b128 v[212:215], v170 offset:33792
	ds_read_b128 v[216:219], v170 offset:34816
	ds_read_b128 v[220:223], v170 offset:35840
	ds_read_b128 v[224:227], v170 offset:36864
	ds_read_b128 v[228:231], v170 offset:37888
	ds_read_b128 v[232:235], v170 offset:38912
	ds_read_b128 v[236:239], v170 offset:39936
	global_load_lds_dwordx4 v[242:243], off
	v_lshl_add_u64 v[242:243], s[42:43], 0, v[150:151]
	s_mov_b32 m0, s57
	s_nop 0
	global_load_lds_dwordx4 v[242:243], off
	s_waitcnt vmcnt(8)
	s_waitcnt lgkmcnt(0)
	s_barrier
	s_setprio 1
	s_waitcnt lgkmcnt(0)
	v_mfma_f32_16x16x32_bf16 v[142:145], v[114:117], v[208:211], v[142:145]
	v_mfma_f32_16x16x32_bf16 v[138:141], v[130:133], v[208:211], v[138:141]
	v_mfma_f32_16x16x32_bf16 v[110:113], v[114:117], v[216:219], v[110:113]
	v_mfma_f32_16x16x32_bf16 v[106:109], v[130:133], v[216:219], v[106:109]
	v_mfma_f32_16x16x32_bf16 v[94:97], v[114:117], v[224:227], v[94:97]
	v_mfma_f32_16x16x32_bf16 v[90:93], v[130:133], v[224:227], v[90:93]
	v_mfma_f32_16x16x32_bf16 v[78:81], v[114:117], v[232:235], v[78:81]
	v_mfma_f32_16x16x32_bf16 v[74:77], v[130:133], v[232:235], v[74:77]
	v_mfma_f32_16x16x32_bf16 v[142:145], v[118:121], v[212:215], v[142:145]
	v_mfma_f32_16x16x32_bf16 v[138:141], v[134:137], v[212:215], v[138:141]
	v_mfma_f32_16x16x32_bf16 v[110:113], v[118:121], v[220:223], v[110:113]
	v_mfma_f32_16x16x32_bf16 v[106:109], v[134:137], v[220:223], v[106:109]
	v_mfma_f32_16x16x32_bf16 v[94:97], v[118:121], v[228:231], v[94:97]
	v_mfma_f32_16x16x32_bf16 v[90:93], v[134:137], v[228:231], v[90:93]
	v_mfma_f32_16x16x32_bf16 v[78:81], v[118:121], v[236:239], v[78:81]
	v_mfma_f32_16x16x32_bf16 v[74:77], v[134:137], v[236:239], v[74:77]
	v_mfma_f32_16x16x32_bf16 v[126:129], v[172:175], v[208:211], v[126:129]
	v_mfma_f32_16x16x32_bf16 v[122:125], v[180:183], v[208:211], v[122:125]
	v_mfma_f32_16x16x32_bf16 v[102:105], v[172:175], v[216:219], v[102:105]
	v_mfma_f32_16x16x32_bf16 v[98:101], v[180:183], v[216:219], v[98:101]
	v_mfma_f32_16x16x32_bf16 v[86:89], v[172:175], v[224:227], v[86:89]
	v_mfma_f32_16x16x32_bf16 v[82:85], v[180:183], v[224:227], v[82:85]
	v_mfma_f32_16x16x32_bf16 v[70:73], v[172:175], v[232:235], v[70:73]
	v_mfma_f32_16x16x32_bf16 v[66:69], v[180:183], v[232:235], v[66:69]
	v_mfma_f32_16x16x32_bf16 v[126:129], v[176:179], v[212:215], v[126:129]
	v_mfma_f32_16x16x32_bf16 v[122:125], v[184:187], v[212:215], v[122:125]
	v_mfma_f32_16x16x32_bf16 v[102:105], v[176:179], v[220:223], v[102:105]
	v_mfma_f32_16x16x32_bf16 v[98:101], v[184:187], v[220:223], v[98:101]
	v_mfma_f32_16x16x32_bf16 v[86:89], v[176:179], v[228:231], v[86:89]
	v_mfma_f32_16x16x32_bf16 v[82:85], v[184:187], v[228:231], v[82:85]
	v_mfma_f32_16x16x32_bf16 v[70:73], v[176:179], v[236:239], v[70:73]
	v_mfma_f32_16x16x32_bf16 v[66:69], v[184:187], v[236:239], v[66:69]
	s_setprio 0
	s_barrier
; #define PG8_STAGE(bufoff, gbase, voff) do { _Pragma("unroll") for (int _i = 0; _i < 2; ++_i) \
;         __builtin_amdgcn_global_load_lds((const unsigned*)((const char*)(gbase) + (voff)[_i]), (PG8_LAS unsigned*)(lds + (bufoff) + ldsw + _i * 8192), 16, 0, 0); } while (0)
; #define PG8_LDA(dst, b, h) do { _Pragma("unroll") for (int m = 0; m < 4; ++m) _Pragma("unroll") for (int k = 0; k < 2; ++k) dst[m][k] = *(const PG8_LAS bf16x8*)(lds + PG8_SA(b, h) + aoff + m * 2048 + k * 1024); } while (0)
; #define PG8_MMA(ai, bj, At, Bt) do { __builtin_amdgcn_s_setprio(1); _Pragma("unroll") for (int m = 0; m < 4; ++m) _Pragma("unroll") for (int n = 0; n < 2; ++n) _Pragma("unroll") for (int k = 0; k < 2; ++k) \
;         acc[ai][bj][m][n] = __builtin_amdgcn_mfma_f32_16x16x32_bf16(Bt[n][k], At[m][k], acc[ai][bj][m][n], 0, 0, 0); __builtin_amdgcn_s_setprio(0); } while (0)
; #define PG8_WAIT_V(n) asm volatile("s_waitcnt vmcnt(" #n ")" ::: "memory")
; #define PG8_WAIT_L(n) asm volatile("s_waitcnt lgkmcnt(" #n ")" ::: "memory")
; #define PG8_BAR __builtin_amdgcn_s_barrier()
; #define PG8_SCHED __builtin_amdgcn_sched_barrier(0)
; template <class Epi, class Sched, bool ALIGN_EPI = false, bool SP2 = false>
; __device__ __forceinline__ void gemm_phase(PG8_LAS unsigned char* lds, const Gemm g, const Sched& S, const Epi& E) {
;     ...
;         for (int t = 0; t < nt; t += 2) {
;             const bool last = (t == nt - 2);
;             const char* a1 = cA + (size_t)(t + 1) * kstep;
;             const char* a2 = last ? nA : cA + (size_t)(t + 2) * kstep; const char* b2 = last ? nB : cB + (size_t)(t + 2) * kstepB;
;             const char* a3 = a2 + kstep; const char* b3 = b2 + kstepB;
;             if (last && has_next) S.a_ready(nxt);
;     ...
;             PG8_LDA(At, 1, 1); PG8_STAGE(PG8_SB(1, 0), b3, voffB); PG8_STAGE(PG8_SB(1, 1), b3 + hstepB, voffB); PG8_STAGE(PG8_SA(1, 0), a3, voffA);
;             PG8_WAIT_V(8); PG8_WAIT_L(0); PG8_BAR; PG8_MMA(1, 0, At, B0); PG8_MMA(1, 1, At, B1); PG8_BAR; PG8_SCHED;
	s_add_u32 s42, s46, 0x8000
	s_addc_u32 s43, s47, 0
	s_add_i32 s48, s79, s33
	v_lshl_add_u64 v[242:243], s[42:43], 0, v[148:149]
	s_mov_b32 m0, s48
	ds_read_b128 v[208:211], v170 offset:49152
	ds_read_b128 v[212:215], v170 offset:50176
	ds_read_b128 v[216:219], v170 offset:51200
	ds_read_b128 v[220:223], v170 offset:52224
	ds_read_b128 v[224:227], v170 offset:53248
	ds_read_b128 v[228:231], v170 offset:54272
	ds_read_b128 v[232:235], v170 offset:55296
	ds_read_b128 v[236:239], v170 offset:56320
	global_load_lds_dwordx4 v[242:243], off
	s_add_i32 m0, s48, 0x2000
	v_lshl_add_u64 v[242:243], s[42:43], 0, v[152:153]
	s_add_u32 s42, s46, 0xc000
	s_addc_u32 s43, s47, 0
	s_add_i32 s46, s80, s33
	global_load_lds_dwordx4 v[242:243], off
	v_lshl_add_u64 v[242:243], s[42:43], 0, v[148:149]
	s_mov_b32 m0, s46
	v_lshl_add_u64 v[164:165], v[164:165], 0, s[30:31]
	global_load_lds_dwordx4 v[242:243], off
	v_lshl_add_u64 v[242:243], s[42:43], 0, v[152:153]
	s_add_i32 m0, s46, 0x2000
	s_nop 0
	global_load_lds_dwordx4 v[242:243], off
	s_mov_b32 m0, s60
	s_nop 0
	global_load_lds_dwordx4 v[164:165], off
	v_lshl_add_u64 v[164:165], v[240:241], 0, s[30:31]
	s_mov_b32 m0, s61
	s_nop 0
	global_load_lds_dwordx4 v[164:165], off
	s_waitcnt vmcnt(8)
	s_waitcnt lgkmcnt(0)
	s_barrier
	s_setprio 1
	s_waitcnt lgkmcnt(0)
	v_mfma_f32_16x16x32_bf16 v[62:65], v[114:117], v[208:211], v[62:65]
	v_mfma_f32_16x16x32_bf16 v[58:61], v[130:133], v[208:211], v[58:61]
	v_mfma_f32_16x16x32_bf16 v[46:49], v[114:117], v[216:219], v[46:49]
	v_mfma_f32_16x16x32_bf16 v[42:45], v[130:133], v[216:219], v[42:45]
	v_mfma_f32_16x16x32_bf16 v[30:33], v[114:117], v[224:227], v[30:33]
	v_mfma_f32_16x16x32_bf16 v[26:29], v[130:133], v[224:227], v[26:29]
	v_mfma_f32_16x16x32_bf16 v[14:17], v[114:117], v[232:235], v[14:17]
	v_mfma_f32_16x16x32_bf16 v[10:13], v[130:133], v[232:235], v[10:13]
	v_mfma_f32_16x16x32_bf16 v[62:65], v[118:121], v[212:215], v[62:65]
	v_mfma_f32_16x16x32_bf16 v[58:61], v[134:137], v[212:215], v[58:61]
	v_mfma_f32_16x16x32_bf16 v[46:49], v[118:121], v[220:223], v[46:49]
	v_mfma_f32_16x16x32_bf16 v[42:45], v[134:137], v[220:223], v[42:45]
	v_mfma_f32_16x16x32_bf16 v[30:33], v[118:121], v[228:231], v[30:33]
	v_mfma_f32_16x16x32_bf16 v[26:29], v[134:137], v[228:231], v[26:29]
	v_mfma_f32_16x16x32_bf16 v[14:17], v[118:121], v[236:239], v[14:17]
	v_mfma_f32_16x16x32_bf16 v[10:13], v[134:137], v[236:239], v[10:13]
	v_mfma_f32_16x16x32_bf16 v[54:57], v[172:175], v[208:211], v[54:57]
	v_mfma_f32_16x16x32_bf16 v[50:53], v[180:183], v[208:211], v[50:53]
	v_mfma_f32_16x16x32_bf16 v[38:41], v[172:175], v[216:219], v[38:41]
	v_mfma_f32_16x16x32_bf16 v[34:37], v[180:183], v[216:219], v[34:37]
	v_mfma_f32_16x16x32_bf16 v[22:25], v[172:175], v[224:227], v[22:25]
	v_mfma_f32_16x16x32_bf16 v[18:21], v[180:183], v[224:227], v[18:21]
	v_mfma_f32_16x16x32_bf16 v[6:9], v[172:175], v[232:235], v[6:9]
	v_mfma_f32_16x16x32_bf16 v[2:5], v[180:183], v[232:235], v[2:5]
	v_mfma_f32_16x16x32_bf16 v[54:57], v[176:179], v[212:215], v[54:57]
	v_mfma_f32_16x16x32_bf16 v[50:53], v[184:187], v[212:215], v[50:53]
	v_mfma_f32_16x16x32_bf16 v[38:41], v[176:179], v[220:223], v[38:41]
	v_mfma_f32_16x16x32_bf16 v[34:37], v[184:187], v[220:223], v[34:37]
	v_mfma_f32_16x16x32_bf16 v[22:25], v[176:179], v[228:231], v[22:25]
	v_mfma_f32_16x16x32_bf16 v[18:21], v[184:187], v[228:231], v[18:21]
	v_mfma_f32_16x16x32_bf16 v[6:9], v[176:179], v[236:239], v[6:9]
	v_mfma_f32_16x16x32_bf16 v[2:5], v[184:187], v[236:239], v[2:5]
	s_setprio 0
	s_barrier
	s_add_i32 s78, s78, 2
	s_add_u32 s76, s76, 0x10000
	s_addc_u32 s77, s77, 0
	s_cmpk_gt_u32 s78, 0xa9
	s_mov_b64 s[42:43], s[44:45]
	s_cbranch_scc0 .LBB0_870
	s_and_b64 vcc, exec, s[38:39]
	s_cbranch_vccz .LBB0_873
	s_barrier

; #define PG8_STAGE(bufoff, gbase, voff) do { _Pragma("unroll") for (int _i = 0; _i < 2; ++_i) \
;         __builtin_amdgcn_global_load_lds((const unsigned*)((const char*)(gbase) + (voff)[_i]), (PG8_LAS unsigned*)(lds + (bufoff) + ldsw + _i * 8192), 16, 0, 0); } while (0)
; #define PG8_LDA(dst, b, h) do { _Pragma("unroll") for (int m = 0; m < 4; ++m) _Pragma("unroll") for (int k = 0; k < 2; ++k) dst[m][k] = *(const PG8_LAS bf16x8*)(lds + PG8_SA(b, h) + aoff + m * 2048 + k * 1024); } while (0)
; #define PG8_LDB(dst, b, h) do { _Pragma("unroll") for (int n = 0; n < 2; ++n) _Pragma("unroll") for (int k = 0; k < 2; ++k) dst[n][k] = *(const PG8_LAS bf16x8*)(lds + PG8_SB(b, h) + boff + n * 2048 + k * 1024); } while (0)
; #define PG8_MMA(ai, bj, At, Bt) do { __builtin_amdgcn_s_setprio(1); _Pragma("unroll") for (int m = 0; m < 4; ++m) _Pragma("unroll") for (int n = 0; n < 2; ++n) _Pragma("unroll") for (int k = 0; k < 2; ++k) \
;         acc[ai][bj][m][n] = __builtin_amdgcn_mfma_f32_16x16x32_bf16(Bt[n][k], At[m][k], acc[ai][bj][m][n], 0, 0, 0); __builtin_amdgcn_s_setprio(0); } while (0)
; #define PG8_WAIT_V(n) asm volatile("s_waitcnt vmcnt(" #n ")" ::: "memory")
; #define PG8_BAR __builtin_amdgcn_s_barrier()
; template <class Epi, class Sched, bool ALIGN_EPI = false, bool SP2 = false>
; __device__ __forceinline__ void gemm_phase(PG8_LAS unsigned char* lds, const Gemm g, const Sched& S, const Epi& E) {
;     ...
;         for (int t = 0; t < nt; t += 2) {
;             const bool last = (t == nt - 2);
;             const char* a1 = cA + (size_t)(t + 1) * kstep;
;             const char* a2 = last ? nA : cA + (size_t)(t + 2) * kstep; const char* b2 = last ? nB : cB + (size_t)(t + 2) * kstepB;
;             const char* a3 = a2 + kstep; const char* b3 = b2 + kstepB;
;             if (last && has_next) S.a_ready(nxt);
;             if constexpr (SP2) {
;             PG8_LDB(B0, 0, 0); PG8_LDB(B1, 0, 1); PG8_SCHED; PG8_LDA(At, 0, 0); PG8_STAGE(PG8_SA(1, 1), a1 + hstepA, voffA);
;             PG8_WAIT_V(8); PG8_WAIT_L(0); PG8_BAR; PG8_MMA(0, 0, At, B0); PG8_MMA(0, 1, At, B1); PG8_BAR; PG8_SCHED;
;             PG8_LDA(At, 0, 1); PG8_STAGE(PG8_SB(0, 0), b2, voffB); PG8_STAGE(PG8_SB(0, 1), b2 + hstepB, voffB); PG8_STAGE(PG8_SA(0, 0), a2, voffA);
;             PG8_WAIT_V(8); PG8_WAIT_L(0); PG8_BAR; PG8_MMA(1, 0, At, B0); PG8_MMA(1, 1, At, B1); PG8_BAR; PG8_SCHED;
.LBB0_906:
	s_add_i32 s4, s54, 2
	s_lshl_b64 s[56:57], s[4:5], 7
	s_add_u32 s55, s48, s56
	s_addc_u32 s58, s49, s57
	s_and_b64 s[56:57], s[52:53], exec
	s_cselect_b32 s59, s39, s58
	s_cselect_b32 s58, s88, s55
	s_lshl_b64 s[56:57], s[4:5], 15
	s_add_u32 s4, s42, s56
	s_addc_u32 s55, s43, s57
	s_and_b64 s[52:53], s[52:53], exec
	s_cselect_b32 s61, s31, s55
	s_cselect_b32 s60, s89, s4
	s_lshl_b32 s4, s54, 7
	s_add_u32 s4, s48, s4
	s_addc_u32 s52, s49, 0
	s_add_u32 s64, s4, 0x10080
	s_addc_u32 s65, s52, 0
	s_add_i32 vcc_lo, s84, s33
	s_add_i32 m0, s41, 0xc000
	s_add_i32 vcc_hi, s41, 0xe000
	s_add_i32 s95, vcc_lo, 0x2000
	ds_read_b128 v[148:151], v144
	ds_read_b128 v[152:155], v144 offset:1024
	ds_read_b128 v[156:159], v144 offset:2048
	ds_read_b128 v[160:163], v144 offset:3072
	ds_read_b128 v[164:167], v145
	ds_read_b128 v[168:171], v145 offset:1024
	ds_read_b128 v[172:175], v145 offset:2048
	ds_read_b128 v[176:179], v145 offset:3072
	s_add_u32 s62, s60, 0x4000
	s_addc_u32 s63, s61, 0
	s_add_i32 s97, s85, s33
	s_add_i32 s96, s97, 0x2000
	s_add_i32 s94, 0, 0x18000
	s_add_i32 s93, 0, 0x1c000
	s_add_u32 s56, s58, 0x10000
	s_addc_u32 s57, s59, 0
	s_add_u32 s52, s60, 0x8000
	s_addc_u32 s53, s61, 0
	s_add_i32 s92, s94, s33
	s_add_i32 s90, s92, 0x2000
	s_add_u32 s54, s60, 0xc000
	s_addc_u32 s55, s61, 0
	s_add_i32 s91, s93, s33
	s_add_i32 s4, s91, 0x2000
	v_lshl_add_u64 v[232:233], s[64:65], 0, v[136:137]
	ds_read_b128 v[180:183], v146
	ds_read_b128 v[184:187], v146 offset:1024
	ds_read_b128 v[208:211], v146 offset:2048
	ds_read_b128 v[212:215], v146 offset:3072
	ds_read_b128 v[216:219], v146 offset:4096
	ds_read_b128 v[220:223], v146 offset:5120
	ds_read_b128 v[224:227], v146 offset:6144
	ds_read_b128 v[228:231], v146 offset:7168
	global_load_lds_dwordx4 v[232:233], off
	v_lshl_add_u64 v[232:233], s[64:65], 0, v[132:133]
	s_mov_b32 m0, vcc_hi
	s_nop 0
	global_load_lds_dwordx4 v[232:233], off
	s_waitcnt vmcnt(8)
	s_waitcnt lgkmcnt(0)
	s_barrier
	s_setprio 1
	s_waitcnt lgkmcnt(0)
	v_mfma_f32_16x16x32_bf16 v[126:129], v[148:151], v[180:183], v[126:129]
	v_mfma_f32_16x16x32_bf16 v[122:125], v[156:159], v[180:183], v[122:125]
	v_mfma_f32_16x16x32_bf16 v[118:121], v[148:151], v[208:211], v[118:121]
	v_mfma_f32_16x16x32_bf16 v[114:117], v[156:159], v[208:211], v[114:117]
	v_mfma_f32_16x16x32_bf16 v[102:105], v[148:151], v[216:219], v[102:105]
	v_mfma_f32_16x16x32_bf16 v[98:101], v[156:159], v[216:219], v[98:101]
	v_mfma_f32_16x16x32_bf16 v[86:89], v[148:151], v[224:227], v[86:89]
	v_mfma_f32_16x16x32_bf16 v[82:85], v[156:159], v[224:227], v[82:85]
	v_mfma_f32_16x16x32_bf16 v[126:129], v[152:155], v[184:187], v[126:129]
	v_mfma_f32_16x16x32_bf16 v[122:125], v[160:163], v[184:187], v[122:125]
	v_mfma_f32_16x16x32_bf16 v[118:121], v[152:155], v[212:215], v[118:121]
	v_mfma_f32_16x16x32_bf16 v[114:117], v[160:163], v[212:215], v[114:117]
	v_mfma_f32_16x16x32_bf16 v[102:105], v[152:155], v[220:223], v[102:105]
	v_mfma_f32_16x16x32_bf16 v[98:101], v[160:163], v[220:223], v[98:101]
	v_mfma_f32_16x16x32_bf16 v[86:89], v[152:155], v[228:231], v[86:89]
	v_mfma_f32_16x16x32_bf16 v[82:85], v[160:163], v[228:231], v[82:85]
	v_mfma_f32_16x16x32_bf16 v[110:113], v[164:167], v[180:183], v[110:113]
	v_mfma_f32_16x16x32_bf16 v[106:109], v[172:175], v[180:183], v[106:109]
	v_mfma_f32_16x16x32_bf16 v[94:97], v[164:167], v[208:211], v[94:97]
	v_mfma_f32_16x16x32_bf16 v[90:93], v[172:175], v[208:211], v[90:93]
	v_mfma_f32_16x16x32_bf16 v[78:81], v[164:167], v[216:219], v[78:81]
	v_mfma_f32_16x16x32_bf16 v[74:77], v[172:175], v[216:219], v[74:77]
	v_mfma_f32_16x16x32_bf16 v[70:73], v[164:167], v[224:227], v[70:73]
	v_mfma_f32_16x16x32_bf16 v[66:69], v[172:175], v[224:227], v[66:69]
	v_mfma_f32_16x16x32_bf16 v[110:113], v[168:171], v[184:187], v[110:113]
	v_mfma_f32_16x16x32_bf16 v[106:109], v[176:179], v[184:187], v[106:109]
	v_mfma_f32_16x16x32_bf16 v[94:97], v[168:171], v[212:215], v[94:97]
	v_mfma_f32_16x16x32_bf16 v[90:93], v[176:179], v[212:215], v[90:93]
	v_mfma_f32_16x16x32_bf16 v[78:81], v[168:171], v[220:223], v[78:81]
	v_mfma_f32_16x16x32_bf16 v[74:77], v[176:179], v[220:223], v[74:77]
	v_mfma_f32_16x16x32_bf16 v[70:73], v[168:171], v[228:231], v[70:73]
	v_mfma_f32_16x16x32_bf16 v[66:69], v[176:179], v[228:231], v[66:69]
	s_setprio 0
	s_barrier
	s_mov_b32 m0, vcc_lo
	v_lshl_add_u64 v[232:233], s[60:61], 0, v[134:135]
	ds_read_b128 v[180:183], v146 offset:16384
	ds_read_b128 v[184:187], v146 offset:17408
	ds_read_b128 v[208:211], v146 offset:18432
	ds_read_b128 v[212:215], v146 offset:19456
	ds_read_b128 v[216:219], v146 offset:20480
	ds_read_b128 v[220:223], v146 offset:21504
	ds_read_b128 v[224:227], v146 offset:22528
	ds_read_b128 v[228:231], v146 offset:23552
	global_load_lds_dwordx4 v[232:233], off
	v_lshl_add_u64 v[232:233], s[60:61], 0, v[130:131]
	s_mov_b32 m0, s95
	v_lshl_add_u64 v[234:235], s[58:59], 0, v[132:133]
	global_load_lds_dwordx4 v[232:233], off
	v_lshl_add_u64 v[232:233], s[62:63], 0, v[134:135]
	s_mov_b32 m0, s97
	s_nop 0
	global_load_lds_dwordx4 v[232:233], off
	v_lshl_add_u64 v[232:233], s[62:63], 0, v[130:131]
	s_mov_b32 m0, s96
	s_nop 0
	global_load_lds_dwordx4 v[232:233], off
	v_lshl_add_u64 v[232:233], s[58:59], 0, v[136:137]
	s_mov_b32 m0, s41
	s_nop 0
	global_load_lds_dwordx4 v[232:233], off
	s_mov_b32 m0, s78
	s_nop 0
	global_load_lds_dwordx4 v[234:235], off
	s_waitcnt vmcnt(8)
	s_waitcnt lgkmcnt(0)
	s_barrier
; #define PG8_STAGE(bufoff, gbase, voff) do { _Pragma("unroll") for (int _i = 0; _i < 2; ++_i) \
;         __builtin_amdgcn_global_load_lds((const unsigned*)((const char*)(gbase) + (voff)[_i]), (PG8_LAS unsigned*)(lds + (bufoff) + ldsw + _i * 8192), 16, 0, 0); } while (0)
; #define PG8_LDA(dst, b, h) do { _Pragma("unroll") for (int m = 0; m < 4; ++m) _Pragma("unroll") for (int k = 0; k < 2; ++k) dst[m][k] = *(const PG8_LAS bf16x8*)(lds + PG8_SA(b, h) + aoff + m * 2048 + k * 1024); } while (0)
; #define PG8_LDB(dst, b, h) do { _Pragma("unroll") for (int n = 0; n < 2; ++n) _Pragma("unroll") for (int k = 0; k < 2; ++k) dst[n][k] = *(const PG8_LAS bf16x8*)(lds + PG8_SB(b, h) + boff + n * 2048 + k * 1024); } while (0)
; #define PG8_MMA(ai, bj, At, Bt) do { __builtin_amdgcn_s_setprio(1); _Pragma("unroll") for (int m = 0; m < 4; ++m) _Pragma("unroll") for (int n = 0; n < 2; ++n) _Pragma("unroll") for (int k = 0; k < 2; ++k) \
;         acc[ai][bj][m][n] = __builtin_amdgcn_mfma_f32_16x16x32_bf16(Bt[n][k], At[m][k], acc[ai][bj][m][n], 0, 0, 0); __builtin_amdgcn_s_setprio(0); } while (0)
; #define PG8_WAIT_V(n) asm volatile("s_waitcnt vmcnt(" #n ")" ::: "memory")
; #define PG8_WAIT_L(n) asm volatile("s_waitcnt lgkmcnt(" #n ")" ::: "memory")
; #define PG8_BAR __builtin_amdgcn_s_barrier()
; #define PG8_SCHED __builtin_amdgcn_sched_barrier(0)
; template <class Epi, class Sched, bool ALIGN_EPI = false, bool SP2 = false>
; __device__ __forceinline__ void gemm_phase(PG8_LAS unsigned char* lds, const Gemm g, const Sched& S, const Epi& E) {
;     ...
;             PG8_WAIT_V(8); PG8_WAIT_L(0); PG8_BAR; PG8_MMA(1, 0, At, B0); PG8_MMA(1, 1, At, B1); PG8_BAR; PG8_SCHED;
;             PG8_LDB(B0, 1, 0); PG8_LDB(B1, 1, 1); PG8_SCHED; PG8_LDA(At, 1, 0); PG8_STAGE(PG8_SA(0, 1), a2 + hstepA, voffA);
;             PG8_WAIT_V(8); PG8_WAIT_L(0); PG8_BAR; PG8_MMA(0, 0, At, B0); PG8_MMA(0, 1, At, B1); PG8_BAR; PG8_SCHED;
;             PG8_LDA(At, 1, 1); PG8_STAGE(PG8_SB(1, 0), b3, voffB); PG8_STAGE(PG8_SB(1, 1), b3 + hstepB, voffB); PG8_STAGE(PG8_SA(1, 0), a3, voffA);
	s_setprio 1
	s_waitcnt lgkmcnt(0)
	v_mfma_f32_16x16x32_bf16 v[62:65], v[148:151], v[180:183], v[62:65]
	v_mfma_f32_16x16x32_bf16 v[58:61], v[156:159], v[180:183], v[58:61]
	v_mfma_f32_16x16x32_bf16 v[54:57], v[148:151], v[208:211], v[54:57]
	v_mfma_f32_16x16x32_bf16 v[50:53], v[156:159], v[208:211], v[50:53]
	v_mfma_f32_16x16x32_bf16 v[38:41], v[148:151], v[216:219], v[38:41]
	v_mfma_f32_16x16x32_bf16 v[34:37], v[156:159], v[216:219], v[34:37]
	v_mfma_f32_16x16x32_bf16 v[22:25], v[148:151], v[224:227], v[22:25]
	v_mfma_f32_16x16x32_bf16 v[18:21], v[156:159], v[224:227], v[18:21]
	v_mfma_f32_16x16x32_bf16 v[62:65], v[152:155], v[184:187], v[62:65]
	v_mfma_f32_16x16x32_bf16 v[58:61], v[160:163], v[184:187], v[58:61]
	v_mfma_f32_16x16x32_bf16 v[54:57], v[152:155], v[212:215], v[54:57]
	v_mfma_f32_16x16x32_bf16 v[50:53], v[160:163], v[212:215], v[50:53]
	v_mfma_f32_16x16x32_bf16 v[38:41], v[152:155], v[220:223], v[38:41]
	v_mfma_f32_16x16x32_bf16 v[34:37], v[160:163], v[220:223], v[34:37]
	v_mfma_f32_16x16x32_bf16 v[22:25], v[152:155], v[228:231], v[22:25]
	v_mfma_f32_16x16x32_bf16 v[18:21], v[160:163], v[228:231], v[18:21]
	v_mfma_f32_16x16x32_bf16 v[46:49], v[164:167], v[180:183], v[46:49]
	v_mfma_f32_16x16x32_bf16 v[42:45], v[172:175], v[180:183], v[42:45]
	v_mfma_f32_16x16x32_bf16 v[30:33], v[164:167], v[208:211], v[30:33]
	v_mfma_f32_16x16x32_bf16 v[26:29], v[172:175], v[208:211], v[26:29]
	v_mfma_f32_16x16x32_bf16 v[14:17], v[164:167], v[216:219], v[14:17]
	v_mfma_f32_16x16x32_bf16 v[10:13], v[172:175], v[216:219], v[10:13]
	v_mfma_f32_16x16x32_bf16 v[6:9], v[164:167], v[224:227], v[6:9]
	v_mfma_f32_16x16x32_bf16 v[2:5], v[172:175], v[224:227], v[2:5]
	v_mfma_f32_16x16x32_bf16 v[46:49], v[168:171], v[184:187], v[46:49]
	v_mfma_f32_16x16x32_bf16 v[42:45], v[176:179], v[184:187], v[42:45]
	v_mfma_f32_16x16x32_bf16 v[30:33], v[168:171], v[212:215], v[30:33]
	v_mfma_f32_16x16x32_bf16 v[26:29], v[176:179], v[212:215], v[26:29]
	v_mfma_f32_16x16x32_bf16 v[14:17], v[168:171], v[220:223], v[14:17]
	v_mfma_f32_16x16x32_bf16 v[10:13], v[176:179], v[220:223], v[10:13]
	v_mfma_f32_16x16x32_bf16 v[6:9], v[168:171], v[228:231], v[6:9]
	v_mfma_f32_16x16x32_bf16 v[2:5], v[176:179], v[228:231], v[2:5]
	s_setprio 0
	s_barrier
	v_add_u32_e32 v147, s94, v1
	ds_read_b128 v[148:151], v147
	ds_read_b128 v[152:155], v147 offset:1024
	ds_read_b128 v[156:159], v147 offset:2048
	ds_read_b128 v[160:163], v147 offset:3072
	v_add_u32_e32 v147, s93, v1
	ds_read_b128 v[164:167], v147
	ds_read_b128 v[168:171], v147 offset:1024
	ds_read_b128 v[172:175], v147 offset:2048
	ds_read_b128 v[176:179], v147 offset:3072
	s_mov_b32 m0, s79
	v_lshl_add_u64 v[236:237], s[56:57], 0, v[136:137]
	ds_read_b128 v[180:183], v146 offset:32768
	ds_read_b128 v[184:187], v146 offset:33792
	ds_read_b128 v[208:211], v146 offset:34816
	ds_read_b128 v[212:215], v146 offset:35840
	ds_read_b128 v[216:219], v146 offset:36864
	ds_read_b128 v[220:223], v146 offset:37888
	ds_read_b128 v[224:227], v146 offset:38912
	ds_read_b128 v[228:231], v146 offset:39936
	global_load_lds_dwordx4 v[236:237], off
	v_lshl_add_u64 v[236:237], s[56:57], 0, v[132:133]
	s_mov_b32 m0, s80
	s_nop 0
	global_load_lds_dwordx4 v[236:237], off
	s_waitcnt vmcnt(8)
	s_waitcnt lgkmcnt(0)
	s_barrier
	s_setprio 1
	s_waitcnt lgkmcnt(0)
	v_mfma_f32_16x16x32_bf16 v[126:129], v[148:151], v[180:183], v[126:129]
	v_mfma_f32_16x16x32_bf16 v[122:125], v[156:159], v[180:183], v[122:125]
	v_mfma_f32_16x16x32_bf16 v[118:121], v[148:151], v[208:211], v[118:121]
	v_mfma_f32_16x16x32_bf16 v[114:117], v[156:159], v[208:211], v[114:117]
	v_mfma_f32_16x16x32_bf16 v[102:105], v[148:151], v[216:219], v[102:105]
	v_mfma_f32_16x16x32_bf16 v[98:101], v[156:159], v[216:219], v[98:101]
	v_mfma_f32_16x16x32_bf16 v[86:89], v[148:151], v[224:227], v[86:89]
	v_mfma_f32_16x16x32_bf16 v[82:85], v[156:159], v[224:227], v[82:85]
	v_mfma_f32_16x16x32_bf16 v[126:129], v[152:155], v[184:187], v[126:129]
	v_mfma_f32_16x16x32_bf16 v[122:125], v[160:163], v[184:187], v[122:125]
	v_mfma_f32_16x16x32_bf16 v[118:121], v[152:155], v[212:215], v[118:121]
	v_mfma_f32_16x16x32_bf16 v[114:117], v[160:163], v[212:215], v[114:117]
	v_mfma_f32_16x16x32_bf16 v[102:105], v[152:155], v[220:223], v[102:105]
	v_mfma_f32_16x16x32_bf16 v[98:101], v[160:163], v[220:223], v[98:101]
	v_mfma_f32_16x16x32_bf16 v[86:89], v[152:155], v[228:231], v[86:89]
	v_mfma_f32_16x16x32_bf16 v[82:85], v[160:163], v[228:231], v[82:85]
	v_mfma_f32_16x16x32_bf16 v[110:113], v[164:167], v[180:183], v[110:113]
	v_mfma_f32_16x16x32_bf16 v[106:109], v[172:175], v[180:183], v[106:109]
	v_mfma_f32_16x16x32_bf16 v[94:97], v[164:167], v[208:211], v[94:97]
	v_mfma_f32_16x16x32_bf16 v[90:93], v[172:175], v[208:211], v[90:93]
	v_mfma_f32_16x16x32_bf16 v[78:81], v[164:167], v[216:219], v[78:81]
	v_mfma_f32_16x16x32_bf16 v[74:77], v[172:175], v[216:219], v[74:77]
	v_mfma_f32_16x16x32_bf16 v[70:73], v[164:167], v[224:227], v[70:73]
	v_mfma_f32_16x16x32_bf16 v[66:69], v[172:175], v[224:227], v[66:69]
	v_mfma_f32_16x16x32_bf16 v[110:113], v[168:171], v[184:187], v[110:113]
	v_mfma_f32_16x16x32_bf16 v[106:109], v[176:179], v[184:187], v[106:109]
	v_mfma_f32_16x16x32_bf16 v[94:97], v[168:171], v[212:215], v[94:97]
	v_mfma_f32_16x16x32_bf16 v[90:93], v[176:179], v[212:215], v[90:93]
	v_mfma_f32_16x16x32_bf16 v[78:81], v[168:171], v[220:223], v[78:81]
	v_mfma_f32_16x16x32_bf16 v[74:77], v[176:179], v[220:223], v[74:77]
	v_mfma_f32_16x16x32_bf16 v[70:73], v[168:171], v[228:231], v[70:73]
	v_mfma_f32_16x16x32_bf16 v[66:69], v[176:179], v[228:231], v[66:69]
	s_setprio 0
	s_barrier
; #define PG8_STAGE(bufoff, gbase, voff) do { _Pragma("unroll") for (int _i = 0; _i < 2; ++_i) \
;         __builtin_amdgcn_global_load_lds((const unsigned*)((const char*)(gbase) + (voff)[_i]), (PG8_LAS unsigned*)(lds + (bufoff) + ldsw + _i * 8192), 16, 0, 0); } while (0)
; #define PG8_LDA(dst, b, h) do { _Pragma("unroll") for (int m = 0; m < 4; ++m) _Pragma("unroll") for (int k = 0; k < 2; ++k) dst[m][k] = *(const PG8_LAS bf16x8*)(lds + PG8_SA(b, h) + aoff + m * 2048 + k * 1024); } while (0)
; #define PG8_MMA(ai, bj, At, Bt) do { __builtin_amdgcn_s_setprio(1); _Pragma("unroll") for (int m = 0; m < 4; ++m) _Pragma("unroll") for (int n = 0; n < 2; ++n) _Pragma("unroll") for (int k = 0; k < 2; ++k) \
;         acc[ai][bj][m][n] = __builtin_amdgcn_mfma_f32_16x16x32_bf16(Bt[n][k], At[m][k], acc[ai][bj][m][n], 0, 0, 0); __builtin_amdgcn_s_setprio(0); } while (0)
; #define PG8_WAIT_V(n) asm volatile("s_waitcnt vmcnt(" #n ")" ::: "memory")
; #define PG8_WAIT_L(n) asm volatile("s_waitcnt lgkmcnt(" #n ")" ::: "memory")
; #define PG8_BAR __builtin_amdgcn_s_barrier()
; #define PG8_SCHED __builtin_amdgcn_sched_barrier(0)
; template <class Epi, class Sched, bool ALIGN_EPI = false, bool SP2 = false>
; __device__ __forceinline__ void gemm_phase(PG8_LAS unsigned char* lds, const Gemm g, const Sched& S, const Epi& E) {
;     ...
;         for (int t = 0; t < nt; t += 2) {
;             const bool last = (t == nt - 2);
;             const char* a1 = cA + (size_t)(t + 1) * kstep;
;             const char* a2 = last ? nA : cA + (size_t)(t + 2) * kstep; const char* b2 = last ? nB : cB + (size_t)(t + 2) * kstepB;
;             const char* a3 = a2 + kstep; const char* b3 = b2 + kstepB;
;             if (last && has_next) S.a_ready(nxt);
;     ...
;             PG8_LDA(At, 1, 1); PG8_STAGE(PG8_SB(1, 0), b3, voffB); PG8_STAGE(PG8_SB(1, 1), b3 + hstepB, voffB); PG8_STAGE(PG8_SA(1, 0), a3, voffA);
;             PG8_WAIT_V(8); PG8_WAIT_L(0); PG8_BAR; PG8_MMA(1, 0, At, B0); PG8_MMA(1, 1, At, B1); PG8_BAR; PG8_SCHED;
	s_mov_b32 m0, s92
	v_lshl_add_u64 v[236:237], s[52:53], 0, v[134:135]
	ds_read_b128 v[180:183], v146 offset:49152
	ds_read_b128 v[184:187], v146 offset:50176
	ds_read_b128 v[208:211], v146 offset:51200
	ds_read_b128 v[212:215], v146 offset:52224
	ds_read_b128 v[216:219], v146 offset:53248
	ds_read_b128 v[220:223], v146 offset:54272
	ds_read_b128 v[224:227], v146 offset:55296
	ds_read_b128 v[228:231], v146 offset:56320
	global_load_lds_dwordx4 v[236:237], off
	v_lshl_add_u64 v[236:237], s[52:53], 0, v[130:131]
	s_mov_b32 m0, s90
	v_lshl_add_u64 v[232:233], v[232:233], 0, s[18:19]
	global_load_lds_dwordx4 v[236:237], off
	v_lshl_add_u64 v[236:237], s[54:55], 0, v[134:135]
	s_mov_b32 m0, s91
	s_nop 0
	global_load_lds_dwordx4 v[236:237], off
	v_lshl_add_u64 v[236:237], s[54:55], 0, v[130:131]
	s_mov_b32 m0, s4
	s_nop 0
	global_load_lds_dwordx4 v[236:237], off
	s_mov_b32 m0, s81
	s_nop 0
	global_load_lds_dwordx4 v[232:233], off
	v_lshl_add_u64 v[232:233], v[234:235], 0, s[18:19]
	s_mov_b32 m0, s82
	s_nop 0
	global_load_lds_dwordx4 v[232:233], off
	s_waitcnt vmcnt(8)
	s_waitcnt lgkmcnt(0)
	s_barrier
	s_setprio 1
	s_waitcnt lgkmcnt(0)
	v_mfma_f32_16x16x32_bf16 v[62:65], v[148:151], v[180:183], v[62:65]
	v_mfma_f32_16x16x32_bf16 v[58:61], v[156:159], v[180:183], v[58:61]
	v_mfma_f32_16x16x32_bf16 v[54:57], v[148:151], v[208:211], v[54:57]
	v_mfma_f32_16x16x32_bf16 v[50:53], v[156:159], v[208:211], v[50:53]
	v_mfma_f32_16x16x32_bf16 v[38:41], v[148:151], v[216:219], v[38:41]
	v_mfma_f32_16x16x32_bf16 v[34:37], v[156:159], v[216:219], v[34:37]
	v_mfma_f32_16x16x32_bf16 v[22:25], v[148:151], v[224:227], v[22:25]
	v_mfma_f32_16x16x32_bf16 v[18:21], v[156:159], v[224:227], v[18:21]
	v_mfma_f32_16x16x32_bf16 v[62:65], v[152:155], v[184:187], v[62:65]
	v_mfma_f32_16x16x32_bf16 v[58:61], v[160:163], v[184:187], v[58:61]
	v_mfma_f32_16x16x32_bf16 v[54:57], v[152:155], v[212:215], v[54:57]
	v_mfma_f32_16x16x32_bf16 v[50:53], v[160:163], v[212:215], v[50:53]
	v_mfma_f32_16x16x32_bf16 v[38:41], v[152:155], v[220:223], v[38:41]
	v_mfma_f32_16x16x32_bf16 v[34:37], v[160:163], v[220:223], v[34:37]
	v_mfma_f32_16x16x32_bf16 v[22:25], v[152:155], v[228:231], v[22:25]
	v_mfma_f32_16x16x32_bf16 v[18:21], v[160:163], v[228:231], v[18:21]
	v_mfma_f32_16x16x32_bf16 v[46:49], v[164:167], v[180:183], v[46:49]
	v_mfma_f32_16x16x32_bf16 v[42:45], v[172:175], v[180:183], v[42:45]
	v_mfma_f32_16x16x32_bf16 v[30:33], v[164:167], v[208:211], v[30:33]
	v_mfma_f32_16x16x32_bf16 v[26:29], v[172:175], v[208:211], v[26:29]
	v_mfma_f32_16x16x32_bf16 v[14:17], v[164:167], v[216:219], v[14:17]
	v_mfma_f32_16x16x32_bf16 v[10:13], v[172:175], v[216:219], v[10:13]
	v_mfma_f32_16x16x32_bf16 v[6:9], v[164:167], v[224:227], v[6:9]
	v_mfma_f32_16x16x32_bf16 v[2:5], v[172:175], v[224:227], v[2:5]
	v_mfma_f32_16x16x32_bf16 v[46:49], v[168:171], v[184:187], v[46:49]
	v_mfma_f32_16x16x32_bf16 v[42:45], v[176:179], v[184:187], v[42:45]
	v_mfma_f32_16x16x32_bf16 v[30:33], v[168:171], v[212:215], v[30:33]
	v_mfma_f32_16x16x32_bf16 v[26:29], v[176:179], v[212:215], v[26:29]
	v_mfma_f32_16x16x32_bf16 v[14:17], v[168:171], v[220:223], v[14:17]
	v_mfma_f32_16x16x32_bf16 v[10:13], v[176:179], v[220:223], v[10:13]
	v_mfma_f32_16x16x32_bf16 v[6:9], v[168:171], v[228:231], v[6:9]
	v_mfma_f32_16x16x32_bf16 v[2:5], v[176:179], v[228:231], v[2:5]
	s_setprio 0
	s_barrier
	s_andn2_b64 vcc, exec, s[50:51]
	s_mov_b64 s[52:53], -1
	s_mov_b64 s[50:51], 0
	s_mov_b32 s54, 2
	s_cbranch_vccz .LBB0_906
	s_and_b64 vcc, exec, s[26:27]
	s_cbranch_vccz .LBB0_909
	s_barrier

; #define PG8_STAGE(bufoff, gbase, voff) do { _Pragma("unroll") for (int _i = 0; _i < 2; ++_i) \
;         __builtin_amdgcn_global_load_lds((const unsigned*)((const char*)(gbase) + (voff)[_i]), (PG8_LAS unsigned*)(lds + (bufoff) + ldsw + _i * 8192), 16, 0, 0); } while (0)
; #define PG8_LDA(dst, b, h) do { _Pragma("unroll") for (int m = 0; m < 4; ++m) _Pragma("unroll") for (int k = 0; k < 2; ++k) dst[m][k] = *(const PG8_LAS bf16x8*)(lds + PG8_SA(b, h) + aoff + m * 2048 + k * 1024); } while (0)
; #define PG8_LDB(dst, b, h) do { _Pragma("unroll") for (int n = 0; n < 2; ++n) _Pragma("unroll") for (int k = 0; k < 2; ++k) dst[n][k] = *(const PG8_LAS bf16x8*)(lds + PG8_SB(b, h) + boff + n * 2048 + k * 1024); } while (0)
; #define PG8_MMA(ai, bj, At, Bt) do { __builtin_amdgcn_s_setprio(1); _Pragma("unroll") for (int m = 0; m < 4; ++m) _Pragma("unroll") for (int n = 0; n < 2; ++n) _Pragma("unroll") for (int k = 0; k < 2; ++k) \
;         acc[ai][bj][m][n] = __builtin_amdgcn_mfma_f32_16x16x32_bf16(Bt[n][k], At[m][k], acc[ai][bj][m][n], 0, 0, 0); __builtin_amdgcn_s_setprio(0); } while (0)
; #define PG8_WAIT_V(n) asm volatile("s_waitcnt vmcnt(" #n ")" ::: "memory")
; #define PG8_BAR __builtin_amdgcn_s_barrier()
; template <class Epi, class Sched, bool ALIGN_EPI = false, bool SP2 = false>
; __device__ __forceinline__ void gemm_phase(PG8_LAS unsigned char* lds, const Gemm g, const Sched& S, const Epi& E) {
;     ...
;         for (int t = 0; t < nt; t += 2) {
;             const bool last = (t == nt - 2);
;             const char* a1 = cA + (size_t)(t + 1) * kstep;
;             const char* a2 = last ? nA : cA + (size_t)(t + 2) * kstep; const char* b2 = last ? nB : cB + (size_t)(t + 2) * kstepB;
;             const char* a3 = a2 + kstep; const char* b3 = b2 + kstepB;
;             if (last && has_next) S.a_ready(nxt);
;             if constexpr (SP2) {
;             PG8_LDB(B0, 0, 0); PG8_LDB(B1, 0, 1); PG8_SCHED; PG8_LDA(At, 0, 0); PG8_STAGE(PG8_SA(1, 1), a1 + hstepA, voffA);
;             PG8_WAIT_V(8); PG8_WAIT_L(0); PG8_BAR; PG8_MMA(0, 0, At, B0); PG8_MMA(0, 1, At, B1); PG8_BAR; PG8_SCHED;
;             PG8_LDA(At, 0, 1); PG8_STAGE(PG8_SB(0, 0), b2, voffB); PG8_STAGE(PG8_SB(0, 1), b2 + hstepB, voffB); PG8_STAGE(PG8_SA(0, 0), a2, voffA);
;             PG8_WAIT_V(8); PG8_WAIT_L(0); PG8_BAR; PG8_MMA(1, 0, At, B0); PG8_MMA(1, 1, At, B1); PG8_BAR; PG8_SCHED;
.LBB0_964:
	ds_read_b128 v[68:71], v210
	ds_read_b128 v[72:75], v210 offset:1024
	ds_read_b128 v[136:139], v210 offset:2048
	ds_read_b128 v[140:143], v210 offset:3072
	ds_read_b128 v[144:147], v211
	ds_read_b128 v[148:151], v211 offset:1024
	ds_read_b128 v[152:155], v211 offset:2048
	ds_read_b128 v[156:159], v211 offset:3072
	s_add_u32 s50, s48, 0xfff00080
	s_addc_u32 s51, s49, -1
	s_cmp_eq_u32 s74, 60
	s_cselect_b32 s53, s33, s51
	s_cselect_b32 s52, s35, s50
	s_cselect_b32 s51, s31, s73
	s_cselect_b32 s50, s47, s72
	v_lshl_add_u64 v[186:187], s[48:49], 0, v[170:171]
	s_add_i32 m0, s55, 0xc000
	ds_read_b128 v[178:181], v212
	ds_read_b128 v[182:185], v212 offset:1024
	ds_read_b128 v[214:217], v212 offset:2048
	ds_read_b128 v[218:221], v212 offset:3072
	ds_read_b128 v[222:225], v212 offset:4096
	ds_read_b128 v[226:229], v212 offset:5120
	ds_read_b128 v[230:233], v212 offset:6144
	ds_read_b128 v[234:237], v212 offset:7168
	global_load_lds_dwordx4 v[186:187], off
	v_lshl_add_u64 v[186:187], s[48:49], 0, v[172:173]
	s_add_i32 m0, s55, 0xe000
	s_nop 0
	global_load_lds_dwordx4 v[186:187], off
	s_waitcnt vmcnt(8)
	s_waitcnt lgkmcnt(0)
	s_barrier
	s_setprio 1
	s_waitcnt lgkmcnt(0)
	v_mfma_f32_16x16x32_bf16 v[60:63], v[68:71], v[178:181], v[60:63]
	v_mfma_f32_16x16x32_bf16 v[56:59], v[136:139], v[178:181], v[56:59]
	v_mfma_f32_16x16x32_bf16 v[124:127], v[68:71], v[214:217], v[124:127]
	v_mfma_f32_16x16x32_bf16 v[120:123], v[136:139], v[214:217], v[120:123]
	v_mfma_f32_16x16x32_bf16 v[108:111], v[68:71], v[222:225], v[108:111]
	v_mfma_f32_16x16x32_bf16 v[104:107], v[136:139], v[222:225], v[104:107]
	v_mfma_f32_16x16x32_bf16 v[92:95], v[68:71], v[230:233], v[92:95]
	v_mfma_f32_16x16x32_bf16 v[88:91], v[136:139], v[230:233], v[88:91]
	v_mfma_f32_16x16x32_bf16 v[60:63], v[72:75], v[182:185], v[60:63]
	v_mfma_f32_16x16x32_bf16 v[56:59], v[140:143], v[182:185], v[56:59]
	v_mfma_f32_16x16x32_bf16 v[124:127], v[72:75], v[218:221], v[124:127]
	v_mfma_f32_16x16x32_bf16 v[120:123], v[140:143], v[218:221], v[120:123]
	v_mfma_f32_16x16x32_bf16 v[108:111], v[72:75], v[226:229], v[108:111]
	v_mfma_f32_16x16x32_bf16 v[104:107], v[140:143], v[226:229], v[104:107]
	v_mfma_f32_16x16x32_bf16 v[92:95], v[72:75], v[234:237], v[92:95]
	v_mfma_f32_16x16x32_bf16 v[88:91], v[140:143], v[234:237], v[88:91]
	v_mfma_f32_16x16x32_bf16 v[132:135], v[144:147], v[178:181], v[132:135]
	v_mfma_f32_16x16x32_bf16 v[128:131], v[152:155], v[178:181], v[128:131]
	v_mfma_f32_16x16x32_bf16 v[116:119], v[144:147], v[214:217], v[116:119]
	v_mfma_f32_16x16x32_bf16 v[112:115], v[152:155], v[214:217], v[112:115]
	v_mfma_f32_16x16x32_bf16 v[100:103], v[144:147], v[222:225], v[100:103]
	v_mfma_f32_16x16x32_bf16 v[96:99], v[152:155], v[222:225], v[96:99]
	v_mfma_f32_16x16x32_bf16 v[84:87], v[144:147], v[230:233], v[84:87]
	v_mfma_f32_16x16x32_bf16 v[80:83], v[152:155], v[230:233], v[80:83]
	v_mfma_f32_16x16x32_bf16 v[132:135], v[148:151], v[182:185], v[132:135]
	v_mfma_f32_16x16x32_bf16 v[128:131], v[156:159], v[182:185], v[128:131]
	v_mfma_f32_16x16x32_bf16 v[116:119], v[148:151], v[218:221], v[116:119]
	v_mfma_f32_16x16x32_bf16 v[112:115], v[156:159], v[218:221], v[112:115]
	v_mfma_f32_16x16x32_bf16 v[100:103], v[148:151], v[226:229], v[100:103]
	v_mfma_f32_16x16x32_bf16 v[96:99], v[156:159], v[226:229], v[96:99]
	v_mfma_f32_16x16x32_bf16 v[84:87], v[148:151], v[234:237], v[84:87]
	v_mfma_f32_16x16x32_bf16 v[80:83], v[156:159], v[234:237], v[80:83]
	s_setprio 0
	s_barrier
	s_add_i32 s75, s63, s54
	v_lshl_add_u64 v[186:187], s[50:51], 0, v[162:163]
	s_mov_b32 m0, s75
	ds_read_b128 v[178:181], v212 offset:16384
	ds_read_b128 v[182:185], v212 offset:17408
	ds_read_b128 v[214:217], v212 offset:18432
	ds_read_b128 v[218:221], v212 offset:19456
	ds_read_b128 v[222:225], v212 offset:20480
	ds_read_b128 v[226:229], v212 offset:21504
	ds_read_b128 v[230:233], v212 offset:22528
	ds_read_b128 v[234:237], v212 offset:23552
	global_load_lds_dwordx4 v[186:187], off
	s_add_i32 m0, s75, 0x2000
	s_add_u32 s76, s50, 0x4000
	v_lshl_add_u64 v[186:187], s[50:51], 0, v[166:167]
	s_addc_u32 s77, s51, 0
	s_add_i32 s75, s64, s54
	global_load_lds_dwordx4 v[186:187], off
	v_lshl_add_u64 v[186:187], s[76:77], 0, v[162:163]
	s_mov_b32 m0, s75
	v_lshl_add_u64 v[238:239], s[52:53], 0, v[164:165]
	global_load_lds_dwordx4 v[186:187], off
	v_lshl_add_u64 v[186:187], s[76:77], 0, v[166:167]
	s_add_i32 m0, s75, 0x2000
	s_nop 0
	global_load_lds_dwordx4 v[186:187], off
	v_lshl_add_u64 v[186:187], s[52:53], 0, v[160:161]
	s_mov_b32 m0, s55
	s_nop 0
	global_load_lds_dwordx4 v[186:187], off
	s_mov_b32 m0, s56
	s_nop 0
	global_load_lds_dwordx4 v[238:239], off
	s_waitcnt vmcnt(8)
	s_waitcnt lgkmcnt(0)
	s_barrier
; #define PG8_STAGE(bufoff, gbase, voff) do { _Pragma("unroll") for (int _i = 0; _i < 2; ++_i) \
;         __builtin_amdgcn_global_load_lds((const unsigned*)((const char*)(gbase) + (voff)[_i]), (PG8_LAS unsigned*)(lds + (bufoff) + ldsw + _i * 8192), 16, 0, 0); } while (0)
; #define PG8_LDA(dst, b, h) do { _Pragma("unroll") for (int m = 0; m < 4; ++m) _Pragma("unroll") for (int k = 0; k < 2; ++k) dst[m][k] = *(const PG8_LAS bf16x8*)(lds + PG8_SA(b, h) + aoff + m * 2048 + k * 1024); } while (0)
; #define PG8_LDB(dst, b, h) do { _Pragma("unroll") for (int n = 0; n < 2; ++n) _Pragma("unroll") for (int k = 0; k < 2; ++k) dst[n][k] = *(const PG8_LAS bf16x8*)(lds + PG8_SB(b, h) + boff + n * 2048 + k * 1024); } while (0)
; #define PG8_MMA(ai, bj, At, Bt) do { __builtin_amdgcn_s_setprio(1); _Pragma("unroll") for (int m = 0; m < 4; ++m) _Pragma("unroll") for (int n = 0; n < 2; ++n) _Pragma("unroll") for (int k = 0; k < 2; ++k) \
;         acc[ai][bj][m][n] = __builtin_amdgcn_mfma_f32_16x16x32_bf16(Bt[n][k], At[m][k], acc[ai][bj][m][n], 0, 0, 0); __builtin_amdgcn_s_setprio(0); } while (0)
; #define PG8_WAIT_V(n) asm volatile("s_waitcnt vmcnt(" #n ")" ::: "memory")
; #define PG8_WAIT_L(n) asm volatile("s_waitcnt lgkmcnt(" #n ")" ::: "memory")
; #define PG8_BAR __builtin_amdgcn_s_barrier()
; #define PG8_SCHED __builtin_amdgcn_sched_barrier(0)
; template <class Epi, class Sched, bool ALIGN_EPI = false, bool SP2 = false>
; __device__ __forceinline__ void gemm_phase(PG8_LAS unsigned char* lds, const Gemm g, const Sched& S, const Epi& E) {
;     ...
;             PG8_WAIT_V(8); PG8_WAIT_L(0); PG8_BAR; PG8_MMA(1, 0, At, B0); PG8_MMA(1, 1, At, B1); PG8_BAR; PG8_SCHED;
;             PG8_LDB(B0, 1, 0); PG8_LDB(B1, 1, 1); PG8_SCHED; PG8_LDA(At, 1, 0); PG8_STAGE(PG8_SA(0, 1), a2 + hstepA, voffA);
;             PG8_WAIT_V(8); PG8_WAIT_L(0); PG8_BAR; PG8_MMA(0, 0, At, B0); PG8_MMA(0, 1, At, B1); PG8_BAR; PG8_SCHED;
;             PG8_LDA(At, 1, 1); PG8_STAGE(PG8_SB(1, 0), b3, voffB); PG8_STAGE(PG8_SB(1, 1), b3 + hstepB, voffB); PG8_STAGE(PG8_SA(1, 0), a3, voffA);
	s_setprio 1
	s_waitcnt lgkmcnt(0)
	v_mfma_f32_16x16x32_bf16 v[76:79], v[68:71], v[178:181], v[76:79]
	v_mfma_f32_16x16x32_bf16 v[64:67], v[136:139], v[178:181], v[64:67]
	v_mfma_f32_16x16x32_bf16 v[44:47], v[68:71], v[214:217], v[44:47]
	v_mfma_f32_16x16x32_bf16 v[40:43], v[136:139], v[214:217], v[40:43]
	v_mfma_f32_16x16x32_bf16 v[28:31], v[68:71], v[222:225], v[28:31]
	v_mfma_f32_16x16x32_bf16 v[24:27], v[136:139], v[222:225], v[24:27]
	v_mfma_f32_16x16x32_bf16 v[12:15], v[68:71], v[230:233], v[12:15]
	v_mfma_f32_16x16x32_bf16 v[8:11], v[136:139], v[230:233], v[8:11]
	v_mfma_f32_16x16x32_bf16 v[76:79], v[72:75], v[182:185], v[76:79]
	v_mfma_f32_16x16x32_bf16 v[64:67], v[140:143], v[182:185], v[64:67]
	v_mfma_f32_16x16x32_bf16 v[44:47], v[72:75], v[218:221], v[44:47]
	v_mfma_f32_16x16x32_bf16 v[40:43], v[140:143], v[218:221], v[40:43]
	v_mfma_f32_16x16x32_bf16 v[28:31], v[72:75], v[226:229], v[28:31]
	v_mfma_f32_16x16x32_bf16 v[24:27], v[140:143], v[226:229], v[24:27]
	v_mfma_f32_16x16x32_bf16 v[12:15], v[72:75], v[234:237], v[12:15]
	v_mfma_f32_16x16x32_bf16 v[8:11], v[140:143], v[234:237], v[8:11]
	v_mfma_f32_16x16x32_bf16 v[52:55], v[144:147], v[178:181], v[52:55]
	v_mfma_f32_16x16x32_bf16 v[48:51], v[152:155], v[178:181], v[48:51]
	v_mfma_f32_16x16x32_bf16 v[36:39], v[144:147], v[214:217], v[36:39]
	v_mfma_f32_16x16x32_bf16 v[32:35], v[152:155], v[214:217], v[32:35]
	v_mfma_f32_16x16x32_bf16 v[20:23], v[144:147], v[222:225], v[20:23]
	v_mfma_f32_16x16x32_bf16 v[16:19], v[152:155], v[222:225], v[16:19]
	v_mfma_f32_16x16x32_bf16 v[4:7], v[144:147], v[230:233], v[4:7]
	v_mfma_f32_16x16x32_bf16 v[0:3], v[152:155], v[230:233], v[0:3]
	v_mfma_f32_16x16x32_bf16 v[52:55], v[148:151], v[182:185], v[52:55]
	v_mfma_f32_16x16x32_bf16 v[48:51], v[156:159], v[182:185], v[48:51]
	v_mfma_f32_16x16x32_bf16 v[36:39], v[148:151], v[218:221], v[36:39]
	v_mfma_f32_16x16x32_bf16 v[32:35], v[156:159], v[218:221], v[32:35]
	v_mfma_f32_16x16x32_bf16 v[20:23], v[148:151], v[226:229], v[20:23]
	v_mfma_f32_16x16x32_bf16 v[16:19], v[156:159], v[226:229], v[16:19]
	v_mfma_f32_16x16x32_bf16 v[4:7], v[148:151], v[234:237], v[4:7]
	v_mfma_f32_16x16x32_bf16 v[0:3], v[156:159], v[234:237], v[0:3]
	s_setprio 0
	s_barrier
	s_add_i32 s75, 0, 0x18000
	s_add_i32 s76, 0, 0x1c000
	v_add_u32_e32 v140, s75, v208
	v_add_u32_e32 v156, s76, v208
	ds_read_b128 v[68:71], v140
	ds_read_b128 v[72:75], v140 offset:1024
	ds_read_b128 v[136:139], v140 offset:2048
	ds_read_b128 v[140:143], v140 offset:3072
	ds_read_b128 v[144:147], v156
	ds_read_b128 v[148:151], v156 offset:1024
	ds_read_b128 v[152:155], v156 offset:2048
	ds_read_b128 v[156:159], v156 offset:3072
	s_add_u32 s52, s52, 0x100000
	s_addc_u32 s53, s53, 0
	s_mov_b32 m0, s57
	v_lshl_add_u64 v[240:241], s[52:53], 0, v[160:161]
	ds_read_b128 v[178:181], v212 offset:32768
	ds_read_b128 v[182:185], v212 offset:33792
	ds_read_b128 v[214:217], v212 offset:34816
	ds_read_b128 v[218:221], v212 offset:35840
	ds_read_b128 v[222:225], v212 offset:36864
	ds_read_b128 v[226:229], v212 offset:37888
	ds_read_b128 v[230:233], v212 offset:38912
	ds_read_b128 v[234:237], v212 offset:39936
	global_load_lds_dwordx4 v[240:241], off
	v_lshl_add_u64 v[240:241], s[52:53], 0, v[164:165]
	s_mov_b32 m0, s58
	s_nop 0
	global_load_lds_dwordx4 v[240:241], off
	s_waitcnt vmcnt(8)
	s_waitcnt lgkmcnt(0)
	s_barrier
	s_setprio 1
	s_waitcnt lgkmcnt(0)
	v_mfma_f32_16x16x32_bf16 v[60:63], v[68:71], v[178:181], v[60:63]
	v_mfma_f32_16x16x32_bf16 v[56:59], v[136:139], v[178:181], v[56:59]
	v_mfma_f32_16x16x32_bf16 v[124:127], v[68:71], v[214:217], v[124:127]
	v_mfma_f32_16x16x32_bf16 v[120:123], v[136:139], v[214:217], v[120:123]
	v_mfma_f32_16x16x32_bf16 v[108:111], v[68:71], v[222:225], v[108:111]
	v_mfma_f32_16x16x32_bf16 v[104:107], v[136:139], v[222:225], v[104:107]
	v_mfma_f32_16x16x32_bf16 v[92:95], v[68:71], v[230:233], v[92:95]
	v_mfma_f32_16x16x32_bf16 v[88:91], v[136:139], v[230:233], v[88:91]
	v_mfma_f32_16x16x32_bf16 v[60:63], v[72:75], v[182:185], v[60:63]
	v_mfma_f32_16x16x32_bf16 v[56:59], v[140:143], v[182:185], v[56:59]
	v_mfma_f32_16x16x32_bf16 v[124:127], v[72:75], v[218:221], v[124:127]
	v_mfma_f32_16x16x32_bf16 v[120:123], v[140:143], v[218:221], v[120:123]
	v_mfma_f32_16x16x32_bf16 v[108:111], v[72:75], v[226:229], v[108:111]
	v_mfma_f32_16x16x32_bf16 v[104:107], v[140:143], v[226:229], v[104:107]
	v_mfma_f32_16x16x32_bf16 v[92:95], v[72:75], v[234:237], v[92:95]
	v_mfma_f32_16x16x32_bf16 v[88:91], v[140:143], v[234:237], v[88:91]
	v_mfma_f32_16x16x32_bf16 v[132:135], v[144:147], v[178:181], v[132:135]
	v_mfma_f32_16x16x32_bf16 v[128:131], v[152:155], v[178:181], v[128:131]
	v_mfma_f32_16x16x32_bf16 v[116:119], v[144:147], v[214:217], v[116:119]
	v_mfma_f32_16x16x32_bf16 v[112:115], v[152:155], v[214:217], v[112:115]
	v_mfma_f32_16x16x32_bf16 v[100:103], v[144:147], v[222:225], v[100:103]
	v_mfma_f32_16x16x32_bf16 v[96:99], v[152:155], v[222:225], v[96:99]
	v_mfma_f32_16x16x32_bf16 v[84:87], v[144:147], v[230:233], v[84:87]
	v_mfma_f32_16x16x32_bf16 v[80:83], v[152:155], v[230:233], v[80:83]
	v_mfma_f32_16x16x32_bf16 v[132:135], v[148:151], v[182:185], v[132:135]
	v_mfma_f32_16x16x32_bf16 v[128:131], v[156:159], v[182:185], v[128:131]
	v_mfma_f32_16x16x32_bf16 v[116:119], v[148:151], v[218:221], v[116:119]
	v_mfma_f32_16x16x32_bf16 v[112:115], v[156:159], v[218:221], v[112:115]
	v_mfma_f32_16x16x32_bf16 v[100:103], v[148:151], v[226:229], v[100:103]
	v_mfma_f32_16x16x32_bf16 v[96:99], v[156:159], v[226:229], v[96:99]
	v_mfma_f32_16x16x32_bf16 v[84:87], v[148:151], v[234:237], v[84:87]
	v_mfma_f32_16x16x32_bf16 v[80:83], v[156:159], v[234:237], v[80:83]
	s_setprio 0
	s_barrier
; #define PG8_STAGE(bufoff, gbase, voff) do { _Pragma("unroll") for (int _i = 0; _i < 2; ++_i) \
;         __builtin_amdgcn_global_load_lds((const unsigned*)((const char*)(gbase) + (voff)[_i]), (PG8_LAS unsigned*)(lds + (bufoff) + ldsw + _i * 8192), 16, 0, 0); } while (0)
; #define PG8_LDA(dst, b, h) do { _Pragma("unroll") for (int m = 0; m < 4; ++m) _Pragma("unroll") for (int k = 0; k < 2; ++k) dst[m][k] = *(const PG8_LAS bf16x8*)(lds + PG8_SA(b, h) + aoff + m * 2048 + k * 1024); } while (0)
; #define PG8_MMA(ai, bj, At, Bt) do { __builtin_amdgcn_s_setprio(1); _Pragma("unroll") for (int m = 0; m < 4; ++m) _Pragma("unroll") for (int n = 0; n < 2; ++n) _Pragma("unroll") for (int k = 0; k < 2; ++k) \
;         acc[ai][bj][m][n] = __builtin_amdgcn_mfma_f32_16x16x32_bf16(Bt[n][k], At[m][k], acc[ai][bj][m][n], 0, 0, 0); __builtin_amdgcn_s_setprio(0); } while (0)
; #define PG8_WAIT_V(n) asm volatile("s_waitcnt vmcnt(" #n ")" ::: "memory")
; #define PG8_WAIT_L(n) asm volatile("s_waitcnt lgkmcnt(" #n ")" ::: "memory")
; #define PG8_BAR __builtin_amdgcn_s_barrier()
; #define PG8_SCHED __builtin_amdgcn_sched_barrier(0)
; template <class Epi, class Sched, bool ALIGN_EPI = false, bool SP2 = false>
; __device__ __forceinline__ void gemm_phase(PG8_LAS unsigned char* lds, const Gemm g, const Sched& S, const Epi& E) {
;     ...
;         for (int t = 0; t < nt; t += 2) {
;             const bool last = (t == nt - 2);
;             const char* a1 = cA + (size_t)(t + 1) * kstep;
;             const char* a2 = last ? nA : cA + (size_t)(t + 2) * kstep; const char* b2 = last ? nB : cB + (size_t)(t + 2) * kstepB;
;             const char* a3 = a2 + kstep; const char* b3 = b2 + kstepB;
;             if (last && has_next) S.a_ready(nxt);
;     ...
;             PG8_LDA(At, 1, 1); PG8_STAGE(PG8_SB(1, 0), b3, voffB); PG8_STAGE(PG8_SB(1, 1), b3 + hstepB, voffB); PG8_STAGE(PG8_SA(1, 0), a3, voffA);
;             PG8_WAIT_V(8); PG8_WAIT_L(0); PG8_BAR; PG8_MMA(1, 0, At, B0); PG8_MMA(1, 1, At, B1); PG8_BAR; PG8_SCHED;
	s_add_u32 s52, s50, 0x8000
	s_addc_u32 s53, s51, 0
	s_add_i32 s75, s75, s54
	v_lshl_add_u64 v[240:241], s[52:53], 0, v[162:163]
	s_mov_b32 m0, s75
	ds_read_b128 v[178:181], v212 offset:49152
	ds_read_b128 v[182:185], v212 offset:50176
	ds_read_b128 v[214:217], v212 offset:51200
	ds_read_b128 v[218:221], v212 offset:52224
	ds_read_b128 v[222:225], v212 offset:53248
	ds_read_b128 v[226:229], v212 offset:54272
	ds_read_b128 v[230:233], v212 offset:55296
	ds_read_b128 v[234:237], v212 offset:56320
	global_load_lds_dwordx4 v[240:241], off
	s_add_i32 m0, s75, 0x2000
	s_add_u32 s50, s50, 0xc000
	v_lshl_add_u64 v[240:241], s[52:53], 0, v[166:167]
	s_addc_u32 s51, s51, 0
	s_add_i32 s52, s76, s54
	global_load_lds_dwordx4 v[240:241], off
	v_lshl_add_u64 v[240:241], s[50:51], 0, v[162:163]
	s_mov_b32 m0, s52
	v_lshl_add_u64 v[186:187], v[186:187], 0, s[18:19]
	global_load_lds_dwordx4 v[240:241], off
	v_lshl_add_u64 v[240:241], s[50:51], 0, v[166:167]
	s_add_i32 m0, s52, 0x2000
	s_nop 0
	global_load_lds_dwordx4 v[240:241], off
	s_mov_b32 m0, s61
	s_nop 0
	global_load_lds_dwordx4 v[186:187], off
	v_lshl_add_u64 v[186:187], v[238:239], 0, s[18:19]
	s_mov_b32 m0, s62
	s_nop 0
	global_load_lds_dwordx4 v[186:187], off
	s_waitcnt vmcnt(8)
	s_waitcnt lgkmcnt(0)
	s_barrier
	s_setprio 1
	s_waitcnt lgkmcnt(0)
	v_mfma_f32_16x16x32_bf16 v[76:79], v[68:71], v[178:181], v[76:79]
	v_mfma_f32_16x16x32_bf16 v[64:67], v[136:139], v[178:181], v[64:67]
	v_mfma_f32_16x16x32_bf16 v[44:47], v[68:71], v[214:217], v[44:47]
	v_mfma_f32_16x16x32_bf16 v[40:43], v[136:139], v[214:217], v[40:43]
	v_mfma_f32_16x16x32_bf16 v[28:31], v[68:71], v[222:225], v[28:31]
	v_mfma_f32_16x16x32_bf16 v[24:27], v[136:139], v[222:225], v[24:27]
	v_mfma_f32_16x16x32_bf16 v[12:15], v[68:71], v[230:233], v[12:15]
	v_mfma_f32_16x16x32_bf16 v[8:11], v[136:139], v[230:233], v[8:11]
	v_mfma_f32_16x16x32_bf16 v[76:79], v[72:75], v[182:185], v[76:79]
	v_mfma_f32_16x16x32_bf16 v[64:67], v[140:143], v[182:185], v[64:67]
	v_mfma_f32_16x16x32_bf16 v[44:47], v[72:75], v[218:221], v[44:47]
	v_mfma_f32_16x16x32_bf16 v[40:43], v[140:143], v[218:221], v[40:43]
	v_mfma_f32_16x16x32_bf16 v[28:31], v[72:75], v[226:229], v[28:31]
	v_mfma_f32_16x16x32_bf16 v[24:27], v[140:143], v[226:229], v[24:27]
	v_mfma_f32_16x16x32_bf16 v[12:15], v[72:75], v[234:237], v[12:15]
	v_mfma_f32_16x16x32_bf16 v[8:11], v[140:143], v[234:237], v[8:11]
	v_mfma_f32_16x16x32_bf16 v[52:55], v[144:147], v[178:181], v[52:55]
	v_mfma_f32_16x16x32_bf16 v[48:51], v[152:155], v[178:181], v[48:51]
	v_mfma_f32_16x16x32_bf16 v[36:39], v[144:147], v[214:217], v[36:39]
	v_mfma_f32_16x16x32_bf16 v[32:35], v[152:155], v[214:217], v[32:35]
	v_mfma_f32_16x16x32_bf16 v[20:23], v[144:147], v[222:225], v[20:23]
	v_mfma_f32_16x16x32_bf16 v[16:19], v[152:155], v[222:225], v[16:19]
	v_mfma_f32_16x16x32_bf16 v[4:7], v[144:147], v[230:233], v[4:7]
	v_mfma_f32_16x16x32_bf16 v[0:3], v[152:155], v[230:233], v[0:3]
	v_mfma_f32_16x16x32_bf16 v[52:55], v[148:151], v[182:185], v[52:55]
	v_mfma_f32_16x16x32_bf16 v[48:51], v[156:159], v[182:185], v[48:51]
	v_mfma_f32_16x16x32_bf16 v[36:39], v[148:151], v[218:221], v[36:39]
	v_mfma_f32_16x16x32_bf16 v[32:35], v[156:159], v[218:221], v[32:35]
	v_mfma_f32_16x16x32_bf16 v[20:23], v[148:151], v[226:229], v[20:23]
	v_mfma_f32_16x16x32_bf16 v[16:19], v[156:159], v[226:229], v[16:19]
	v_mfma_f32_16x16x32_bf16 v[4:7], v[148:151], v[234:237], v[4:7]
	v_mfma_f32_16x16x32_bf16 v[0:3], v[156:159], v[234:237], v[0:3]
	s_setprio 0
	s_barrier
	s_add_i32 s74, s74, 2
	s_add_u32 s72, s72, 0x10000
	s_addc_u32 s73, s73, 0
	s_add_u32 s48, s48, 0x100
	s_addc_u32 s49, s49, 0
	s_cmp_gt_u32 s74, 61
	s_cbranch_scc0 .LBB0_964
	s_and_b64 vcc, exec, s[26:27]
	s_cbranch_vccz .LBB0_967
	s_barrier
